# conv4x8 row loads (ssd_s1 x2, ssd_s3): three rows in flight instead of one (7 -> 3 round trips)
# speedup vs baseline: 1.0085x; 1.0085x over previous
.LBB0_214:
	s_or_b64 exec, exec, s[2:3]
	v_ashrrev_i32_e32 v136, 2, v66
	v_and_b32_e32 v40, -4, v136
	s_mov_b32 s17, s57
	v_ashrrev_i32_e32 v41, 31, v40
	v_lshl_add_u64 v[4:5], s[16:17], 0, v[40:41]
	v_mad_u64_u32 v[8:9], s[2:3], v4, s68, 0
	v_lshlrev_b32_e32 v3, 3, v66
	v_mov_b32_e32 v4, v9
	v_and_b32_e32 v135, 0x78, v3
	v_mad_u64_u32 v[4:5], s[2:3], v5, s68, v[4:5]
	v_lshl_or_b32 v67, s19, 7, v135
	v_readlane_b32 s2, v242, 63
	v_or_b32_e32 v6, 0x400, v67
	v_add_u32_e32 v7, s18, v40
	v_mov_b32_e32 v9, v4
	v_readlane_b32 s3, v241, 0
	v_cmp_lt_i32_e64 s[0:1], 2, v7
	v_mov_b32_e32 v98, 0
	v_lshl_add_u64 v[42:43], s[2:3], 0, v[8:9]
	v_lshlrev_b32_e32 v4, 1, v6
	v_mov_b32_e32 v99, 0
	v_mov_b32_e32 v109, 0
	v_mov_b32_e32 v115, 0
	v_mov_b32_e32 v117, 0
	v_mov_b32_e32 v119, 0
	v_mov_b32_e32 v121, 0
	v_mov_b32_e32 v125, 0
	v_mov_b32_e32 v129, 0
	v_mov_b32_e32 v244, 0
	v_mov_b32_e32 v245, 0
	v_mov_b32_e32 v246, 0
	v_mov_b32_e32 v247, 0
	s_and_saveexec_b64 s[2:3], s[0:1]
	s_cbranch_execz .LBB0_216
	v_mov_b32_e32 v5, v2
	v_lshl_add_u64 v[8:9], v[42:43], 0, v[4:5]
	v_add_co_u32_e32 v8, vcc, 0xffffa000, v8
	s_nop 1
	v_addc_co_u32_e32 v9, vcc, -1, v9, vcc
	global_load_dwordx4 v[244:247], v[8:9], off offset:-3072
.LBB0_216:
	s_or_b64 exec, exec, s[2:3]
	v_cmp_lt_i32_e64 s[14:15], 1, v7
	v_mov_b32_e32 v108, 0
	v_mov_b32_e32 v114, 0
	v_mov_b32_e32 v116, 0
	v_mov_b32_e32 v118, 0
	v_mov_b32_e32 v120, 0
	v_mov_b32_e32 v124, 0
	v_mov_b32_e32 v128, 0
	v_mov_b32_e32 v248, 0
	v_mov_b32_e32 v249, 0
	v_mov_b32_e32 v250, 0
	v_mov_b32_e32 v251, 0
	s_and_saveexec_b64 s[2:3], s[14:15]
	s_cbranch_execz .LBB0_218
	v_mov_b32_e32 v5, v2
	v_lshl_add_u64 v[8:9], v[42:43], 0, v[4:5]
	v_add_co_u32_e32 v8, vcc, 0xffffc000, v8
	s_nop 1
	v_addc_co_u32_e32 v9, vcc, -1, v9, vcc
	global_load_dwordx4 v[248:251], v[8:9], off offset:-2048
.LBB0_218:
	s_or_b64 exec, exec, s[2:3]
	v_cmp_lt_i32_e64 s[4:5], 0, v7
	v_mov_b32_e32 v112, 0
	v_mov_b32_e32 v113, 0
	v_mov_b32_e32 v111, 0
	v_mov_b32_e32 v105, 0
	v_mov_b32_e32 v101, 0
	v_mov_b32_e32 v95, 0
	v_mov_b32_e32 v89, 0
	v_mov_b32_e32 v79, 0
	v_mov_b32_e32 v71, 0
	v_mov_b32_e32 v252, 0
	v_mov_b32_e32 v253, 0
	v_mov_b32_e32 v254, 0
	v_mov_b32_e32 v255, 0
	s_and_saveexec_b64 s[2:3], s[4:5]
	s_cbranch_execz .LBB0_220
	v_mov_b32_e32 v5, v2
	v_lshl_add_u64 v[8:9], v[42:43], 0, v[4:5]
	v_add_co_u32_e32 v8, vcc, 0xffffe000, v8
	s_nop 1
	v_addc_co_u32_e32 v9, vcc, -1, v9, vcc
	global_load_dwordx4 v[252:255], v[8:9], off offset:-1024
.LBB0_220:
	s_or_b64 exec, exec, s[2:3]
	s_waitcnt vmcnt(0)
	v_lshlrev_b32_e32 v129, 16, v244
	v_and_b32_e32 v125, 0xffff0000, v244
	v_lshlrev_b32_e32 v121, 16, v245
	v_and_b32_e32 v119, 0xffff0000, v245
	v_lshlrev_b32_e32 v117, 16, v246
	v_and_b32_e32 v115, 0xffff0000, v246
	v_lshlrev_b32_e32 v109, 16, v247
	v_and_b32_e32 v99, 0xffff0000, v247
	v_lshlrev_b32_e32 v128, 16, v248
	v_and_b32_e32 v124, 0xffff0000, v248
	v_lshlrev_b32_e32 v120, 16, v249
	v_and_b32_e32 v118, 0xffff0000, v249
	v_lshlrev_b32_e32 v116, 16, v250
	v_and_b32_e32 v114, 0xffff0000, v250
	v_lshlrev_b32_e32 v108, 16, v251
	v_and_b32_e32 v98, 0xffff0000, v251
	v_lshlrev_b32_e32 v113, 16, v252
	v_and_b32_e32 v111, 0xffff0000, v252
	v_lshlrev_b32_e32 v105, 16, v253
	v_and_b32_e32 v101, 0xffff0000, v253
	v_lshlrev_b32_e32 v95, 16, v254
	v_and_b32_e32 v89, 0xffff0000, v254
	v_lshlrev_b32_e32 v79, 16, v255
	v_and_b32_e32 v71, 0xffff0000, v255
	v_cmp_lt_i32_e64 s[6:7], -1, v7
	v_mov_b32_e32 v110, 0
	v_mov_b32_e32 v104, 0
	v_mov_b32_e32 v100, 0
	v_mov_b32_e32 v94, 0
	v_mov_b32_e32 v88, 0
	v_mov_b32_e32 v78, 0
	v_mov_b32_e32 v70, 0
	v_mov_b32_e32 v244, 0
	v_mov_b32_e32 v245, 0
	v_mov_b32_e32 v246, 0
	v_mov_b32_e32 v247, 0
	s_and_saveexec_b64 s[2:3], s[6:7]
	s_cbranch_execz .LBB0_222
	v_mov_b32_e32 v5, v2
	v_lshl_add_u64 v[8:9], v[42:43], 0, v[4:5]
	global_load_dwordx4 v[244:247], v[8:9], off
.LBB0_222:
	s_or_b64 exec, exec, s[2:3]
	v_cmp_lt_i32_e64 s[8:9], -2, v7
	v_mov_b32_e32 v84, 0
	v_mov_b32_e32 v86, 0
	v_mov_b32_e32 v76, 0
	v_mov_b32_e32 v68, 0
	v_mov_b32_e32 v60, 0
	v_mov_b32_e32 v54, 0
	v_mov_b32_e32 v50, 0
	v_mov_b32_e32 v46, 0
	v_mov_b32_e32 v44, 0
	v_mov_b32_e32 v248, 0
	v_mov_b32_e32 v249, 0
	v_mov_b32_e32 v250, 0
	v_mov_b32_e32 v251, 0
	s_and_saveexec_b64 s[2:3], s[8:9]
	s_cbranch_execz .LBB0_224
	v_mov_b32_e32 v5, v2
	v_lshl_add_u64 v[8:9], v[42:43], 0, v[4:5]
	v_add_co_u32_e32 v8, vcc, 0x2000, v8
	s_nop 1
	v_addc_co_u32_e32 v9, vcc, 0, v9, vcc
	global_load_dwordx4 v[248:251], v[8:9], off offset:1024
.LBB0_224:
	s_or_b64 exec, exec, s[2:3]
	v_cmp_lt_i32_e64 s[10:11], -3, v7
	v_mov_b32_e32 v92, 0
	v_mov_b32_e32 v82, 0
	v_mov_b32_e32 v74, 0
	v_mov_b32_e32 v64, 0
	v_mov_b32_e32 v58, 0
	v_mov_b32_e32 v52, 0
	v_mov_b32_e32 v48, 0
	v_mov_b32_e32 v252, 0
	v_mov_b32_e32 v253, 0
	v_mov_b32_e32 v254, 0
	v_mov_b32_e32 v255, 0
	s_and_saveexec_b64 s[2:3], s[10:11]
	s_cbranch_execz .LBB0_226
	v_mov_b32_e32 v5, v2
	v_lshl_add_u64 v[8:9], v[42:43], 0, v[4:5]
	v_add_co_u32_e32 v8, vcc, 0x4000, v8
	s_nop 1
	v_addc_co_u32_e32 v9, vcc, 0, v9, vcc
	global_load_dwordx4 v[252:255], v[8:9], off offset:2048
.LBB0_226:
	s_or_b64 exec, exec, s[2:3]
	s_waitcnt vmcnt(0)
	v_lshlrev_b32_e32 v112, 16, v244
	v_and_b32_e32 v110, 0xffff0000, v244
	v_lshlrev_b32_e32 v104, 16, v245
	v_and_b32_e32 v100, 0xffff0000, v245
	v_lshlrev_b32_e32 v94, 16, v246
	v_and_b32_e32 v88, 0xffff0000, v246
	v_lshlrev_b32_e32 v78, 16, v247
	v_and_b32_e32 v70, 0xffff0000, v247
	v_lshlrev_b32_e32 v86, 16, v248
	v_and_b32_e32 v76, 0xffff0000, v248
	v_lshlrev_b32_e32 v68, 16, v249
	v_and_b32_e32 v60, 0xffff0000, v249
	v_lshlrev_b32_e32 v54, 16, v250
	v_and_b32_e32 v50, 0xffff0000, v250
	v_lshlrev_b32_e32 v46, 16, v251
	v_and_b32_e32 v44, 0xffff0000, v251
	v_lshlrev_b32_e32 v84, 16, v252
	v_and_b32_e32 v92, 0xffff0000, v252
	v_lshlrev_b32_e32 v82, 16, v253
	v_and_b32_e32 v74, 0xffff0000, v253
	v_lshlrev_b32_e32 v64, 16, v254
	v_and_b32_e32 v58, 0xffff0000, v254
	v_lshlrev_b32_e32 v52, 16, v255
	v_and_b32_e32 v48, 0xffff0000, v255
	v_cmp_lt_i32_e64 s[12:13], -4, v7
	v_mov_b32_e32 v41, 0
	v_mov_b32_e32 v106, 0
	v_mov_b32_e32 v102, 0
	v_mov_b32_e32 v96, 0
	v_mov_b32_e32 v90, 0
	v_mov_b32_e32 v80, 0
	v_mov_b32_e32 v72, 0
	v_mov_b32_e32 v62, 0
	v_mov_b32_e32 v56, 0
	v_mov_b32_e32 v244, 0
	v_mov_b32_e32 v245, 0
	v_mov_b32_e32 v246, 0
	v_mov_b32_e32 v247, 0
	s_and_saveexec_b64 s[2:3], s[12:13]
	s_cbranch_execz .LBB0_228
	v_mov_b32_e32 v5, v2
	v_lshl_add_u64 v[4:5], v[42:43], 0, v[4:5]
	v_add_co_u32_e32 v4, vcc, 0x6000, v4
	s_nop 1
	v_addc_co_u32_e32 v5, vcc, 0, v5, vcc
	global_load_dwordx4 v[244:247], v[4:5], off offset:3072
.LBB0_228:
	s_or_b64 exec, exec, s[2:3]
	s_waitcnt vmcnt(0)
	v_lshlrev_b32_e32 v106, 16, v244
	v_and_b32_e32 v102, 0xffff0000, v244
	v_lshlrev_b32_e32 v96, 16, v245
	v_and_b32_e32 v90, 0xffff0000, v245
	v_lshlrev_b32_e32 v80, 16, v246
	v_and_b32_e32 v72, 0xffff0000, v246
	v_lshlrev_b32_e32 v62, 16, v247
	v_and_b32_e32 v56, 0xffff0000, v247
	v_readlane_b32 s36, v242, 2
	v_readlane_b32 s40, v242, 6
	v_readlane_b32 s41, v242, 7
	v_lshlrev_b32_e32 v24, 2, v6
	v_mov_b32_e32 v25, v2
	v_readlane_b32 s42, v242, 8
	v_readlane_b32 s43, v242, 9
	v_readlane_b32 s44, v242, 10
	v_readlane_b32 s45, v242, 11
	v_readlane_b32 s46, v242, 12
	v_readlane_b32 s47, v242, 13
	v_readlane_b32 s48, v242, 14
	v_readlane_b32 s49, v242, 15
	v_readlane_b32 s50, v242, 16
	v_readlane_b32 s51, v242, 17
	s_mov_b64 s[20:21], s[40:41]
	v_lshl_add_u64 v[12:13], s[20:21], 0, v[24:25]
	s_mov_b64 s[2:3], 0x1800
	v_add_co_u32_e32 v10, vcc, s34, v12
	v_lshl_add_u64 v[8:9], v[12:13], 0, s[2:3]
	s_nop 0
	v_addc_co_u32_e32 v11, vcc, 0, v13, vcc
	s_mov_b64 s[2:3], 0x3000
	global_load_dwordx4 v[4:7], v24, s[20:21] offset:16
	global_load_dwordx4 v[16:19], v24, s[20:21]
	global_load_dwordx4 v[36:39], v[10:11], off offset:2048
	global_load_dwordx4 v[28:31], v[8:9], off offset:16
	v_lshl_add_u64 v[8:9], v[12:13], 0, s[2:3]
	s_movk_i32 s2, 0x3000
	v_add_co_u32_e32 v10, vcc, s2, v12
	s_mov_b64 s[2:3], 0x4800
	s_nop 0
	v_addc_co_u32_e32 v11, vcc, 0, v13, vcc
	v_lshl_add_u64 v[14:15], v[12:13], 0, s[2:3]
	v_add_co_u32_e32 v12, vcc, s35, v12
	s_mov_b64 s[22:23], s[42:43]
	s_nop 0
	v_addc_co_u32_e32 v13, vcc, 0, v13, vcc
	global_load_dwordx4 v[20:23], v[10:11], off
	s_nop 0
	global_load_dwordx4 v[8:11], v[8:9], off offset:16
	s_nop 0
	global_load_dwordx4 v[130:133], v[12:13], off offset:2048
	global_load_dwordx4 v[32:35], v[14:15], off offset:16
	s_nop 0
	global_load_dwordx4 v[12:15], v24, s[22:23] offset:16
	s_nop 0
	global_load_dwordx4 v[24:27], v24, s[22:23]
	v_mov_b32_e32 v87, v112
	v_mov_b32_e32 v77, v110
	v_mov_b32_e32 v69, v104
	v_mov_b32_e32 v61, v100
	v_mov_b32_e32 v55, v94
	v_mov_b32_e32 v51, v88
	v_mov_b32_e32 v85, v86
	v_mov_b32_e32 v93, v76
	v_mov_b32_e32 v83, v68
	v_mov_b32_e32 v75, v60
	v_mov_b32_e32 v65, v54
	v_mov_b32_e32 v59, v50
	v_mov_b32_e32 v103, v92
	v_mov_b32_e32 v73, v58
	v_mov_b32_e32 v97, v82
	v_mov_b32_e32 v63, v52
	v_mov_b32_e32 v107, v84
	v_mov_b32_e32 v91, v74
	v_mov_b32_e32 v81, v64
	v_lshlrev_b32_e32 v137, 1, v40
	v_readlane_b32 s37, v242, 3
	v_readlane_b32 s38, v242, 4
	v_readlane_b32 s39, v242, 5
	s_mov_b64 s[24:25], s[44:45]
	s_mov_b64 s[26:27], s[46:47]
	s_mov_b64 s[28:29], s[48:49]
	s_mov_b64 s[30:31], s[50:51]
	s_waitcnt vmcnt(8)
	v_mov_b32_e32 v123, v16
	s_waitcnt vmcnt(7)
	v_mov_b32_e32 v122, v36
	v_pk_mul_f32 v[126:127], v[128:129], v[122:123]
	s_waitcnt vmcnt(0)
	v_add_f32_e32 v16, v127, v24
	v_add_f32_e32 v16, v126, v16
	v_mov_b32_e32 v126, v130
	v_mov_b32_e32 v127, v20
	v_pk_mul_f32 v[138:139], v[112:113], v[126:127]
	s_nop 0
	v_add_f32_e32 v16, v139, v16
	v_add_f32_e32 v16, v138, v16
	v_mul_f32_e32 v20, 0xbfb8aa3b, v16
	v_exp_f32_e32 v20, v20
	s_nop 0
	v_add_f32_e32 v20, 1.0, v20
	v_rcp_f32_e32 v20, v20
	s_nop 0
	v_mul_f32_e32 v129, v16, v20
	v_mov_b32_e32 v16, v37
	v_pk_mul_f32 v[36:37], v[124:125], v[16:17]
	s_nop 0
	v_add_f32_e32 v20, v37, v25
	v_add_f32_e32 v45, v36, v20
	v_mov_b32_e32 v20, v131
	v_pk_mul_f32 v[36:37], v[110:111], v[20:21]
	s_nop 0
	v_add_f32_e32 v37, v37, v45
	v_add_f32_e32 v36, v36, v37
	v_mul_f32_e32 v37, 0xbfb8aa3b, v36
	v_exp_f32_e32 v37, v37
	s_nop 0
	v_add_f32_e32 v37, 1.0, v37
	v_rcp_f32_e32 v37, v37
	s_nop 0
	v_mul_f32_e32 v125, v36, v37
	v_mov_b32_e32 v36, v38
	v_mov_b32_e32 v37, v18
	v_pk_mul_f32 v[130:131], v[120:121], v[36:37]
	s_nop 0
	v_add_f32_e32 v18, v131, v26
	v_add_f32_e32 v18, v130, v18
	v_mov_b32_e32 v130, v132
	v_mov_b32_e32 v131, v22
	v_pk_mul_f32 v[138:139], v[104:105], v[130:131]
	s_nop 0
	v_add_f32_e32 v18, v139, v18
	v_add_f32_e32 v18, v138, v18
	v_mul_f32_e32 v22, 0xbfb8aa3b, v18
	v_exp_f32_e32 v22, v22
	s_nop 0
	v_add_f32_e32 v22, 1.0, v22
	v_rcp_f32_e32 v22, v22
	s_nop 0
	v_mul_f32_e32 v121, v18, v22
	v_mov_b32_e32 v18, v39
	v_pk_mul_f32 v[38:39], v[118:119], v[18:19]
	s_nop 0
	v_add_f32_e32 v22, v39, v27
	v_add_f32_e32 v45, v38, v22
	v_mov_b32_e32 v22, v133
	v_pk_mul_f32 v[38:39], v[100:101], v[22:23]
	s_nop 0
	v_add_f32_e32 v39, v39, v45
	v_add_f32_e32 v38, v38, v39
	v_mul_f32_e32 v39, 0xbfb8aa3b, v38
	v_exp_f32_e32 v39, v39
	s_nop 0
	v_add_f32_e32 v39, 1.0, v39
	v_rcp_f32_e32 v39, v39
	s_nop 0
	v_mul_f32_e32 v119, v38, v39
	v_mov_b32_e32 v38, v28
	v_mov_b32_e32 v39, v4
	v_pk_mul_f32 v[132:133], v[116:117], v[38:39]
	s_nop 0
	v_add_f32_e32 v4, v133, v12
	v_add_f32_e32 v4, v132, v4
	v_mov_b32_e32 v132, v32
	v_mov_b32_e32 v133, v8
	v_pk_mul_f32 v[138:139], v[94:95], v[132:133]
	s_nop 0
	v_add_f32_e32 v4, v139, v4
	v_add_f32_e32 v4, v138, v4
	v_mul_f32_e32 v8, 0xbfb8aa3b, v4
	v_exp_f32_e32 v8, v8
	s_nop 0
	v_add_f32_e32 v8, 1.0, v8
	v_rcp_f32_e32 v8, v8
	s_nop 0
	v_mul_f32_e32 v117, v4, v8
	v_mov_b32_e32 v4, v29
	v_pk_mul_f32 v[28:29], v[114:115], v[4:5]
	s_nop 0
	v_add_f32_e32 v8, v29, v13
	v_add_f32_e32 v32, v28, v8
	v_mov_b32_e32 v8, v33
	v_pk_mul_f32 v[28:29], v[88:89], v[8:9]
	s_nop 0
	v_add_f32_e32 v29, v29, v32
	v_add_f32_e32 v28, v28, v29
	v_mul_f32_e32 v29, 0xbfb8aa3b, v28
	v_exp_f32_e32 v29, v29
	s_nop 0
	v_add_f32_e32 v29, 1.0, v29
	v_rcp_f32_e32 v29, v29
	s_nop 0
	v_mul_f32_e32 v115, v28, v29
	v_mov_b32_e32 v28, v30
	v_mov_b32_e32 v29, v6
	v_pk_mul_f32 v[32:33], v[108:109], v[28:29]
	s_nop 0
	v_add_f32_e32 v6, v33, v14
	v_add_f32_e32 v6, v32, v6
	v_mov_b32_e32 v32, v34
	v_mov_b32_e32 v33, v10
	v_pk_mul_f32 v[138:139], v[78:79], v[32:33]
	s_nop 0
	v_add_f32_e32 v6, v139, v6
	v_add_f32_e32 v6, v138, v6
	v_mul_f32_e32 v10, 0xbfb8aa3b, v6
	v_exp_f32_e32 v10, v10
	s_nop 0
	v_add_f32_e32 v10, 1.0, v10
	v_rcp_f32_e32 v10, v10
	s_nop 0
	v_mul_f32_e32 v30, v6, v10
	v_mov_b32_e32 v6, v31
	v_pk_mul_f32 v[138:139], v[98:99], v[6:7]
	s_nop 0
	v_add_f32_e32 v10, v139, v15
	v_add_f32_e32 v31, v138, v10
	v_mov_b32_e32 v10, v35
	v_pk_mul_f32 v[34:35], v[70:71], v[10:11]
	v_mov_b32_e32 v138, v111
	v_add_f32_e32 v31, v35, v31
	v_add_f32_e32 v31, v34, v31
	v_mul_f32_e32 v34, 0xbfb8aa3b, v31
	v_exp_f32_e32 v34, v34
	v_mov_b32_e32 v35, v128
	v_mov_b32_e32 v139, v124
	v_pk_mul_f32 v[138:139], v[138:139], v[16:17]
	v_add_f32_e32 v34, 1.0, v34
	v_rcp_f32_e32 v34, v34
	v_pk_mul_f32 v[110:111], v[110:111], v[16:17]
	v_pk_mul_f32 v[16:17], v[76:77], v[16:17]
	v_mul_f32_e32 v31, v31, v34
	v_mov_b32_e32 v34, v113
	v_pk_mul_f32 v[34:35], v[34:35], v[122:123]
	v_pk_mul_f32 v[112:113], v[112:113], v[122:123]
	v_add_f32_e32 v35, v35, v24
	v_add_f32_e32 v45, v34, v35
	v_pk_mul_f32 v[34:35], v[86:87], v[126:127]
	v_add_f32_e32 v17, v17, v25
	v_add_f32_e32 v35, v35, v45
	v_add_f32_e32 v34, v34, v35
	v_mul_f32_e32 v35, 0xbfb8aa3b, v34
	v_exp_f32_e32 v35, v35
	s_nop 0
	v_add_f32_e32 v35, 1.0, v35
	v_rcp_f32_e32 v35, v35
	s_nop 0
	v_mul_f32_e32 v34, v34, v35
	v_add_f32_e32 v35, v139, v25
	v_add_f32_e32 v35, v138, v35
	v_pk_mul_f32 v[138:139], v[76:77], v[20:21]
	s_nop 0
	v_add_f32_e32 v35, v139, v35
	v_add_f32_e32 v35, v138, v35
	v_mul_f32_e32 v45, 0xbfb8aa3b, v35
	v_exp_f32_e32 v45, v45
	v_mov_b32_e32 v138, v105
	v_mov_b32_e32 v139, v120
	v_pk_mul_f32 v[138:139], v[138:139], v[36:37]
	v_add_f32_e32 v45, 1.0, v45
	v_rcp_f32_e32 v45, v45
	v_pk_mul_f32 v[104:105], v[104:105], v[36:37]
	v_mul_f32_e32 v35, v35, v45
	v_add_f32_e32 v45, v139, v26
	v_add_f32_e32 v45, v138, v45
	v_pk_mul_f32 v[138:139], v[68:69], v[130:131]
	s_nop 0
	v_add_f32_e32 v45, v139, v45
	v_add_f32_e32 v45, v138, v45
	v_mul_f32_e32 v47, 0xbfb8aa3b, v45
	v_exp_f32_e32 v47, v47
	v_mov_b32_e32 v138, v101
	v_mov_b32_e32 v139, v118
	v_pk_mul_f32 v[138:139], v[138:139], v[18:19]
	v_add_f32_e32 v47, 1.0, v47
	v_rcp_f32_e32 v47, v47
	v_pk_mul_f32 v[100:101], v[100:101], v[18:19]
	v_mul_f32_e32 v99, v45, v47
	v_add_f32_e32 v45, v139, v27
	v_add_f32_e32 v45, v138, v45
	v_pk_mul_f32 v[138:139], v[60:61], v[22:23]
	s_nop 0
	v_add_f32_e32 v45, v139, v45
	v_add_f32_e32 v45, v138, v45
	v_mul_f32_e32 v47, 0xbfb8aa3b, v45
	v_exp_f32_e32 v47, v47
	v_mov_b32_e32 v138, v95
	v_mov_b32_e32 v139, v116
	v_pk_mul_f32 v[138:139], v[138:139], v[38:39]
	v_add_f32_e32 v47, 1.0, v47
	v_rcp_f32_e32 v47, v47
	v_pk_mul_f32 v[94:95], v[94:95], v[38:39]
	v_mul_f32_e32 v109, v45, v47
	v_add_f32_e32 v45, v139, v12
	v_add_f32_e32 v45, v138, v45
	v_pk_mul_f32 v[138:139], v[54:55], v[132:133]
	s_nop 0
	v_add_f32_e32 v45, v139, v45
	v_add_f32_e32 v45, v138, v45
	v_mul_f32_e32 v47, 0xbfb8aa3b, v45
	v_exp_f32_e32 v47, v47
	v_mov_b32_e32 v138, v89
	v_mov_b32_e32 v139, v114
	v_pk_mul_f32 v[138:139], v[138:139], v[4:5]
	v_add_f32_e32 v47, 1.0, v47
	v_rcp_f32_e32 v47, v47
	v_pk_mul_f32 v[88:89], v[88:89], v[4:5]
	v_pk_mul_f32 v[4:5], v[50:51], v[4:5]
	v_mul_f32_e32 v116, v45, v47
	v_add_f32_e32 v45, v139, v13
	v_add_f32_e32 v45, v138, v45
	v_pk_mul_f32 v[138:139], v[50:51], v[8:9]
	v_add_f32_e32 v5, v5, v13
	v_add_f32_e32 v45, v139, v45
	v_add_f32_e32 v45, v138, v45
	v_mul_f32_e32 v47, 0xbfb8aa3b, v45
	v_exp_f32_e32 v47, v47
	v_mov_b32_e32 v138, v79
	v_mov_b32_e32 v139, v108
	v_pk_mul_f32 v[138:139], v[138:139], v[28:29]
	v_add_f32_e32 v47, 1.0, v47
	v_rcp_f32_e32 v47, v47
	s_nop 0
	v_mul_f32_e32 v114, v45, v47
	v_add_f32_e32 v45, v139, v14
	v_mov_b32_e32 v47, v78
	v_add_f32_e32 v45, v138, v45
	v_pk_mul_f32 v[138:139], v[46:47], v[32:33]
	v_pk_mul_f32 v[78:79], v[78:79], v[28:29]
	v_add_f32_e32 v45, v139, v45
	v_add_f32_e32 v45, v138, v45
	v_mul_f32_e32 v49, 0xbfb8aa3b, v45
	v_exp_f32_e32 v49, v49
	v_mov_b32_e32 v138, v71
	v_mov_b32_e32 v139, v98
	v_pk_mul_f32 v[138:139], v[138:139], v[6:7]
	v_add_f32_e32 v49, 1.0, v49
	v_rcp_f32_e32 v49, v49
	s_nop 0
	v_mul_f32_e32 v108, v45, v49
	v_add_f32_e32 v45, v139, v15
	v_add_f32_e32 v49, v138, v45
	v_mov_b32_e32 v45, v70
	v_pk_mul_f32 v[138:139], v[44:45], v[10:11]
	v_pk_mul_f32 v[70:71], v[70:71], v[6:7]
	v_add_f32_e32 v49, v139, v49
	v_add_f32_e32 v49, v138, v49
	v_mul_f32_e32 v53, 0xbfb8aa3b, v49
	v_exp_f32_e32 v53, v53
	s_nop 0
	v_add_f32_e32 v53, 1.0, v53
	v_rcp_f32_e32 v53, v53
	s_nop 0
	v_mul_f32_e32 v98, v49, v53
	v_add_f32_e32 v49, v113, v24
	v_add_f32_e32 v49, v112, v49
	v_pk_mul_f32 v[112:113], v[84:85], v[126:127]
	s_nop 0
	v_add_f32_e32 v49, v113, v49
	v_add_f32_e32 v49, v112, v49
	v_mul_f32_e32 v53, 0xbfb8aa3b, v49
	v_exp_f32_e32 v53, v53
	v_mov_b32_e32 v113, 0
	v_add_f32_e32 v53, 1.0, v53
	v_rcp_f32_e32 v53, v53
	s_nop 0
	v_mul_f32_e32 v85, v49, v53
	v_add_f32_e32 v49, v111, v25
	v_add_f32_e32 v49, v110, v49
	v_pk_mul_f32 v[110:111], v[92:93], v[20:21]
	v_add_f32_e32 v25, v16, v17
	v_add_f32_e32 v49, v111, v49
	v_add_f32_e32 v49, v110, v49
	v_mul_f32_e32 v53, 0xbfb8aa3b, v49
	v_exp_f32_e32 v53, v53
	v_pk_mul_f32 v[16:17], v[102:103], v[20:21]
	v_add_f32_e32 v53, 1.0, v53
	v_rcp_f32_e32 v53, v53
	v_add_f32_e32 v17, v17, v25
	v_add_f32_e32 v16, v16, v17
	v_mul_f32_e32 v17, 0xbfb8aa3b, v16
	v_mul_f32_e32 v93, v49, v53
	v_add_f32_e32 v49, v105, v26
	v_add_f32_e32 v49, v104, v49
	v_pk_mul_f32 v[104:105], v[82:83], v[130:131]
	v_exp_f32_e32 v17, v17
	v_add_f32_e32 v49, v105, v49
	v_add_f32_e32 v49, v104, v49
	v_mul_f32_e32 v53, 0xbfb8aa3b, v49
	v_exp_f32_e32 v53, v53
	v_add_f32_e32 v17, 1.0, v17
	v_rcp_f32_e32 v17, v17
	v_add_f32_e32 v53, 1.0, v53
	v_rcp_f32_e32 v53, v53
	v_mul_f32_e32 v20, v16, v17
	v_pk_mul_f32 v[16:17], v[68:69], v[36:37]
	v_mul_f32_e32 v83, v49, v53
	v_add_f32_e32 v49, v101, v27
	v_add_f32_e32 v49, v100, v49
	v_pk_mul_f32 v[100:101], v[74:75], v[22:23]
	v_add_f32_e32 v17, v17, v26
	v_add_f32_e32 v49, v101, v49
	v_add_f32_e32 v49, v100, v49
	v_mul_f32_e32 v53, 0xbfb8aa3b, v49
	v_exp_f32_e32 v53, v53
	v_add_f32_e32 v21, v16, v17
	v_pk_mul_f32 v[16:17], v[96:97], v[130:131]
	v_add_f32_e32 v53, 1.0, v53
	v_rcp_f32_e32 v53, v53
	v_add_f32_e32 v17, v17, v21
	v_add_f32_e32 v16, v16, v17
	v_mul_f32_e32 v17, 0xbfb8aa3b, v16
	v_mul_f32_e32 v75, v49, v53
	v_add_f32_e32 v49, v95, v12
	v_add_f32_e32 v49, v94, v49
	v_pk_mul_f32 v[94:95], v[64:65], v[132:133]
	v_exp_f32_e32 v17, v17
	v_add_f32_e32 v49, v95, v49
	v_add_f32_e32 v49, v94, v49
	v_mul_f32_e32 v53, 0xbfb8aa3b, v49
	v_exp_f32_e32 v53, v53
	v_add_f32_e32 v17, 1.0, v17
	v_rcp_f32_e32 v17, v17
	v_add_f32_e32 v53, 1.0, v53
	v_rcp_f32_e32 v53, v53
	v_mul_f32_e32 v21, v16, v17
	v_pk_mul_f32 v[16:17], v[60:61], v[18:19]
	v_mul_f32_e32 v65, v49, v53
	v_add_f32_e32 v49, v89, v13
	v_add_f32_e32 v49, v88, v49
	v_pk_mul_f32 v[88:89], v[58:59], v[8:9]
	v_add_f32_e32 v13, v4, v5
	v_add_f32_e32 v49, v89, v49
	v_add_f32_e32 v49, v88, v49
	v_mul_f32_e32 v53, 0xbfb8aa3b, v49
	v_exp_f32_e32 v53, v53
	v_pk_mul_f32 v[4:5], v[72:73], v[8:9]
	v_add_f32_e32 v17, v17, v27
	v_add_f32_e32 v5, v5, v13
	v_add_f32_e32 v53, 1.0, v53
	v_rcp_f32_e32 v53, v53
	v_add_f32_e32 v4, v4, v5
	v_mul_f32_e32 v5, 0xbfb8aa3b, v4
	v_exp_f32_e32 v5, v5
	v_mul_f32_e32 v59, v49, v53
	v_add_f32_e32 v49, v79, v14
	v_mov_b32_e32 v53, v46
	v_add_f32_e32 v49, v78, v49
	v_pk_mul_f32 v[78:79], v[52:53], v[32:33]
	v_add_f32_e32 v5, 1.0, v5
	v_add_f32_e32 v49, v79, v49
	v_add_f32_e32 v49, v78, v49
	v_mul_f32_e32 v53, 0xbfb8aa3b, v49
	v_exp_f32_e32 v53, v53
	v_rcp_f32_e32 v5, v5
	v_add_f32_e32 v18, v16, v17
	v_pk_mul_f32 v[16:17], v[90:91], v[22:23]
	v_add_f32_e32 v53, 1.0, v53
	v_rcp_f32_e32 v53, v53
	v_mul_f32_e32 v8, v4, v5
	v_pk_mul_f32 v[4:5], v[46:47], v[28:29]
	v_add_f32_e32 v17, v17, v18
	v_mul_f32_e32 v53, v49, v53
	v_add_f32_e32 v49, v71, v15
	v_add_f32_e32 v57, v70, v49
	v_mov_b32_e32 v49, v44
	v_pk_mul_f32 v[70:71], v[48:49], v[10:11]
	v_add_f32_e32 v5, v5, v14
	v_add_f32_e32 v49, v71, v57
	v_add_f32_e32 v49, v70, v49
	v_mul_f32_e32 v57, 0xbfb8aa3b, v49
	v_exp_f32_e32 v57, v57
	v_pk_mul_f32 v[70:71], v[86:87], v[122:123]
	v_add_f32_e32 v9, v4, v5
	v_add_f32_e32 v24, v71, v24
	v_add_f32_e32 v57, 1.0, v57
	v_rcp_f32_e32 v57, v57
	v_pk_mul_f32 v[4:5], v[62:63], v[32:33]
	v_add_f32_e32 v24, v70, v24
	v_pk_mul_f32 v[70:71], v[106:107], v[126:127]
	v_add_f32_e32 v5, v5, v9
	v_add_f32_e32 v24, v71, v24
	v_add_f32_e32 v4, v4, v5
	v_add_f32_e32 v24, v70, v24
	v_mul_f32_e32 v5, 0xbfb8aa3b, v4
	v_mul_f32_e32 v49, v49, v57
	v_mul_f32_e32 v57, 0xbfb8aa3b, v24
	v_add_f32_e32 v16, v16, v17
	v_exp_f32_e32 v5, v5
	v_exp_f32_e32 v57, v57
	v_mul_f32_e32 v17, 0xbfb8aa3b, v16
	v_exp_f32_e32 v17, v17
	v_add_f32_e32 v5, 1.0, v5
	v_add_f32_e32 v57, 1.0, v57
	v_rcp_f32_e32 v5, v5
	v_rcp_f32_e32 v57, v57
	v_add_f32_e32 v17, 1.0, v17
	v_rcp_f32_e32 v17, v17
	v_mul_f32_e32 v9, v4, v5
	v_pk_mul_f32 v[4:5], v[44:45], v[6:7]
	v_mul_f32_e32 v24, v24, v57
	v_add_f32_e32 v5, v5, v15
	v_mov_b32_e32 v57, v48
	v_mul_f32_e32 v18, v16, v17
	v_pk_mul_f32 v[16:17], v[54:55], v[38:39]
	v_add_f32_e32 v6, v4, v5
	v_pk_mul_f32 v[4:5], v[56:57], v[10:11]
	v_add_f32_e32 v12, v17, v12
	v_add_f32_e32 v5, v5, v6
	v_add_f32_e32 v12, v16, v12
	v_pk_mul_f32 v[16:17], v[80:81], v[132:133]
	v_add_f32_e32 v4, v4, v5
	v_add_f32_e32 v12, v17, v12
	v_mul_f32_e32 v5, 0xbfb8aa3b, v4
	v_add_f32_e32 v12, v16, v12
	v_exp_f32_e32 v5, v5
	v_mul_f32_e32 v16, 0xbfb8aa3b, v12
	v_exp_f32_e32 v16, v16
	v_lshl_add_u32 v11, v135, 1, 0
	v_add_f32_e32 v5, 1.0, v5
	v_rcp_f32_e32 v5, v5
	v_add_f32_e32 v16, 1.0, v16
	v_rcp_f32_e32 v16, v16
	v_mul_lo_u32 v13, v40, s55
	v_cvt_pk_bf16_f32 v6, v117, v115
	v_add_u32_e32 v130, v11, v13
	v_mul_f32_e32 v10, v4, v5
	v_cvt_pk_bf16_f32 v4, v129, v125
	v_cvt_pk_bf16_f32 v5, v121, v119
	v_cvt_pk_bf16_f32 v7, v30, v31
	ds_write_b128 v130, v[4:7] offset:34816
	v_cvt_pk_bf16_f32 v6, v116, v114
	v_or_b32_e32 v13, 3, v136
	v_cvt_pk_bf16_f32 v4, v34, v35
	v_cvt_pk_bf16_f32 v5, v99, v109
	v_cvt_pk_bf16_f32 v7, v108, v98
	ds_write_b128 v130, v[4:7] offset:35088
	v_cvt_pk_bf16_f32 v6, v65, v59
	v_mul_lo_u32 v13, v13, s55
	v_mul_f32_e32 v12, v12, v16
	v_cvt_pk_bf16_f32 v4, v85, v93
	v_cvt_pk_bf16_f32 v5, v83, v75
	v_cvt_pk_bf16_f32 v7, v53, v49
	ds_write_b128 v130, v[4:7] offset:35360
	v_cvt_pk_bf16_f32 v6, v12, v8
	v_add_u32_e32 v131, v11, v13
	v_cvt_pk_bf16_f32 v4, v24, v20
	v_cvt_pk_bf16_f32 v5, v21, v18
	v_cvt_pk_bf16_f32 v7, v9, v10
	ds_write_b128 v131, v[4:7] offset:34816
	v_mul_u32_u24_e32 v6, 0x110, v135
	v_add3_u32 v11, s52, v137, v6
	v_cvt_pk_bf16_f32 v6, v125, v35
	v_cvt_pk_bf16_f32 v4, v129, v34
	v_cvt_pk_bf16_f32 v5, v85, v24
	v_cvt_pk_bf16_f32 v7, v93, v20
	ds_write2_b64 v11, v[4:5], v[6:7] offset1:34
	v_cvt_pk_bf16_f32 v6, v119, v109
	v_cvt_pk_bf16_f32 v4, v121, v99
	v_cvt_pk_bf16_f32 v5, v83, v21
	v_cvt_pk_bf16_f32 v7, v75, v18
	ds_write2_b64 v11, v[4:5], v[6:7] offset0:68 offset1:102
	v_cvt_pk_bf16_f32 v6, v115, v114
	v_cvt_pk_bf16_f32 v4, v117, v116
	v_cvt_pk_bf16_f32 v5, v65, v12
	v_cvt_pk_bf16_f32 v7, v59, v8
	ds_write2_b64 v11, v[4:5], v[6:7] offset0:136 offset1:170
	v_cvt_pk_bf16_f32 v6, v31, v98
	v_cvt_pk_bf16_f32 v4, v30, v108
	v_cvt_pk_bf16_f32 v5, v53, v9
	v_cvt_pk_bf16_f32 v7, v49, v10
	ds_write2_b64 v11, v[4:5], v[6:7] offset0:204 offset1:238
	v_or_b32_e32 v6, 0x500, v67
	v_lshlrev_b32_e32 v4, 1, v6
	v_mov_b32_e32 v109, 0
	v_mov_b32_e32 v115, 0
	v_mov_b32_e32 v117, 0
	v_mov_b32_e32 v119, 0
	v_mov_b32_e32 v121, 0
	v_mov_b32_e32 v125, 0
	v_mov_b32_e32 v244, 0
	v_mov_b32_e32 v245, 0
	v_mov_b32_e32 v246, 0
	v_mov_b32_e32 v247, 0
	s_and_saveexec_b64 s[2:3], s[0:1]
	s_cbranch_execz .LBB0_230
	v_mov_b32_e32 v5, v2
	v_lshl_add_u64 v[8:9], v[42:43], 0, v[4:5]
	v_add_co_u32_e32 v8, vcc, 0xffffa000, v8
	s_nop 1
	v_addc_co_u32_e32 v9, vcc, -1, v9, vcc
	global_load_dwordx4 v[244:247], v[8:9], off offset:-3072
.LBB0_230:
	s_or_b64 exec, exec, s[2:3]
	v_mov_b32_e32 v107, 0
	v_mov_b32_e32 v40, 0
	v_mov_b32_e32 v108, 0
	v_mov_b32_e32 v112, 0
	v_mov_b32_e32 v114, 0
	v_mov_b32_e32 v116, 0
	v_mov_b32_e32 v118, 0
	v_mov_b32_e32 v120, 0
	v_mov_b32_e32 v124, 0
	v_mov_b32_e32 v248, 0
	v_mov_b32_e32 v249, 0
	v_mov_b32_e32 v250, 0
	v_mov_b32_e32 v251, 0
	s_and_saveexec_b64 s[0:1], s[14:15]
	s_cbranch_execz .LBB0_232
	v_mov_b32_e32 v5, v2
	v_lshl_add_u64 v[8:9], v[42:43], 0, v[4:5]
	v_add_co_u32_e32 v8, vcc, 0xffffc000, v8
	s_nop 1
	v_addc_co_u32_e32 v9, vcc, -1, v9, vcc
	global_load_dwordx4 v[248:251], v[8:9], off offset:-2048
.LBB0_232:
	s_or_b64 exec, exec, s[0:1]
	v_mov_b32_e32 v111, 0
	v_mov_b32_e32 v105, 0
	v_mov_b32_e32 v101, 0
	v_mov_b32_e32 v93, 0
	v_mov_b32_e32 v87, 0
	v_mov_b32_e32 v81, 0
	v_mov_b32_e32 v71, 0
	v_mov_b32_e32 v252, 0
	v_mov_b32_e32 v253, 0
	v_mov_b32_e32 v254, 0
	v_mov_b32_e32 v255, 0
	s_and_saveexec_b64 s[0:1], s[4:5]
	s_cbranch_execz .LBB0_234
	v_mov_b32_e32 v5, v2
	v_lshl_add_u64 v[8:9], v[42:43], 0, v[4:5]
	v_add_co_u32_e32 v8, vcc, 0xffffe000, v8
	s_nop 1
	v_addc_co_u32_e32 v9, vcc, -1, v9, vcc
	global_load_dwordx4 v[252:255], v[8:9], off offset:-1024
.LBB0_234:
	s_or_b64 exec, exec, s[0:1]
	s_waitcnt vmcnt(0)
	v_lshlrev_b32_e32 v125, 16, v244
	v_and_b32_e32 v121, 0xffff0000, v244
	v_lshlrev_b32_e32 v119, 16, v245
	v_and_b32_e32 v117, 0xffff0000, v245
	v_lshlrev_b32_e32 v115, 16, v246
	v_and_b32_e32 v113, 0xffff0000, v246
	v_lshlrev_b32_e32 v109, 16, v247
	v_and_b32_e32 v41, 0xffff0000, v247
	v_lshlrev_b32_e32 v124, 16, v248
	v_and_b32_e32 v120, 0xffff0000, v248
	v_lshlrev_b32_e32 v118, 16, v249
	v_and_b32_e32 v116, 0xffff0000, v249
	v_lshlrev_b32_e32 v114, 16, v250
	v_and_b32_e32 v112, 0xffff0000, v250
	v_lshlrev_b32_e32 v108, 16, v251
	v_and_b32_e32 v40, 0xffff0000, v251
	v_lshlrev_b32_e32 v107, 16, v252
	v_and_b32_e32 v111, 0xffff0000, v252
	v_lshlrev_b32_e32 v105, 16, v253
	v_and_b32_e32 v101, 0xffff0000, v253
	v_lshlrev_b32_e32 v93, 16, v254
	v_and_b32_e32 v87, 0xffff0000, v254
	v_lshlrev_b32_e32 v81, 16, v255
	v_and_b32_e32 v71, 0xffff0000, v255
	v_mov_b32_e32 v72, 0
	v_mov_b32_e32 v106, 0
	v_mov_b32_e32 v110, 0
	v_mov_b32_e32 v104, 0
	v_mov_b32_e32 v100, 0
	v_mov_b32_e32 v92, 0
	v_mov_b32_e32 v86, 0
	v_mov_b32_e32 v80, 0
	v_mov_b32_e32 v70, 0
	v_mov_b32_e32 v244, 0
	v_mov_b32_e32 v245, 0
	v_mov_b32_e32 v246, 0
	v_mov_b32_e32 v247, 0
	s_and_saveexec_b64 s[0:1], s[6:7]
	s_cbranch_execz .LBB0_236
	v_mov_b32_e32 v5, v2
	v_lshl_add_u64 v[8:9], v[42:43], 0, v[4:5]
	global_load_dwordx4 v[244:247], v[8:9], off
.LBB0_236:
	s_or_b64 exec, exec, s[0:1]
	v_mov_b32_e32 v78, 0
	v_mov_b32_e32 v68, 0
	v_mov_b32_e32 v60, 0
	v_mov_b32_e32 v54, 0
	v_mov_b32_e32 v50, 0
	v_mov_b32_e32 v46, 0
	v_mov_b32_e32 v44, 0
	v_mov_b32_e32 v248, 0
	v_mov_b32_e32 v249, 0
	v_mov_b32_e32 v250, 0
	v_mov_b32_e32 v251, 0
	s_and_saveexec_b64 s[0:1], s[8:9]
	s_cbranch_execz .LBB0_238
	v_mov_b32_e32 v5, v2
	v_lshl_add_u64 v[8:9], v[42:43], 0, v[4:5]
	v_add_co_u32_e32 v8, vcc, 0x2000, v8
	s_nop 1
	v_addc_co_u32_e32 v9, vcc, 0, v9, vcc
	global_load_dwordx4 v[248:251], v[8:9], off offset:1024
.LBB0_238:
	s_or_b64 exec, exec, s[0:1]
	v_mov_b32_e32 v96, 0
	v_mov_b32_e32 v98, 0
	v_mov_b32_e32 v90, 0
	v_mov_b32_e32 v84, 0
	v_mov_b32_e32 v76, 0
	v_mov_b32_e32 v64, 0
	v_mov_b32_e32 v58, 0
	v_mov_b32_e32 v52, 0
	v_mov_b32_e32 v48, 0
	v_mov_b32_e32 v252, 0
	v_mov_b32_e32 v253, 0
	v_mov_b32_e32 v254, 0
	v_mov_b32_e32 v255, 0
	s_and_saveexec_b64 s[0:1], s[10:11]
	s_cbranch_execz .LBB0_240
	v_mov_b32_e32 v5, v2
	v_lshl_add_u64 v[8:9], v[42:43], 0, v[4:5]
	v_add_co_u32_e32 v8, vcc, 0x4000, v8
	s_nop 1
	v_addc_co_u32_e32 v9, vcc, 0, v9, vcc
	global_load_dwordx4 v[252:255], v[8:9], off offset:2048
.LBB0_240:
	s_or_b64 exec, exec, s[0:1]
	s_waitcnt vmcnt(0)
	v_lshlrev_b32_e32 v106, 16, v244
	v_and_b32_e32 v110, 0xffff0000, v244
	v_lshlrev_b32_e32 v104, 16, v245
	v_and_b32_e32 v100, 0xffff0000, v245
	v_lshlrev_b32_e32 v92, 16, v246
	v_and_b32_e32 v86, 0xffff0000, v246
	v_lshlrev_b32_e32 v80, 16, v247
	v_and_b32_e32 v70, 0xffff0000, v247
	v_lshlrev_b32_e32 v72, 16, v248
	v_and_b32_e32 v78, 0xffff0000, v248
	v_lshlrev_b32_e32 v68, 16, v249
	v_and_b32_e32 v60, 0xffff0000, v249
	v_lshlrev_b32_e32 v54, 16, v250
	v_and_b32_e32 v50, 0xffff0000, v250
	v_lshlrev_b32_e32 v46, 16, v251
	v_and_b32_e32 v44, 0xffff0000, v251
	v_lshlrev_b32_e32 v98, 16, v252
	v_and_b32_e32 v90, 0xffff0000, v252
	v_lshlrev_b32_e32 v84, 16, v253
	v_and_b32_e32 v76, 0xffff0000, v253
	v_lshlrev_b32_e32 v64, 16, v254
	v_and_b32_e32 v58, 0xffff0000, v254
	v_lshlrev_b32_e32 v52, 16, v255
	v_and_b32_e32 v48, 0xffff0000, v255
	v_mov_b32_e32 v102, 0
	v_mov_b32_e32 v94, 0
	v_mov_b32_e32 v88, 0
	v_mov_b32_e32 v82, 0
	v_mov_b32_e32 v74, 0
	v_mov_b32_e32 v62, 0
	v_mov_b32_e32 v56, 0
	v_mov_b32_e32 v244, 0
	v_mov_b32_e32 v245, 0
	v_mov_b32_e32 v246, 0
	v_mov_b32_e32 v247, 0
	s_and_saveexec_b64 s[0:1], s[12:13]
	s_cbranch_execz .LBB0_242
	v_mov_b32_e32 v5, v2
	v_lshl_add_u64 v[4:5], v[42:43], 0, v[4:5]
	v_add_co_u32_e32 v4, vcc, 0x6000, v4
	s_nop 1
	v_addc_co_u32_e32 v5, vcc, 0, v5, vcc
	global_load_dwordx4 v[244:247], v[4:5], off offset:3072
.LBB0_242:
	s_or_b64 exec, exec, s[0:1]
	s_waitcnt vmcnt(0)
	v_lshlrev_b32_e32 v96, 16, v244
	v_and_b32_e32 v102, 0xffff0000, v244
	v_lshlrev_b32_e32 v94, 16, v245
	v_and_b32_e32 v88, 0xffff0000, v245
	v_lshlrev_b32_e32 v82, 16, v246
	v_and_b32_e32 v74, 0xffff0000, v246
	v_lshlrev_b32_e32 v62, 16, v247
	v_and_b32_e32 v56, 0xffff0000, v247
	v_readlane_b32 s0, v242, 2
	v_lshlrev_b32_e32 v24, 2, v6
	v_mov_b32_e32 v25, v2
	v_readlane_b32 s4, v242, 6
	v_readlane_b32 s5, v242, 7
	v_readlane_b32 s1, v242, 3
	s_mov_b64 s[0:1], 0x1800
	v_lshl_add_u64 v[12:13], s[4:5], 0, v[24:25]
	v_add_co_u32_e32 v10, vcc, s34, v12
	v_lshl_add_u64 v[8:9], v[12:13], 0, s[0:1]
	s_nop 0
	v_addc_co_u32_e32 v11, vcc, 0, v13, vcc
	s_mov_b64 s[0:1], 0x3000
	global_load_dwordx4 v[4:7], v24, s[4:5] offset:16
	global_load_dwordx4 v[16:19], v24, s[4:5]
	global_load_dwordx4 v[36:39], v[10:11], off offset:2048
	global_load_dwordx4 v[28:31], v[8:9], off offset:16
	v_lshl_add_u64 v[8:9], v[12:13], 0, s[0:1]
	s_movk_i32 s0, 0x3000
	v_add_co_u32_e32 v10, vcc, s0, v12
	s_mov_b64 s[0:1], 0x4800
	s_nop 0
	v_addc_co_u32_e32 v11, vcc, 0, v13, vcc
	v_lshl_add_u64 v[14:15], v[12:13], 0, s[0:1]
	v_add_co_u32_e32 v12, vcc, s35, v12
	v_readlane_b32 s6, v242, 8
	s_nop 0
	v_addc_co_u32_e32 v13, vcc, 0, v13, vcc
	v_readlane_b32 s7, v242, 9
	global_load_dwordx4 v[20:23], v[10:11], off
	s_nop 0
	global_load_dwordx4 v[8:11], v[8:9], off offset:16
	s_nop 0
	global_load_dwordx4 v[126:129], v[12:13], off offset:2048
	global_load_dwordx4 v[32:35], v[14:15], off offset:16
	s_nop 0
	global_load_dwordx4 v[12:15], v24, s[6:7] offset:16
	s_nop 0
	global_load_dwordx4 v[24:27], v24, s[6:7]
	v_mov_b32_e32 v73, v106
	v_mov_b32_e32 v79, v110
	v_mov_b32_e32 v69, v104
	v_mov_b32_e32 v61, v100
	v_mov_b32_e32 v55, v92
	v_mov_b32_e32 v51, v86
	v_mov_b32_e32 v99, v72
	v_mov_b32_e32 v91, v78
	v_mov_b32_e32 v85, v68
	v_mov_b32_e32 v77, v60
	v_mov_b32_e32 v65, v54
	v_mov_b32_e32 v103, v90
	v_mov_b32_e32 v59, v50
	v_mov_b32_e32 v75, v58
	v_mov_b32_e32 v95, v84
	v_mov_b32_e32 v63, v52
	v_mov_b32_e32 v89, v76
	v_mov_b32_e32 v83, v64
	v_mov_b32_e32 v97, v98
	v_and_b32_e32 v67, 15, v66
	s_movk_i32 s0, 0x100
	v_cmp_gt_i32_e64 s[90:91], s0, v66
	s_movk_i32 s0, 0xff
	v_cmp_lt_i32_e32 vcc, s0, v66
	v_readlane_b32 s2, v242, 4
	v_readlane_b32 s3, v242, 5
	v_readlane_b32 s8, v242, 10
	v_readlane_b32 s9, v242, 11
	v_readlane_b32 s10, v242, 12
	v_readlane_b32 s11, v242, 13
	v_readlane_b32 s12, v242, 14
	v_readlane_b32 s13, v242, 15
	v_readlane_b32 s14, v242, 16
	v_readlane_b32 s15, v242, 17
	s_waitcnt vmcnt(8)
	v_mov_b32_e32 v43, v16
	s_waitcnt vmcnt(7)
	v_mov_b32_e32 v42, v36
	v_pk_mul_f32 v[122:123], v[124:125], v[42:43]
	s_waitcnt vmcnt(0)
	v_add_f32_e32 v16, v123, v24
	v_add_f32_e32 v16, v122, v16
	v_mov_b32_e32 v122, v126
	v_mov_b32_e32 v123, v20
	v_pk_mul_f32 v[132:133], v[106:107], v[122:123]
	s_nop 0
	v_add_f32_e32 v16, v133, v16
	v_add_f32_e32 v16, v132, v16
	v_mul_f32_e32 v20, 0xbfb8aa3b, v16
	v_exp_f32_e32 v20, v20
	s_nop 0
	v_add_f32_e32 v20, 1.0, v20
	v_rcp_f32_e32 v20, v20
	s_nop 0
	v_mul_f32_e32 v125, v16, v20
	v_mov_b32_e32 v16, v37
	v_pk_mul_f32 v[36:37], v[120:121], v[16:17]
	s_nop 0
	v_add_f32_e32 v20, v37, v25
	v_add_f32_e32 v45, v36, v20
	v_mov_b32_e32 v20, v127
	v_pk_mul_f32 v[36:37], v[110:111], v[20:21]
	s_nop 0
	v_add_f32_e32 v37, v37, v45
	v_add_f32_e32 v36, v36, v37
	v_mul_f32_e32 v37, 0xbfb8aa3b, v36
	v_exp_f32_e32 v37, v37
	s_nop 0
	v_add_f32_e32 v37, 1.0, v37
	v_rcp_f32_e32 v37, v37
	s_nop 0
	v_mul_f32_e32 v121, v36, v37
	v_mov_b32_e32 v36, v38
	v_mov_b32_e32 v37, v18
	v_pk_mul_f32 v[126:127], v[118:119], v[36:37]
	s_nop 0
	v_add_f32_e32 v18, v127, v26
	v_add_f32_e32 v18, v126, v18
	v_mov_b32_e32 v126, v128
	v_mov_b32_e32 v127, v22
	v_pk_mul_f32 v[132:133], v[104:105], v[126:127]
	s_nop 0
	v_add_f32_e32 v18, v133, v18
	v_add_f32_e32 v18, v132, v18
	v_mul_f32_e32 v22, 0xbfb8aa3b, v18
	v_exp_f32_e32 v22, v22
	s_nop 0
	v_add_f32_e32 v22, 1.0, v22
	v_rcp_f32_e32 v22, v22
	s_nop 0
	v_mul_f32_e32 v119, v18, v22
	v_mov_b32_e32 v18, v39
	v_pk_mul_f32 v[38:39], v[116:117], v[18:19]
	s_nop 0
	v_add_f32_e32 v22, v39, v27
	v_add_f32_e32 v45, v38, v22
	v_mov_b32_e32 v22, v129
	v_pk_mul_f32 v[38:39], v[100:101], v[22:23]
	s_nop 0
	v_add_f32_e32 v39, v39, v45
	v_add_f32_e32 v38, v38, v39
	v_mul_f32_e32 v39, 0xbfb8aa3b, v38
	v_exp_f32_e32 v39, v39
	s_nop 0
	v_add_f32_e32 v39, 1.0, v39
	v_rcp_f32_e32 v39, v39
	s_nop 0
	v_mul_f32_e32 v117, v38, v39
	v_mov_b32_e32 v38, v28
	v_mov_b32_e32 v39, v4
	v_pk_mul_f32 v[128:129], v[114:115], v[38:39]
	s_nop 0
	v_add_f32_e32 v4, v129, v12
	v_add_f32_e32 v4, v128, v4
	v_mov_b32_e32 v128, v32
	v_mov_b32_e32 v129, v8
	v_pk_mul_f32 v[132:133], v[92:93], v[128:129]
	s_nop 0
	v_add_f32_e32 v4, v133, v4
	v_add_f32_e32 v4, v132, v4
	v_mul_f32_e32 v8, 0xbfb8aa3b, v4
	v_exp_f32_e32 v8, v8
	s_nop 0
	v_add_f32_e32 v8, 1.0, v8
	v_rcp_f32_e32 v8, v8
	s_nop 0
	v_mul_f32_e32 v115, v4, v8
	v_mov_b32_e32 v4, v29
	v_pk_mul_f32 v[28:29], v[112:113], v[4:5]
	s_nop 0
	v_add_f32_e32 v8, v29, v13
	v_add_f32_e32 v32, v28, v8
	v_mov_b32_e32 v8, v33
	v_pk_mul_f32 v[28:29], v[86:87], v[8:9]
	s_nop 0
	v_add_f32_e32 v29, v29, v32
	v_add_f32_e32 v28, v28, v29
	v_mul_f32_e32 v29, 0xbfb8aa3b, v28
	v_exp_f32_e32 v29, v29
	s_nop 0
	v_add_f32_e32 v29, 1.0, v29
	v_rcp_f32_e32 v29, v29
	s_nop 0
	v_mul_f32_e32 v113, v28, v29
	v_mov_b32_e32 v28, v30
	v_mov_b32_e32 v29, v6
	v_pk_mul_f32 v[32:33], v[108:109], v[28:29]
	s_nop 0
	v_add_f32_e32 v6, v33, v14
	v_add_f32_e32 v6, v32, v6
	v_mov_b32_e32 v32, v34
	v_mov_b32_e32 v33, v10
	v_pk_mul_f32 v[132:133], v[80:81], v[32:33]
	s_nop 0
	v_add_f32_e32 v6, v133, v6
	v_add_f32_e32 v6, v132, v6
	v_mul_f32_e32 v10, 0xbfb8aa3b, v6
	v_exp_f32_e32 v10, v10
	s_nop 0
	v_add_f32_e32 v10, 1.0, v10
	v_rcp_f32_e32 v10, v10
	s_nop 0
	v_mul_f32_e32 v30, v6, v10
	v_mov_b32_e32 v6, v31
	v_pk_mul_f32 v[132:133], v[40:41], v[6:7]
	s_nop 0
	v_add_f32_e32 v10, v133, v15
	v_add_f32_e32 v31, v132, v10
	v_mov_b32_e32 v10, v35
	v_pk_mul_f32 v[34:35], v[70:71], v[10:11]
	v_mov_b32_e32 v132, v111
	v_add_f32_e32 v31, v35, v31
	v_add_f32_e32 v31, v34, v31
	v_mul_f32_e32 v34, 0xbfb8aa3b, v31
	v_exp_f32_e32 v34, v34
	v_mov_b32_e32 v35, v124
	v_mov_b32_e32 v133, v120
	v_pk_mul_f32 v[132:133], v[132:133], v[16:17]
	v_add_f32_e32 v34, 1.0, v34
	v_rcp_f32_e32 v34, v34
	s_nop 0
	v_mul_f32_e32 v31, v31, v34
	v_mov_b32_e32 v34, v107
	v_pk_mul_f32 v[34:35], v[34:35], v[42:43]
	v_pk_mul_f32 v[106:107], v[106:107], v[42:43]
	v_add_f32_e32 v35, v35, v24
	v_add_f32_e32 v41, v34, v35
	v_pk_mul_f32 v[34:35], v[72:73], v[122:123]
	v_pk_mul_f32 v[42:43], v[72:73], v[42:43]
	v_add_f32_e32 v35, v35, v41
	v_add_f32_e32 v34, v34, v35
	v_mul_f32_e32 v35, 0xbfb8aa3b, v34
	v_exp_f32_e32 v35, v35
	s_nop 0
	v_add_f32_e32 v35, 1.0, v35
	v_rcp_f32_e32 v35, v35
	s_nop 0
	v_mul_f32_e32 v34, v34, v35
	v_add_f32_e32 v35, v133, v25
	v_add_f32_e32 v35, v132, v35
	v_pk_mul_f32 v[132:133], v[78:79], v[20:21]
	s_nop 0
	v_add_f32_e32 v35, v133, v35
	v_add_f32_e32 v35, v132, v35
	v_mul_f32_e32 v41, 0xbfb8aa3b, v35
	v_exp_f32_e32 v41, v41
	v_mov_b32_e32 v132, v105
	v_mov_b32_e32 v133, v118
	v_pk_mul_f32 v[132:133], v[132:133], v[36:37]
	v_add_f32_e32 v41, 1.0, v41
	v_rcp_f32_e32 v41, v41
	v_pk_mul_f32 v[104:105], v[104:105], v[36:37]
	v_mul_f32_e32 v35, v35, v41
	v_add_f32_e32 v41, v133, v26
	v_add_f32_e32 v41, v132, v41
	v_pk_mul_f32 v[132:133], v[68:69], v[126:127]
	s_nop 0
	v_add_f32_e32 v41, v133, v41
	v_add_f32_e32 v41, v132, v41
	v_mul_f32_e32 v45, 0xbfb8aa3b, v41
	v_exp_f32_e32 v45, v45
	v_mov_b32_e32 v132, v101
	v_mov_b32_e32 v133, v116
	v_pk_mul_f32 v[132:133], v[132:133], v[18:19]
	v_add_f32_e32 v45, 1.0, v45
	v_rcp_f32_e32 v45, v45
	v_pk_mul_f32 v[100:101], v[100:101], v[18:19]
	v_mul_f32_e32 v41, v41, v45
	v_add_f32_e32 v45, v133, v27
	v_add_f32_e32 v45, v132, v45
	v_pk_mul_f32 v[132:133], v[60:61], v[22:23]
	s_nop 0
	v_add_f32_e32 v45, v133, v45
	v_add_f32_e32 v45, v132, v45
	v_mul_f32_e32 v47, 0xbfb8aa3b, v45
	v_exp_f32_e32 v47, v47
	v_mov_b32_e32 v132, v93
	v_mov_b32_e32 v133, v114
	v_pk_mul_f32 v[132:133], v[132:133], v[38:39]
	v_add_f32_e32 v47, 1.0, v47
	v_rcp_f32_e32 v47, v47
	v_pk_mul_f32 v[92:93], v[92:93], v[38:39]
	v_mul_f32_e32 v109, v45, v47
	v_add_f32_e32 v45, v133, v12
	v_add_f32_e32 v45, v132, v45
	v_pk_mul_f32 v[132:133], v[54:55], v[128:129]
	s_nop 0
	v_add_f32_e32 v45, v133, v45
	v_add_f32_e32 v45, v132, v45
	v_mul_f32_e32 v47, 0xbfb8aa3b, v45
	v_exp_f32_e32 v47, v47
	v_mov_b32_e32 v132, v87
	v_mov_b32_e32 v133, v112
	v_pk_mul_f32 v[132:133], v[132:133], v[4:5]
	v_add_f32_e32 v47, 1.0, v47
	v_rcp_f32_e32 v47, v47
	v_pk_mul_f32 v[86:87], v[86:87], v[4:5]
	v_pk_mul_f32 v[4:5], v[50:51], v[4:5]
	v_mul_f32_e32 v114, v45, v47
	v_add_f32_e32 v45, v133, v13
	v_add_f32_e32 v45, v132, v45
	v_pk_mul_f32 v[132:133], v[50:51], v[8:9]
	v_add_f32_e32 v5, v5, v13
	v_add_f32_e32 v45, v133, v45
	v_add_f32_e32 v45, v132, v45
	v_mul_f32_e32 v47, 0xbfb8aa3b, v45
	v_exp_f32_e32 v47, v47
	v_mov_b32_e32 v132, v81
	v_mov_b32_e32 v133, v108
	v_pk_mul_f32 v[132:133], v[132:133], v[28:29]
	v_add_f32_e32 v47, 1.0, v47
	v_rcp_f32_e32 v47, v47
	s_nop 0
	v_mul_f32_e32 v112, v45, v47
	v_add_f32_e32 v45, v133, v14
	v_mov_b32_e32 v47, v80
	v_add_f32_e32 v45, v132, v45
	v_pk_mul_f32 v[132:133], v[46:47], v[32:33]
	v_pk_mul_f32 v[80:81], v[80:81], v[28:29]
	v_add_f32_e32 v45, v133, v45
	v_add_f32_e32 v45, v132, v45
	v_mul_f32_e32 v49, 0xbfb8aa3b, v45
	v_exp_f32_e32 v49, v49
	v_mov_b32_e32 v132, v71
	v_mov_b32_e32 v133, v40
	v_pk_mul_f32 v[132:133], v[132:133], v[6:7]
	v_add_f32_e32 v49, 1.0, v49
	v_rcp_f32_e32 v49, v49
	v_add_f32_e32 v40, v133, v15
	v_add_f32_e32 v40, v132, v40
	v_mul_f32_e32 v108, v45, v49
	v_mov_b32_e32 v45, v70
	v_pk_mul_f32 v[132:133], v[44:45], v[10:11]
	v_pk_mul_f32 v[70:71], v[70:71], v[6:7]
	v_add_f32_e32 v40, v133, v40
	v_add_f32_e32 v40, v132, v40
	v_mul_f32_e32 v49, 0xbfb8aa3b, v40
	v_exp_f32_e32 v49, v49
	s_nop 0
	v_add_f32_e32 v49, 1.0, v49
	v_rcp_f32_e32 v49, v49
	s_nop 0
	v_mul_f32_e32 v40, v40, v49
	v_add_f32_e32 v49, v107, v24
	v_add_f32_e32 v49, v106, v49
	v_pk_mul_f32 v[106:107], v[98:99], v[122:123]
	v_add_f32_e32 v24, v43, v24
	v_add_f32_e32 v49, v107, v49
	v_add_f32_e32 v49, v106, v49
	v_mul_f32_e32 v53, 0xbfb8aa3b, v49
	v_exp_f32_e32 v53, v53
	v_pk_mul_f32 v[106:107], v[110:111], v[16:17]
	v_pk_mul_f32 v[16:17], v[78:79], v[16:17]
	v_add_f32_e32 v24, v42, v24
	v_add_f32_e32 v53, 1.0, v53
	v_rcp_f32_e32 v53, v53
	v_add_f32_e32 v17, v17, v25
	v_pk_mul_f32 v[42:43], v[96:97], v[122:123]
	v_bfe_u32 v78, v66, 6, 1
	v_mul_f32_e32 v99, v49, v53
	v_add_f32_e32 v49, v107, v25
	v_add_f32_e32 v49, v106, v49
	v_pk_mul_f32 v[106:107], v[90:91], v[20:21]
	v_add_f32_e32 v25, v16, v17
	v_add_f32_e32 v49, v107, v49
	v_add_f32_e32 v49, v106, v49
	v_mul_f32_e32 v53, 0xbfb8aa3b, v49
	v_exp_f32_e32 v53, v53
	v_pk_mul_f32 v[16:17], v[102:103], v[20:21]
	v_add_f32_e32 v24, v43, v24
	v_add_f32_e32 v17, v17, v25
	v_add_f32_e32 v53, 1.0, v53
	v_rcp_f32_e32 v53, v53
	v_add_f32_e32 v16, v16, v17
	v_mul_f32_e32 v17, 0xbfb8aa3b, v16
	v_exp_f32_e32 v17, v17
	v_mul_f32_e32 v91, v49, v53
	v_add_f32_e32 v49, v105, v26
	v_add_f32_e32 v49, v104, v49
	v_pk_mul_f32 v[104:105], v[84:85], v[126:127]
	v_add_f32_e32 v17, 1.0, v17
	v_add_f32_e32 v49, v105, v49
	v_add_f32_e32 v49, v104, v49
	v_mul_f32_e32 v53, 0xbfb8aa3b, v49
	v_exp_f32_e32 v53, v53
	v_rcp_f32_e32 v17, v17
	v_add_f32_e32 v24, v42, v24
	v_mul_f32_e32 v42, 0xbfb8aa3b, v24
	v_add_f32_e32 v53, 1.0, v53
	v_rcp_f32_e32 v53, v53
	v_mul_f32_e32 v20, v16, v17
	v_pk_mul_f32 v[16:17], v[68:69], v[36:37]
	v_exp_f32_e32 v42, v42
	v_mul_f32_e32 v85, v49, v53
	v_add_f32_e32 v49, v101, v27
	v_add_f32_e32 v49, v100, v49
	v_pk_mul_f32 v[100:101], v[76:77], v[22:23]
	v_add_f32_e32 v17, v17, v26
	v_add_f32_e32 v49, v101, v49
	v_add_f32_e32 v49, v100, v49
	v_mul_f32_e32 v53, 0xbfb8aa3b, v49
	v_exp_f32_e32 v53, v53
	v_add_f32_e32 v21, v16, v17
	v_pk_mul_f32 v[16:17], v[94:95], v[126:127]
	v_add_f32_e32 v42, 1.0, v42
	v_add_f32_e32 v53, 1.0, v53
	v_rcp_f32_e32 v53, v53
	v_add_f32_e32 v17, v17, v21
	v_add_f32_e32 v16, v16, v17
	v_mul_f32_e32 v17, 0xbfb8aa3b, v16
	v_mul_f32_e32 v77, v49, v53
	v_add_f32_e32 v49, v93, v12
	v_add_f32_e32 v49, v92, v49
	v_pk_mul_f32 v[92:93], v[64:65], v[128:129]
	v_exp_f32_e32 v17, v17
	v_add_f32_e32 v49, v93, v49
	v_add_f32_e32 v49, v92, v49
	v_mul_f32_e32 v53, 0xbfb8aa3b, v49
	v_exp_f32_e32 v53, v53
	v_add_f32_e32 v17, 1.0, v17
	v_rcp_f32_e32 v17, v17
	v_rcp_f32_e32 v42, v42
	v_add_f32_e32 v53, 1.0, v53
	v_rcp_f32_e32 v53, v53
	v_mul_f32_e32 v21, v16, v17
	v_pk_mul_f32 v[16:17], v[60:61], v[18:19]
	v_ashrrev_i32_e32 v76, 7, v66
	v_mul_f32_e32 v65, v49, v53
	v_add_f32_e32 v49, v87, v13
	v_add_f32_e32 v49, v86, v49
	v_pk_mul_f32 v[86:87], v[58:59], v[8:9]
	v_add_f32_e32 v13, v4, v5
	v_add_f32_e32 v49, v87, v49
	v_add_f32_e32 v49, v86, v49
	v_mul_f32_e32 v53, 0xbfb8aa3b, v49
	v_exp_f32_e32 v53, v53
	v_pk_mul_f32 v[4:5], v[74:75], v[8:9]
	v_add_f32_e32 v17, v17, v27
	v_add_f32_e32 v5, v5, v13
	v_add_f32_e32 v53, 1.0, v53
	v_rcp_f32_e32 v53, v53
	v_add_f32_e32 v4, v4, v5
	v_mul_f32_e32 v5, 0xbfb8aa3b, v4
	v_exp_f32_e32 v5, v5
	v_mul_f32_e32 v59, v49, v53
	v_add_f32_e32 v49, v81, v14
	v_mov_b32_e32 v53, v46
	v_add_f32_e32 v49, v80, v49
	v_pk_mul_f32 v[80:81], v[52:53], v[32:33]
	v_add_f32_e32 v5, 1.0, v5
	v_add_f32_e32 v49, v81, v49
	v_add_f32_e32 v49, v80, v49
	v_mul_f32_e32 v53, 0xbfb8aa3b, v49
	v_exp_f32_e32 v53, v53
	v_rcp_f32_e32 v5, v5
	v_add_f32_e32 v18, v16, v17
	v_pk_mul_f32 v[16:17], v[88:89], v[22:23]
	v_add_f32_e32 v53, 1.0, v53
	v_rcp_f32_e32 v53, v53
	v_mul_f32_e32 v8, v4, v5
	v_pk_mul_f32 v[4:5], v[46:47], v[28:29]
	v_add_f32_e32 v17, v17, v18
	v_mul_f32_e32 v53, v49, v53
	v_add_f32_e32 v49, v71, v15
	v_add_f32_e32 v5, v5, v14
	v_add_f32_e32 v57, v70, v49
	v_mov_b32_e32 v49, v44
	v_add_f32_e32 v9, v4, v5
	v_pk_mul_f32 v[4:5], v[62:63], v[32:33]
	v_pk_mul_f32 v[70:71], v[48:49], v[10:11]
	v_add_f32_e32 v5, v5, v9
	v_add_f32_e32 v49, v71, v57
	v_add_f32_e32 v4, v4, v5
	v_add_f32_e32 v49, v70, v49
	v_add_f32_e32 v16, v16, v17
	v_mul_f32_e32 v5, 0xbfb8aa3b, v4
	v_mul_f32_e32 v57, 0xbfb8aa3b, v49
	v_mul_f32_e32 v17, 0xbfb8aa3b, v16
	v_exp_f32_e32 v5, v5
	v_exp_f32_e32 v57, v57
	v_exp_f32_e32 v17, v17
	v_lshlrev_b32_e32 v80, 5, v76
	v_add_f32_e32 v5, 1.0, v5
	v_add_f32_e32 v57, 1.0, v57
	v_add_f32_e32 v17, 1.0, v17
	v_rcp_f32_e32 v5, v5
	v_rcp_f32_e32 v57, v57
	v_rcp_f32_e32 v17, v17
	v_or_b32_e32 v68, v80, v67
	v_mul_f32_e32 v9, v4, v5
	v_pk_mul_f32 v[4:5], v[44:45], v[6:7]
	v_mul_f32_e32 v49, v49, v57
	v_mul_f32_e32 v18, v16, v17
	v_pk_mul_f32 v[16:17], v[54:55], v[38:39]
	v_add_f32_e32 v5, v5, v15
	v_mov_b32_e32 v57, v48
	v_add_f32_e32 v12, v17, v12
	v_add_f32_e32 v6, v4, v5
	v_pk_mul_f32 v[4:5], v[56:57], v[10:11]
	v_add_f32_e32 v12, v16, v12
	v_pk_mul_f32 v[16:17], v[82:83], v[128:129]
	v_add_f32_e32 v5, v5, v6
	v_add_f32_e32 v12, v17, v12
	v_add_f32_e32 v4, v4, v5
	v_add_f32_e32 v12, v16, v12
	v_mul_f32_e32 v5, 0xbfb8aa3b, v4
	v_mul_f32_e32 v16, 0xbfb8aa3b, v12
	v_exp_f32_e32 v5, v5
	v_exp_f32_e32 v16, v16
	v_cvt_pk_bf16_f32 v6, v115, v113
	v_cvt_pk_bf16_f32 v7, v30, v31
	v_add_f32_e32 v5, 1.0, v5
	v_add_f32_e32 v16, 1.0, v16
	v_rcp_f32_e32 v5, v5
	v_rcp_f32_e32 v16, v16
	v_and_b32_e32 v79, 48, v66
	v_lshlrev_b32_e32 v81, 6, v78
	v_mul_f32_e32 v10, v4, v5
	v_cvt_pk_bf16_f32 v4, v125, v121
	v_cvt_pk_bf16_f32 v5, v119, v117
	ds_write_b128 v130, v[4:7]
	v_cvt_pk_bf16_f32 v6, v114, v112
	v_mul_f32_e32 v12, v12, v16
	v_cvt_pk_bf16_f32 v4, v34, v35
	v_cvt_pk_bf16_f32 v5, v41, v109
	v_cvt_pk_bf16_f32 v7, v108, v40
	ds_write_b128 v130, v[4:7] offset:272
	v_cvt_pk_bf16_f32 v6, v65, v59
	v_cvt_pk_bf16_f32 v4, v99, v91
	v_cvt_pk_bf16_f32 v5, v85, v77
	v_cvt_pk_bf16_f32 v7, v53, v49
	ds_write_b128 v130, v[4:7] offset:544
	v_cvt_pk_bf16_f32 v6, v12, v8
	v_add_u32_e32 v77, 0, v79
	v_or_b32_e32 v12, v81, v67
	v_mul_lo_u32 v69, v68, s55
	v_mul_f32_e32 v24, v24, v42
	v_cvt_pk_bf16_f32 v4, v24, v20
	v_cvt_pk_bf16_f32 v5, v21, v18
	v_cvt_pk_bf16_f32 v7, v9, v10
	v_add_u32_e32 v167, v77, v69
	v_mad_u32_u24 v64, v12, s55, v77
	ds_write_b128 v131, v[4:7]
	s_waitcnt lgkmcnt(0)
	s_barrier
	ds_read_b128 v[4:7], v167
	ds_read_b128 v[8:11], v167 offset:4352
	ds_read_b128 v[12:15], v64 offset:34816
	ds_read_b128 v[16:19], v64 offset:39168
	ds_read_b128 v[20:23], v64 offset:43520
	ds_read_b128 v[24:27], v64 offset:47872
	s_waitcnt lgkmcnt(3)
	v_mfma_f32_16x16x32_bf16 v[28:31], v[12:15], v[4:7], 0
	s_waitcnt lgkmcnt(2)
	v_mfma_f32_16x16x32_bf16 v[32:35], v[16:19], v[4:7], 0
	s_waitcnt lgkmcnt(1)
	v_mfma_f32_16x16x32_bf16 v[36:39], v[20:23], v[4:7], 0
	s_waitcnt lgkmcnt(0)
	v_mfma_f32_16x16x32_bf16 v[4:7], v[24:27], v[4:7], 0
	v_mfma_f32_16x16x32_bf16 v[12:15], v[12:15], v[8:11], 0
	v_mfma_f32_16x16x32_bf16 v[16:19], v[16:19], v[8:11], 0
	v_mfma_f32_16x16x32_bf16 v[20:23], v[20:23], v[8:11], 0
	v_mfma_f32_16x16x32_bf16 v[8:11], v[24:27], v[8:11], 0
	ds_read_b128 v[24:27], v167 offset:64
	ds_read_b128 v[40:43], v167 offset:4416
	ds_read_b128 v[44:47], v64 offset:34880
	ds_read_b128 v[48:51], v64 offset:39232
	ds_read_b128 v[52:55], v64 offset:43584
	ds_read_b128 v[56:59], v64 offset:47936
	s_waitcnt lgkmcnt(3)
	v_mfma_f32_16x16x32_bf16 v[28:31], v[44:47], v[24:27], v[28:31]
	s_waitcnt lgkmcnt(2)
	v_mfma_f32_16x16x32_bf16 v[32:35], v[48:51], v[24:27], v[32:35]
	s_waitcnt lgkmcnt(1)
	v_mfma_f32_16x16x32_bf16 v[36:39], v[52:55], v[24:27], v[36:39]
	s_waitcnt lgkmcnt(0)
	v_mfma_f32_16x16x32_bf16 v[4:7], v[56:59], v[24:27], v[4:7]
	v_mfma_f32_16x16x32_bf16 v[12:15], v[44:47], v[40:43], v[12:15]
	v_mfma_f32_16x16x32_bf16 v[16:19], v[48:51], v[40:43], v[16:19]
	v_mfma_f32_16x16x32_bf16 v[20:23], v[52:55], v[40:43], v[20:23]
	v_mfma_f32_16x16x32_bf16 v[8:11], v[56:59], v[40:43], v[8:11]
	ds_read_b128 v[24:27], v167 offset:128
	ds_read_b128 v[40:43], v167 offset:4480
	ds_read_b128 v[44:47], v64 offset:34944
	ds_read_b128 v[48:51], v64 offset:39296
	ds_read_b128 v[52:55], v64 offset:43648
	ds_read_b128 v[56:59], v64 offset:48000
	s_waitcnt lgkmcnt(3)
	v_mfma_f32_16x16x32_bf16 v[28:31], v[44:47], v[24:27], v[28:31]
	s_waitcnt lgkmcnt(2)
	v_mfma_f32_16x16x32_bf16 v[32:35], v[48:51], v[24:27], v[32:35]
	s_waitcnt lgkmcnt(1)
	v_mfma_f32_16x16x32_bf16 v[36:39], v[52:55], v[24:27], v[36:39]
	s_waitcnt lgkmcnt(0)
	v_mfma_f32_16x16x32_bf16 v[24:27], v[56:59], v[24:27], v[4:7]
	v_mfma_f32_16x16x32_bf16 v[44:47], v[44:47], v[40:43], v[12:15]
	v_mfma_f32_16x16x32_bf16 v[48:51], v[48:51], v[40:43], v[16:19]
	v_mfma_f32_16x16x32_bf16 v[52:55], v[52:55], v[40:43], v[20:23]
	v_mfma_f32_16x16x32_bf16 v[40:43], v[56:59], v[40:43], v[8:11]
	s_nop 1
	ds_read_b128 v[18:21], v167 offset:192
	ds_read_b128 v[56:59], v167 offset:4544
	ds_read_b128 v[60:63], v64 offset:35008
	ds_read_b128 v[70:73], v64 offset:39360
	ds_read_b128 v[82:85], v64 offset:43712
	ds_read_b128 v[86:89], v64 offset:48064
	s_waitcnt lgkmcnt(0)
	s_barrier
	v_mfma_f32_16x16x32_bf16 v[6:9], v[60:63], v[18:21], v[28:31]
	v_mfma_f32_16x16x32_bf16 v[10:13], v[70:73], v[18:21], v[32:35]
	v_mfma_f32_16x16x32_bf16 v[14:17], v[82:85], v[18:21], v[36:39]
	v_mfma_f32_16x16x32_bf16 v[18:21], v[86:89], v[18:21], v[24:27]
	v_mfma_f32_16x16x32_bf16 v[22:25], v[60:63], v[56:59], v[44:47]
	v_mfma_f32_16x16x32_bf16 v[26:29], v[70:73], v[56:59], v[48:51]
	v_mfma_f32_16x16x32_bf16 v[30:33], v[82:85], v[56:59], v[52:55]
	v_and_b32_e32 v82, 56, v3
	v_mfma_f32_16x16x32_bf16 v[34:37], v[86:89], v[56:59], v[40:43]
	s_and_saveexec_b64 s[0:1], vcc
	s_xor_b64 s[0:1], exec, s[0:1]
	v_lshrrev_b32_e32 v4, 1, v66
	v_and_b32_e32 v72, 0x3ffffffc, v4
	v_mov_b32_e32 v73, v2
	v_and_b32_e32 v82, 56, v3
	v_lshl_add_u64 v[70:71], s[16:17], 0, v[72:73]
	v_add_u32_e32 v73, s18, v72
	s_or_saveexec_b64 s[0:1], s[0:1]
	s_xor_b64 exec, exec, s[0:1]
	s_cbranch_execz .LBB0_260
	v_ashrrev_i32_e32 v3, 1, v66
	s_lshl_b32 s2, s19, 10
	v_readlane_b32 s4, v242, 63
	v_and_b32_e32 v72, -4, v3
	v_readlane_b32 s5, v241, 0
	s_add_u32 s2, s4, s2
	v_ashrrev_i32_e32 v73, 31, v72
	v_mov_b32_e32 v40, v2
	v_mov_b32_e32 v41, v2
	s_addc_u32 s3, s5, 0
	v_lshlrev_b32_e32 v4, 1, v82
	v_mov_b32_e32 v5, v2
	v_lshl_add_u64 v[70:71], s[16:17], 0, v[72:73]
	v_add_u32_e32 v73, s18, v72
	v_mov_b32_e32 v38, v2
	v_mov_b32_e32 v39, v2
	v_mov_b64_e32 v[44:45], v[40:41]
	v_lshl_add_u64 v[74:75], s[2:3], 0, v[4:5]
	v_cmp_lt_i32_e32 vcc, 2, v73
	v_mov_b64_e32 v[42:43], v[38:39]
	s_and_saveexec_b64 s[2:3], vcc
	s_cbranch_execz .LBB0_247
	v_mad_u64_u32 v[4:5], s[4:5], v70, s68, v[74:75]
	v_mov_b32_e32 v42, v5
	v_mad_u64_u32 v[42:43], s[4:5], v71, s68, v[42:43]
	v_add_co_u32_e32 v4, vcc, 0xffffa000, v4
	s_nop 1
	v_addc_co_u32_e32 v5, vcc, -1, v42, vcc
	global_load_dwordx4 v[42:45], v[4:5], off offset:-3072

.LBB0_530:
	s_ashr_i32 s16, s38, 5
	s_bfe_u32 s20, s38, 0x40001
	s_ashr_i32 s17, s16, 31
	s_and_b32 s4, s38, 1
	s_lshl_b64 s[18:19], s[16:17], 11
	s_lshl_b32 s22, s20, 7
	s_lshl_b64 s[16:17], s[16:17], 8
	s_lshl_b32 s20, s20, 4
	s_or_b32 s39, s16, s20
	s_lshl_b32 s40, s4, 3
	v_mov_b32_e32 v146, v0
	s_or_b32 s16, s39, s40
	s_or_b32 s18, s18, s22
	v_ashrrev_i32_e32 v150, 3, v146
	s_lshl_b64 s[20:21], s[16:17], 15
	v_lshlrev_b32_e32 v2, 4, v146
	s_add_u32 s20, s74, s20
	s_waitcnt vmcnt(5)
	v_lshlrev_b32_e32 v42, 7, v150
	v_and_b32_e32 v149, 0x70, v2
	s_addc_u32 s21, s75, s21
	v_ashrrev_i32_e32 v43, 31, v42
	v_lshl_add_u64 v[2:3], v[42:43], 2, s[20:21]
	v_lshlrev_b32_e32 v74, 2, v149
	v_lshl_add_u64 v[14:15], v[2:3], 0, v[74:75]
	global_load_dwordx4 v[2:5], v[14:15], off offset:48
	global_load_dwordx4 v[6:9], v[14:15], off offset:32
	global_load_dwordx4 v[10:13], v[14:15], off offset:16
	s_nop 0
	global_load_dwordx4 v[14:17], v[14:15], off
	v_lshlrev_b32_e32 v18, 3, v146
	v_ashrrev_i32_e32 v151, 2, v146
	v_and_b32_e32 v152, 0x78, v18
	s_waitcnt vmcnt(8)
	v_and_b32_e32 v46, -4, v151
	v_lshl_or_b32 v18, s4, 7, v152
	v_or_b32_e32 v22, 0x500, v18
	v_ashrrev_i32_e32 v47, 31, v46
	v_add_u32_e32 v23, s22, v46
	v_lshl_add_u64 v[20:21], s[18:19], 0, v[46:47]
	v_cmp_lt_i32_e32 vcc, 2, v23
	v_lshlrev_b32_e32 v18, 1, v22
	v_mov_b32_e32 v49, 0
	v_mov_b32_e32 v57, 0
	v_mov_b32_e32 v67, 0
	v_mov_b32_e32 v77, 0
	v_mov_b32_e32 v89, 0
	v_mov_b32_e32 v97, 0
	v_mov_b32_e32 v103, 0
	v_mov_b32_e32 v111, 0
	s_barrier
	v_mov_b32_e32 v244, 0
	v_mov_b32_e32 v245, 0
	v_mov_b32_e32 v246, 0
	v_mov_b32_e32 v247, 0
	s_and_saveexec_b64 s[22:23], vcc
	s_cbranch_execz .LBB0_532
	v_mov_b64_e32 v[24:25], s[2:3]
	v_mad_u64_u32 v[24:25], s[42:43], v20, s28, v[24:25]
	v_mov_b32_e32 v26, v25
	v_mad_u64_u32 v[26:27], s[42:43], v21, s28, v[26:27]
	v_mov_b32_e32 v25, v26
	v_mov_b32_e32 v19, v75
	v_lshl_add_u64 v[24:25], v[24:25], 0, v[18:19]
	v_add_co_u32_e32 v24, vcc, 0xffffa000, v24
	s_nop 1
	v_addc_co_u32_e32 v25, vcc, -1, v25, vcc
	global_load_dwordx4 v[244:247], v[24:25], off offset:-3072
.LBB0_532:
	s_or_b64 exec, exec, s[22:23]
	v_cmp_lt_i32_e32 vcc, 1, v23
	v_mov_b32_e32 v69, 0
	v_mov_b32_e32 v48, 0
	v_mov_b32_e32 v56, 0
	v_mov_b32_e32 v66, 0
	v_mov_b32_e32 v76, 0
	v_mov_b32_e32 v88, 0
	v_mov_b32_e32 v96, 0
	v_mov_b32_e32 v102, 0
	v_mov_b32_e32 v110, 0
	v_mov_b32_e32 v248, 0
	v_mov_b32_e32 v249, 0
	v_mov_b32_e32 v250, 0
	v_mov_b32_e32 v251, 0
	s_and_saveexec_b64 s[22:23], vcc
	s_cbranch_execz .LBB0_534
	v_mov_b64_e32 v[24:25], s[2:3]
	v_mad_u64_u32 v[24:25], s[42:43], v20, s28, v[24:25]
	v_mov_b32_e32 v26, v25
	v_mad_u64_u32 v[26:27], s[42:43], v21, s28, v[26:27]
	v_mov_b32_e32 v25, v26
	v_mov_b32_e32 v19, v75
	v_lshl_add_u64 v[24:25], v[24:25], 0, v[18:19]
	v_add_co_u32_e32 v24, vcc, 0xffffc000, v24
	s_nop 1
	v_addc_co_u32_e32 v25, vcc, -1, v25, vcc
	global_load_dwordx4 v[248:251], v[24:25], off offset:-2048
.LBB0_534:
	s_or_b64 exec, exec, s[22:23]
	v_cmp_lt_i32_e32 vcc, 0, v23
	v_mov_b32_e32 v95, 0
	v_mov_b32_e32 v87, 0
	v_mov_b32_e32 v81, 0
	v_mov_b32_e32 v71, 0
	s_waitcnt vmcnt(4)
	v_mov_b32_e32 v61, 0
	v_mov_b32_e32 v55, 0
	v_mov_b32_e32 v51, 0
	v_mov_b32_e32 v252, 0
	v_mov_b32_e32 v253, 0
	v_mov_b32_e32 v254, 0
	v_mov_b32_e32 v255, 0
	s_and_saveexec_b64 s[22:23], vcc
	s_cbranch_execz .LBB0_536
	v_mov_b64_e32 v[24:25], s[2:3]
	v_mad_u64_u32 v[24:25], s[42:43], v20, s28, v[24:25]
	v_mov_b32_e32 v26, v25
	v_mad_u64_u32 v[26:27], s[42:43], v21, s28, v[26:27]
	v_mov_b32_e32 v25, v26
	v_mov_b32_e32 v19, v75
	v_lshl_add_u64 v[24:25], v[24:25], 0, v[18:19]
	v_add_co_u32_e32 v24, vcc, 0xffffe000, v24
	s_nop 1
	v_addc_co_u32_e32 v25, vcc, -1, v25, vcc
	global_load_dwordx4 v[252:255], v[24:25], off offset:-1024
.LBB0_536:
	s_or_b64 exec, exec, s[22:23]
	s_waitcnt vmcnt(0)
	v_lshlrev_b32_e32 v111, 16, v244
	v_and_b32_e32 v103, 0xffff0000, v244
	v_lshlrev_b32_e32 v97, 16, v245
	v_and_b32_e32 v89, 0xffff0000, v245
	v_lshlrev_b32_e32 v77, 16, v246
	v_and_b32_e32 v67, 0xffff0000, v246
	v_lshlrev_b32_e32 v57, 16, v247
	v_and_b32_e32 v49, 0xffff0000, v247
	v_lshlrev_b32_e32 v110, 16, v248
	v_and_b32_e32 v102, 0xffff0000, v248
	v_lshlrev_b32_e32 v96, 16, v249
	v_and_b32_e32 v88, 0xffff0000, v249
	v_lshlrev_b32_e32 v76, 16, v250
	v_and_b32_e32 v66, 0xffff0000, v250
	v_lshlrev_b32_e32 v56, 16, v251
	v_and_b32_e32 v48, 0xffff0000, v251
	v_lshlrev_b32_e32 v69, 16, v252
	v_and_b32_e32 v95, 0xffff0000, v252
	v_lshlrev_b32_e32 v87, 16, v253
	v_and_b32_e32 v81, 0xffff0000, v253
	v_lshlrev_b32_e32 v71, 16, v254
	v_and_b32_e32 v61, 0xffff0000, v254
	v_lshlrev_b32_e32 v55, 16, v255
	v_and_b32_e32 v51, 0xffff0000, v255
	v_cmp_lt_i32_e32 vcc, -1, v23
	v_mov_b32_e32 v62, 0
	v_mov_b32_e32 v68, 0
	v_mov_b32_e32 v94, 0
	v_mov_b32_e32 v86, 0
	v_mov_b32_e32 v80, 0
	v_mov_b32_e32 v70, 0
	v_mov_b32_e32 v60, 0
	v_mov_b32_e32 v54, 0
	v_mov_b32_e32 v50, 0
	v_mov_b32_e32 v244, 0
	v_mov_b32_e32 v245, 0
	v_mov_b32_e32 v246, 0
	v_mov_b32_e32 v247, 0
	s_and_saveexec_b64 s[22:23], vcc
	s_cbranch_execz .LBB0_538
	v_mov_b64_e32 v[24:25], s[2:3]
	v_mad_u64_u32 v[24:25], s[42:43], v20, s28, v[24:25]
	v_mov_b32_e32 v26, v25
	v_mad_u64_u32 v[26:27], s[42:43], v21, s28, v[26:27]
	v_mov_b32_e32 v25, v26
	v_mov_b32_e32 v19, v75
	v_lshl_add_u64 v[24:25], v[24:25], 0, v[18:19]
	global_load_dwordx4 v[244:247], v[24:25], off
.LBB0_538:
	s_or_b64 exec, exec, s[22:23]
	v_cmp_lt_i32_e32 vcc, -2, v23
	v_mov_b32_e32 v90, 0
	v_mov_b32_e32 v82, 0
	v_mov_b32_e32 v72, 0
	v_mov_b32_e32 v64, 0
	v_mov_b32_e32 v58, 0
	v_mov_b32_e32 v52, 0
	v_mov_b32_e32 v44, 0
	v_mov_b32_e32 v248, 0
	v_mov_b32_e32 v249, 0
	v_mov_b32_e32 v250, 0
	v_mov_b32_e32 v251, 0
	s_and_saveexec_b64 s[22:23], vcc
	s_cbranch_execz .LBB0_540
	v_mov_b64_e32 v[24:25], s[2:3]
	v_mad_u64_u32 v[24:25], s[42:43], v20, s28, v[24:25]
	v_mov_b32_e32 v26, v25
	v_mad_u64_u32 v[26:27], s[42:43], v21, s28, v[26:27]
	v_mov_b32_e32 v25, v26
	v_mov_b32_e32 v19, v75
	v_lshl_add_u64 v[24:25], v[24:25], 0, v[18:19]
	v_add_co_u32_e32 v24, vcc, 0x2000, v24
	s_nop 1
	v_addc_co_u32_e32 v25, vcc, 0, v25, vcc
	global_load_dwordx4 v[248:251], v[24:25], off offset:1024
.LBB0_540:
	s_or_b64 exec, exec, s[22:23]
	v_cmp_lt_i32_e32 vcc, -3, v23
	v_mov_b32_e32 v116, 0
	v_mov_b32_e32 v118, 0
	v_mov_b32_e32 v112, 0
	v_mov_b32_e32 v106, 0
	v_mov_b32_e32 v100, 0
	v_mov_b32_e32 v98, 0
	v_mov_b32_e32 v92, 0
	v_mov_b32_e32 v84, 0
	v_mov_b32_e32 v78, 0
	v_mov_b32_e32 v252, 0
	v_mov_b32_e32 v253, 0
	v_mov_b32_e32 v254, 0
	v_mov_b32_e32 v255, 0
	s_and_saveexec_b64 s[22:23], vcc
	s_cbranch_execz .LBB0_542
	v_mov_b64_e32 v[24:25], s[2:3]
	v_mad_u64_u32 v[24:25], s[42:43], v20, s28, v[24:25]
	v_mov_b32_e32 v26, v25
	v_mad_u64_u32 v[26:27], s[42:43], v21, s28, v[26:27]
	v_mov_b32_e32 v25, v26
	v_mov_b32_e32 v19, v75
	v_lshl_add_u64 v[24:25], v[24:25], 0, v[18:19]
	v_add_co_u32_e32 v24, vcc, 0x4000, v24
	s_nop 1
	v_addc_co_u32_e32 v25, vcc, 0, v25, vcc
	global_load_dwordx4 v[252:255], v[24:25], off offset:2048
.LBB0_542:
	s_or_b64 exec, exec, s[22:23]
	s_waitcnt vmcnt(0)
	v_lshlrev_b32_e32 v68, 16, v244
	v_and_b32_e32 v94, 0xffff0000, v244
	v_lshlrev_b32_e32 v86, 16, v245
	v_and_b32_e32 v80, 0xffff0000, v245
	v_lshlrev_b32_e32 v70, 16, v246
	v_and_b32_e32 v60, 0xffff0000, v246
	v_lshlrev_b32_e32 v54, 16, v247
	v_and_b32_e32 v50, 0xffff0000, v247
	v_lshlrev_b32_e32 v62, 16, v248
	v_and_b32_e32 v90, 0xffff0000, v248
	v_lshlrev_b32_e32 v82, 16, v249
	v_and_b32_e32 v72, 0xffff0000, v249
	v_lshlrev_b32_e32 v64, 16, v250
	v_and_b32_e32 v58, 0xffff0000, v250
	v_lshlrev_b32_e32 v52, 16, v251
	v_and_b32_e32 v44, 0xffff0000, v251
	v_lshlrev_b32_e32 v118, 16, v252
	v_and_b32_e32 v112, 0xffff0000, v252
	v_lshlrev_b32_e32 v106, 16, v253
	v_and_b32_e32 v100, 0xffff0000, v253
	v_lshlrev_b32_e32 v98, 16, v254
	v_and_b32_e32 v92, 0xffff0000, v254
	v_lshlrev_b32_e32 v84, 16, v255
	v_and_b32_e32 v78, 0xffff0000, v255
	v_cmp_lt_i32_e32 vcc, -4, v23
	v_mov_b32_e32 v126, 0
	v_mov_b32_e32 v124, 0
	v_mov_b32_e32 v122, 0
	v_mov_b32_e32 v120, 0
	v_mov_b32_e32 v114, 0
	v_mov_b32_e32 v108, 0
	v_mov_b32_e32 v104, 0
	v_mov_b32_e32 v244, 0
	v_mov_b32_e32 v245, 0
	v_mov_b32_e32 v246, 0
	v_mov_b32_e32 v247, 0
	s_and_saveexec_b64 s[22:23], vcc
	s_cbranch_execz .LBB0_544
	v_mov_b64_e32 v[24:25], s[2:3]
	v_mad_u64_u32 v[24:25], s[42:43], v20, s28, v[24:25]
	v_mov_b32_e32 v20, v25
	v_mad_u64_u32 v[20:21], s[42:43], v21, s28, v[20:21]
	v_mov_b32_e32 v25, v20
	v_mov_b32_e32 v19, v75
	v_lshl_add_u64 v[18:19], v[24:25], 0, v[18:19]
	v_add_co_u32_e32 v18, vcc, 0x6000, v18
	s_nop 1
	v_addc_co_u32_e32 v19, vcc, 0, v19, vcc
	global_load_dwordx4 v[244:247], v[18:19], off offset:3072
.LBB0_544:
	s_or_b64 exec, exec, s[22:23]
	s_waitcnt vmcnt(0)
	v_lshlrev_b32_e32 v116, 16, v244
	v_and_b32_e32 v126, 0xffff0000, v244
	v_lshlrev_b32_e32 v124, 16, v245
	v_and_b32_e32 v122, 0xffff0000, v245
	v_lshlrev_b32_e32 v120, 16, v246
	v_and_b32_e32 v114, 0xffff0000, v246
	v_lshlrev_b32_e32 v108, 16, v247
	v_and_b32_e32 v104, 0xffff0000, v247
	v_readlane_b32 s80, v242, 2
	v_readlane_b32 s84, v242, 6
	v_readlane_b32 s85, v242, 7
	v_lshlrev_b32_e32 v26, 2, v22
	v_mov_b32_e32 v27, v75
	v_readlane_b32 s86, v242, 8
	v_readlane_b32 s87, v242, 9
	s_mov_b64 s[44:45], s[84:85]
	v_lshl_add_u64 v[22:23], s[44:45], 0, v[26:27]
	v_add_co_u32_e32 v24, vcc, s30, v22
	global_load_dwordx4 v[18:21], v26, s[44:45] offset:16
	global_load_dwordx4 v[30:33], v26, s[44:45]
	v_addc_co_u32_e32 v25, vcc, 0, v23, vcc
	global_load_dwordx4 v[140:143], v[24:25], off offset:2048
	v_add_co_u32_e32 v24, vcc, s31, v22
	s_mov_b64 s[46:47], s[86:87]
	s_nop 0
	v_addc_co_u32_e32 v25, vcc, 0, v23, vcc
	v_add_co_u32_e32 v28, vcc, s29, v22
	v_mov_b32_e32 v91, v94
	s_nop 0
	v_addc_co_u32_e32 v29, vcc, 0, v23, vcc
	global_load_dwordx4 v[154:157], v[28:29], off offset:2048
	global_load_dwordx4 v[34:37], v[24:25], off
	v_lshl_add_u64 v[24:25], v[22:23], 0, s[8:9]
	global_load_dwordx4 v[158:161], v[24:25], off offset:16
	v_lshl_add_u64 v[24:25], v[22:23], 0, s[10:11]
	v_lshl_add_u64 v[22:23], v[22:23], 0, s[12:13]
	global_load_dwordx4 v[162:165], v[22:23], off offset:16
	s_nop 0
	global_load_dwordx4 v[22:25], v[24:25], off offset:16
	s_nop 0
	global_load_dwordx4 v[38:41], v26, s[46:47]
	s_nop 0
	global_load_dwordx4 v[26:29], v26, s[46:47] offset:16
	v_mov_b32_e32 v83, v86
	v_mov_b32_e32 v119, v62
	v_mov_b32_e32 v113, v90
	v_mov_b32_e32 v107, v82
	v_mov_b32_e32 v101, v72
	v_mov_b32_e32 v99, v64
	v_mov_b32_e32 v93, v58
	v_mov_b32_e32 v127, v112
	v_mov_b32_e32 v117, v118
	v_mov_b32_e32 v125, v106
	v_mov_b32_e32 v123, v100
	v_mov_b32_e32 v121, v98
	v_mov_b32_e32 v115, v92
	v_mov_b32_e32 v109, v84
	v_mov_b32_e32 v105, v78
	v_and_b32_e32 v147, 15, v146
	v_bfe_u32 v148, v146, 4, 2
	s_waitcnt vmcnt(12)
	v_cvt_pk_bf16_f32 v6, v6, v7
	v_cvt_pk_bf16_f32 v7, v8, v9
	v_cvt_pk_bf16_f32 v8, v2, v3
	v_lshlrev_b32_e32 v2, 1, v149
	s_waitcnt vmcnt(10)
	v_cvt_pk_bf16_f32 v14, v14, v15
	v_cvt_pk_bf16_f32 v15, v16, v17
	v_cvt_pk_bf16_f32 v16, v10, v11
	v_cvt_pk_bf16_f32 v17, v12, v13
	v_cvt_pk_bf16_f32 v9, v4, v5
	v_readlane_b32 s81, v242, 3
	v_readlane_b32 s82, v242, 4
	v_readlane_b32 s83, v242, 5
	v_readlane_b32 s88, v242, 10
	v_readlane_b32 s89, v242, 11
	v_readlane_b32 s90, v242, 12
	v_readlane_b32 s91, v242, 13
	v_readlane_b32 s92, v242, 14
	v_readlane_b32 s93, v242, 15
	v_readlane_b32 s94, v242, 16
	v_readlane_b32 s95, v242, 17
	s_waitcnt vmcnt(9)
	v_mov_b32_e32 v133, v18
	s_waitcnt vmcnt(8)
	v_mov_b32_e32 v129, v30
	v_mov_b32_e32 v131, v32
	s_waitcnt vmcnt(7)
	v_mov_b32_e32 v128, v140
	v_mov_b32_e32 v30, v141
	v_mov_b32_e32 v130, v142
	v_pk_mul_f32 v[140:141], v[110:111], v[128:129]
	v_mov_b32_e32 v32, v143
	v_pk_mul_f32 v[168:169], v[88:89], v[32:33]
	s_waitcnt vmcnt(6)
	v_mov_b32_e32 v138, v154
	s_waitcnt vmcnt(5)
	v_mov_b32_e32 v139, v34
	v_mov_b32_e32 v34, v155
	s_waitcnt vmcnt(4)
	v_mov_b32_e32 v132, v158
	s_waitcnt vmcnt(2)
	v_mov_b32_e32 v135, v22
	v_mov_b32_e32 v18, v159
	v_pk_mul_f32 v[158:159], v[96:97], v[130:131]
	s_waitcnt vmcnt(1)
	v_add_f32_e32 v22, v141, v38
	v_mov_b32_e32 v136, v156
	v_mov_b32_e32 v137, v36
	v_pk_mul_f32 v[142:143], v[68:69], v[138:139]
	v_pk_mul_f32 v[154:155], v[102:103], v[30:31]
	v_add_f32_e32 v47, v159, v40
	v_add_f32_e32 v22, v140, v22
	v_pk_mul_f32 v[166:167], v[86:87], v[136:137]
	v_add_f32_e32 v45, v155, v39
	v_add_f32_e32 v47, v158, v47
	v_add_f32_e32 v22, v143, v22
	v_mov_b32_e32 v36, v157
	v_pk_mul_f32 v[156:157], v[94:95], v[34:35]
	v_add_f32_e32 v45, v154, v45
	v_add_f32_e32 v47, v167, v47
	v_add_f32_e32 v22, v142, v22
	v_add_f32_e32 v45, v157, v45
	v_add_f32_e32 v65, v166, v47
	v_mul_f32_e32 v47, 0xbfb8aa3b, v22
	v_add_f32_e32 v45, v156, v45
	v_exp_f32_e32 v47, v47
	v_pk_mul_f32 v[176:177], v[66:67], v[18:19]
	v_mul_f32_e32 v67, 0xbfb8aa3b, v45
	v_exp_f32_e32 v67, v67
	v_add_f32_e32 v47, 1.0, v47
	v_rcp_f32_e32 v47, v47
	s_waitcnt vmcnt(0)
	v_add_f32_e32 v63, v177, v27
	v_add_f32_e32 v67, 1.0, v67
	v_rcp_f32_e32 v67, v67
	v_mul_f32_e32 v47, v22, v47
	v_mov_b32_e32 v22, v163
	v_add_f32_e32 v63, v176, v63
	v_pk_mul_f32 v[140:141], v[60:61], v[22:23]
	v_mul_f32_e32 v67, v45, v67
	v_add_f32_e32 v45, v141, v63
	v_add_f32_e32 v45, v140, v45
	v_mov_b32_e32 v140, v160
	v_mov_b32_e32 v141, v20
	v_pk_mul_f32 v[142:143], v[56:57], v[140:141]
	v_mul_f32_e32 v63, 0xbfb8aa3b, v45
	v_add_f32_e32 v20, v143, v28
	v_exp_f32_e32 v63, v63
	v_add_f32_e32 v20, v142, v20
	v_mov_b32_e32 v142, v164
	v_mov_b32_e32 v143, v24
	v_pk_mul_f32 v[154:155], v[54:55], v[142:143]
	v_pk_mul_f32 v[172:173], v[76:77], v[132:133]
	v_mul_f32_e32 v73, 0xbfb8aa3b, v65
	v_add_f32_e32 v20, v155, v20
	v_mov_b32_e32 v134, v162
	v_add_f32_e32 v53, v169, v41
	v_add_f32_e32 v59, v173, v26
	v_exp_f32_e32 v73, v73
	v_add_f32_e32 v57, v154, v20
	v_pk_mul_f32 v[170:171], v[80:81], v[36:37]
	v_pk_mul_f32 v[174:175], v[70:71], v[134:135]
	v_add_f32_e32 v53, v168, v53
	v_add_f32_e32 v59, v172, v59
	v_add_f32_e32 v63, 1.0, v63
	v_mul_f32_e32 v20, 0xbfb8aa3b, v57
	v_add_f32_e32 v53, v171, v53
	v_add_f32_e32 v59, v175, v59
	v_rcp_f32_e32 v63, v63
	v_exp_f32_e32 v20, v20
	v_add_f32_e32 v53, v170, v53
	v_add_f32_e32 v59, v174, v59
	v_mul_f32_e32 v77, 0xbfb8aa3b, v53
	v_mul_f32_e32 v79, 0xbfb8aa3b, v59
	v_add_f32_e32 v73, 1.0, v73
	v_exp_f32_e32 v77, v77
	v_exp_f32_e32 v79, v79
	v_rcp_f32_e32 v73, v73
	v_mul_f32_e32 v155, v45, v63
	v_add_f32_e32 v45, 1.0, v20
	v_mov_b32_e32 v20, v161
	v_pk_mul_f32 v[156:157], v[48:49], v[20:21]
	v_add_f32_e32 v77, 1.0, v77
	v_add_f32_e32 v24, v157, v29
	v_mul_f32_e32 v103, v65, v73
	v_add_f32_e32 v73, 1.0, v79
	v_add_f32_e32 v49, v156, v24
	v_mov_b32_e32 v24, v165
	v_rcp_f32_e32 v65, v77
	v_rcp_f32_e32 v73, v73
	v_pk_mul_f32 v[156:157], v[50:51], v[24:25]
	v_mov_b32_e32 v63, v68
	v_add_f32_e32 v49, v157, v49
	v_add_f32_e32 v49, v156, v49
	v_mov_b32_e32 v156, v69
	v_mov_b32_e32 v157, v110
	v_pk_mul_f32 v[110:111], v[156:157], v[128:129]
	v_mul_f32_e32 v153, v53, v65
	v_mul_f32_e32 v154, v59, v73
	v_mul_f32_e32 v53, 0xbfb8aa3b, v49
	v_add_f32_e32 v59, v111, v38
	v_exp_f32_e32 v53, v53
	v_add_f32_e32 v59, v110, v59
	v_pk_mul_f32 v[110:111], v[62:63], v[138:139]
	v_rcp_f32_e32 v45, v45
	v_add_f32_e32 v59, v111, v59
	v_add_f32_e32 v59, v110, v59
	v_mov_b32_e32 v110, v95
	v_mov_b32_e32 v111, v102
	v_pk_mul_f32 v[110:111], v[110:111], v[30:31]
	v_mul_f32_e32 v65, 0xbfb8aa3b, v59
	v_add_f32_e32 v53, 1.0, v53
	v_add_f32_e32 v73, v111, v39
	v_exp_f32_e32 v65, v65
	v_rcp_f32_e32 v53, v53
	v_add_f32_e32 v73, v110, v73
	v_pk_mul_f32 v[110:111], v[90:91], v[34:35]
	v_add_f32_e32 v65, 1.0, v65
	v_add_f32_e32 v73, v111, v73
	v_add_f32_e32 v79, v110, v73
	v_mov_b32_e32 v110, v87
	v_mov_b32_e32 v111, v96
	v_pk_mul_f32 v[96:97], v[110:111], v[130:131]
	v_mul_f32_e32 v73, 0xbfb8aa3b, v79
	v_mul_f32_e32 v156, v49, v53
	v_add_f32_e32 v53, v97, v40
	v_rcp_f32_e32 v65, v65
	v_exp_f32_e32 v73, v73
	v_add_f32_e32 v53, v96, v53
	v_pk_mul_f32 v[96:97], v[82:83], v[136:137]
	v_mul_f32_e32 v102, v57, v45
	v_add_f32_e32 v53, v97, v53
	v_add_f32_e32 v53, v96, v53
	v_mov_b32_e32 v96, v81
	v_mov_b32_e32 v97, v88
	v_pk_mul_f32 v[88:89], v[96:97], v[32:33]
	v_mul_f32_e32 v49, v59, v65
	v_add_f32_e32 v45, 1.0, v73
	v_add_f32_e32 v59, v89, v41
	v_mov_b32_e32 v73, v80
	v_add_f32_e32 v59, v88, v59
	v_pk_mul_f32 v[88:89], v[72:73], v[36:37]
	v_mul_f32_e32 v57, 0xbfb8aa3b, v53
	v_add_f32_e32 v59, v89, v59
	v_add_f32_e32 v59, v88, v59
	v_mul_f32_e32 v65, 0xbfb8aa3b, v59
	v_exp_f32_e32 v65, v65
	v_mov_b32_e32 v88, v71
	v_mov_b32_e32 v89, v76
	v_pk_mul_f32 v[76:77], v[88:89], v[132:133]
	v_add_f32_e32 v65, 1.0, v65
	v_rcp_f32_e32 v85, v65
	v_add_f32_e32 v65, v77, v26
	v_add_f32_e32 v88, v76, v65
	v_mov_b32_e32 v65, v70
	v_pk_mul_f32 v[76:77], v[64:65], v[134:135]
	v_exp_f32_e32 v57, v57
	v_add_f32_e32 v77, v77, v88
	v_add_f32_e32 v88, v76, v77
	v_mul_f32_e32 v76, 0xbfb8aa3b, v88
	v_rcp_f32_e32 v45, v45
	v_exp_f32_e32 v76, v76
	v_add_f32_e32 v57, 1.0, v57
	v_rcp_f32_e32 v57, v57
	v_mul_f32_e32 v157, v79, v45
	v_add_f32_e32 v45, 1.0, v76
	v_mov_b32_e32 v76, v61
	v_mov_b32_e32 v77, v66
	v_pk_mul_f32 v[76:77], v[76:77], v[18:19]
	v_mul_f32_e32 v158, v53, v57
	v_mul_f32_e32 v159, v59, v85
	v_add_f32_e32 v53, v77, v27
	v_mov_b32_e32 v59, v60
	v_add_f32_e32 v53, v76, v53
	v_pk_mul_f32 v[76:77], v[58:59], v[22:23]
	v_lshlrev_b32_e32 v110, 2, v148
	v_add_f32_e32 v53, v77, v53
	v_add_f32_e32 v66, v76, v53
	v_mov_b32_e32 v76, v55
	v_mov_b32_e32 v77, v56
	v_mul_f32_e32 v53, 0xbfb8aa3b, v66
	v_pk_mul_f32 v[56:57], v[76:77], v[140:141]
	v_exp_f32_e32 v79, v53
	v_add_f32_e32 v53, v57, v28
	v_add_f32_e32 v76, v56, v53
	v_mov_b32_e32 v53, v54
	v_pk_mul_f32 v[56:57], v[52:53], v[142:143]
	v_rcp_f32_e32 v77, v45
	v_add_f32_e32 v57, v57, v76
	v_add_f32_e32 v76, v56, v57
	v_mul_f32_e32 v56, 0xbfb8aa3b, v76
	v_exp_f32_e32 v56, v56
	v_add_f32_e32 v45, 1.0, v79
	v_rcp_f32_e32 v79, v45
	v_mov_b32_e32 v57, v48
	v_add_f32_e32 v45, 1.0, v56
	v_mov_b32_e32 v56, v51
	v_pk_mul_f32 v[56:57], v[56:57], v[20:21]
	v_rcp_f32_e32 v85, v45
	v_add_f32_e32 v45, v57, v29
	v_add_f32_e32 v48, v56, v45
	v_mov_b32_e32 v45, v50
	v_pk_mul_f32 v[56:57], v[44:45], v[24:25]
	v_mul_f32_e32 v161, v76, v85
	v_add_f32_e32 v48, v57, v48
	v_add_f32_e32 v48, v56, v48
	v_mul_f32_e32 v56, 0xbfb8aa3b, v48
	v_exp_f32_e32 v56, v56
	v_mul_f32_e32 v160, v88, v77
	v_mul_f32_e32 v66, v66, v79
	v_pk_mul_f32 v[54:55], v[54:55], v[140:141]
	v_add_f32_e32 v76, 1.0, v56
	v_pk_mul_f32 v[56:57], v[68:69], v[128:129]
	v_rcp_f32_e32 v76, v76
	v_add_f32_e32 v57, v57, v38
	v_add_f32_e32 v68, v56, v57
	v_pk_mul_f32 v[56:57], v[118:119], v[138:139]
	v_mul_f32_e32 v48, v48, v76
	v_add_f32_e32 v57, v57, v68
	v_add_f32_e32 v68, v56, v57
	v_mul_f32_e32 v56, 0xbfb8aa3b, v68
	v_exp_f32_e32 v69, v56
	v_pk_mul_f32 v[56:57], v[94:95], v[30:31]
	v_add_f32_e32 v55, v55, v28
	v_add_f32_e32 v57, v57, v39
	v_add_f32_e32 v77, v56, v57
	v_pk_mul_f32 v[56:57], v[112:113], v[34:35]
	v_pk_mul_f32 v[50:51], v[50:51], v[20:21]
	v_add_f32_e32 v57, v57, v77
	v_add_f32_e32 v77, v56, v57
	v_mul_f32_e32 v56, 0xbfb8aa3b, v77
	v_exp_f32_e32 v56, v56
	v_add_f32_e32 v57, 1.0, v69
	v_rcp_f32_e32 v69, v57
	v_add_f32_e32 v51, v51, v29
	v_add_f32_e32 v56, 1.0, v56
	v_rcp_f32_e32 v79, v56
	v_pk_mul_f32 v[56:57], v[86:87], v[130:131]
	v_mul_f32_e32 v68, v68, v69
	v_add_f32_e32 v57, v57, v40
	v_add_f32_e32 v85, v56, v57
	v_pk_mul_f32 v[56:57], v[106:107], v[136:137]
	v_mul_f32_e32 v69, v77, v79
	v_add_f32_e32 v57, v57, v85
	v_add_f32_e32 v85, v56, v57
	v_mul_f32_e32 v56, 0xbfb8aa3b, v85
	v_exp_f32_e32 v56, v56
	v_pk_mul_f32 v[30:31], v[90:91], v[30:31]
	v_bfe_u32 v112, v146, 6, 1
	v_add_f32_e32 v31, v31, v39
	v_add_f32_e32 v76, 1.0, v56
	v_pk_mul_f32 v[56:57], v[80:81], v[32:33]
	v_add_f32_e32 v39, v30, v31
	v_add_f32_e32 v57, v57, v41
	v_add_f32_e32 v77, v56, v57
	v_pk_mul_f32 v[56:57], v[100:101], v[36:37]
	v_pk_mul_f32 v[30:31], v[126:127], v[34:35]
	v_add_f32_e32 v57, v57, v77
	v_add_f32_e32 v77, v56, v57
	v_mul_f32_e32 v56, 0xbfb8aa3b, v77
	v_exp_f32_e32 v79, v56
	v_pk_mul_f32 v[56:57], v[70:71], v[132:133]
	v_rcp_f32_e32 v71, v76
	v_add_f32_e32 v57, v57, v26
	v_add_f32_e32 v70, v56, v57
	v_pk_mul_f32 v[56:57], v[98:99], v[134:135]
	v_add_f32_e32 v31, v31, v39
	v_add_f32_e32 v57, v57, v70
	v_add_f32_e32 v70, v56, v57
	v_mul_f32_e32 v56, 0xbfb8aa3b, v70
	v_exp_f32_e32 v56, v56
	v_add_f32_e32 v57, 1.0, v79
	v_rcp_f32_e32 v76, v57
	v_add_f32_e32 v34, v30, v31
	v_add_f32_e32 v56, 1.0, v56
	v_rcp_f32_e32 v79, v56
	v_pk_mul_f32 v[56:57], v[60:61], v[18:19]
	v_mul_f32_e32 v30, 0xbfb8aa3b, v34
	v_add_f32_e32 v57, v57, v27
	v_add_f32_e32 v60, v56, v57
	v_pk_mul_f32 v[56:57], v[92:93], v[22:23]
	v_mul_f32_e32 v70, v70, v79
	v_add_f32_e32 v57, v57, v60
	v_mul_f32_e32 v60, v85, v71
	v_mov_b32_e32 v85, v52
	v_add_f32_e32 v71, v54, v55
	v_pk_mul_f32 v[54:55], v[84:85], v[142:143]
	v_mov_b32_e32 v79, v44
	v_add_f32_e32 v55, v55, v71
	v_add_f32_e32 v71, v50, v51
	v_pk_mul_f32 v[50:51], v[78:79], v[24:25]
	v_add_f32_e32 v54, v54, v55
	v_add_f32_e32 v51, v51, v71
	v_add_f32_e32 v71, v50, v51
	v_mul_f32_e32 v55, 0xbfb8aa3b, v54
	v_mul_f32_e32 v50, 0xbfb8aa3b, v71
	v_exp_f32_e32 v55, v55
	v_exp_f32_e32 v50, v50
	v_mul_f32_e32 v61, v77, v76
	v_exp_f32_e32 v35, v30
	v_add_f32_e32 v51, 1.0, v55
	v_add_f32_e32 v50, 1.0, v50
	v_rcp_f32_e32 v55, v51
	v_rcp_f32_e32 v76, v50
	v_pk_mul_f32 v[50:51], v[62:63], v[128:129]
	v_pk_mul_f32 v[30:31], v[82:83], v[130:131]
	v_add_f32_e32 v38, v51, v38
	v_add_f32_e32 v31, v31, v40
	v_add_f32_e32 v38, v50, v38
	v_pk_mul_f32 v[50:51], v[116:117], v[138:139]
	v_add_f32_e32 v39, v30, v31
	v_pk_mul_f32 v[30:31], v[124:125], v[136:137]
	v_add_f32_e32 v38, v51, v38
	v_add_f32_e32 v31, v31, v39
	v_add_f32_e32 v38, v50, v38
	v_add_f32_e32 v39, v30, v31
	v_mul_f32_e32 v50, 0xbfb8aa3b, v38
	v_mul_f32_e32 v30, 0xbfb8aa3b, v39
	v_exp_f32_e32 v50, v50
	v_exp_f32_e32 v30, v30
	v_add_f32_e32 v31, 1.0, v35
	v_rcp_f32_e32 v35, v31
	v_add_f32_e32 v50, 1.0, v50
	v_add_f32_e32 v30, 1.0, v30
	v_rcp_f32_e32 v40, v50
	v_rcp_f32_e32 v50, v30
	v_pk_mul_f32 v[30:31], v[72:73], v[32:33]
	v_mul_f32_e32 v63, v71, v76
	v_add_f32_e32 v31, v31, v41
	v_add_f32_e32 v32, v30, v31
	v_pk_mul_f32 v[30:31], v[122:123], v[36:37]
	v_mul_f32_e32 v71, v34, v35
	v_add_f32_e32 v31, v31, v32
	v_add_f32_e32 v32, v30, v31
	v_mul_f32_e32 v30, 0xbfb8aa3b, v32
	v_exp_f32_e32 v30, v30
	v_pk_mul_f32 v[18:19], v[58:59], v[18:19]
	v_add_f32_e32 v56, v56, v57
	v_add_f32_e32 v19, v19, v27
	v_add_f32_e32 v30, 1.0, v30
	v_rcp_f32_e32 v34, v30
	v_pk_mul_f32 v[30:31], v[64:65], v[132:133]
	v_add_f32_e32 v27, v18, v19
	v_add_f32_e32 v26, v31, v26
	v_add_f32_e32 v26, v30, v26
	v_pk_mul_f32 v[30:31], v[120:121], v[134:135]
	v_pk_mul_f32 v[18:19], v[114:115], v[22:23]
	v_add_f32_e32 v26, v31, v26
	v_add_f32_e32 v26, v30, v26
	v_add_f32_e32 v19, v19, v27
	v_mul_f32_e32 v30, 0xbfb8aa3b, v26
	v_add_f32_e32 v27, v18, v19
	v_exp_f32_e32 v30, v30
	v_mul_f32_e32 v18, 0xbfb8aa3b, v27
	v_exp_f32_e32 v18, v18
	v_mul_f32_e32 v31, v32, v34
	v_add_f32_e32 v19, 1.0, v30
	v_rcp_f32_e32 v30, v19
	v_add_f32_e32 v32, 1.0, v18
	v_pk_mul_f32 v[18:19], v[52:53], v[140:141]
	v_mul_f32_e32 v57, 0xbfb8aa3b, v56
	v_add_f32_e32 v19, v19, v28
	v_add_f32_e32 v22, v18, v19
	v_pk_mul_f32 v[18:19], v[108:109], v[142:143]
	v_exp_f32_e32 v57, v57
	v_add_f32_e32 v19, v19, v22
	v_add_f32_e32 v28, v18, v19
	v_mul_f32_e32 v18, 0xbfb8aa3b, v28
	v_exp_f32_e32 v52, v18
	v_pk_mul_f32 v[18:19], v[44:45], v[20:21]
	v_lshlrev_b64 v[92:93], 2, v[42:43]
	v_add_f32_e32 v19, v19, v29
	v_add_f32_e32 v20, v18, v19
	v_pk_mul_f32 v[18:19], v[104:105], v[24:25]
	v_add_f32_e32 v57, 1.0, v57
	v_add_f32_e32 v19, v19, v20
	v_add_f32_e32 v29, v18, v19
	v_lshl_add_u64 v[18:19], s[20:21], 0, v[92:93]
	s_lshl_b64 s[20:21], s[16:17], 9
	s_add_u32 s20, s26, s20
	s_addc_u32 s21, s27, s21
	s_lshl_b32 s16, s4, 10
	v_rcp_f32_e32 v57, v57
	v_and_or_b32 v80, v151, s34, v147
	s_add_u32 s22, s24, s16
	v_lshl_add_u64 v[18:19], v[18:19], 0, v[74:75]
	s_addc_u32 s23, s25, 0
	v_ashrrev_i32_e32 v81, 31, v80
	v_lshlrev_b32_e32 v111, 5, v112
	v_lshl_add_u64 v[20:21], v[18:19], 0, s[14:15]
	v_add_co_u32_e32 v18, vcc, s35, v18
	s_add_u32 s42, s60, s16
	v_lshl_add_u64 v[82:83], s[18:19], 0, v[80:81]
	v_or_b32_e32 v58, v111, v110
	v_addc_co_u32_e32 v19, vcc, 0, v19, vcc
	s_addc_u32 s43, s61, 0
	v_lshlrev_b64 v[88:89], 11, v[82:83]
	v_or_b32_e32 v78, 16, v80
	v_mul_f32_e32 v51, v56, v57
	v_mul_f32_e32 v62, v54, v55
	v_mul_f32_e32 v33, v38, v40
	v_mul_f32_e32 v50, v39, v50
	global_load_dwordx4 v[38:41], v[18:19], off
	global_load_dwordx4 v[34:37], v[20:21], off offset:48
	global_load_dwordx4 v[42:45], v[20:21], off offset:32
	global_load_dwordx4 v[54:57], v[20:21], off offset:16
	v_lshlrev_b64 v[86:87], 2, v[80:81]
	v_lshl_add_u64 v[20:21], s[22:23], 0, v[88:89]
	v_mov_b64_e32 v[22:23], s[42:43]
	v_lshlrev_b32_e32 v76, 1, v58
	v_mov_b32_e32 v77, v75
	v_ashrrev_i32_e32 v79, 31, v78
	v_lshl_add_u64 v[18:19], s[20:21], 0, v[86:87]
	v_mul_lo_u32 v81, v83, s28
	v_mad_u64_u32 v[24:25], s[20:21], v82, s28, v[22:23]
	v_lshl_add_u64 v[20:21], v[20:21], 0, v[76:77]
	v_lshl_add_u64 v[84:85], s[18:19], 0, v[78:79]
	v_add_u32_e32 v25, v81, v25
	global_load_dword v83, v[18:19], off
	global_load_dwordx2 v[94:95], v[20:21], off
	global_load_dwordx2 v[98:99], v[20:21], off offset:32
	global_load_dword v113, v[18:19], off offset:64
	v_lshlrev_b64 v[90:91], 11, v[84:85]
	v_mul_lo_u32 v79, v85, s28
	v_mad_u64_u32 v[20:21], s[18:19], v84, s28, v[22:23]
	v_lshl_add_u64 v[24:25], v[24:25], 0, v[76:77]
	v_lshl_add_u64 v[18:19], s[22:23], 0, v[90:91]
	v_add_u32_e32 v21, v79, v21
	v_lshl_add_u64 v[18:19], v[18:19], 0, v[76:77]
	v_lshl_add_u64 v[20:21], v[20:21], 0, v[76:77]
	global_load_dwordx2 v[106:107], v[24:25], off
	global_load_dwordx2 v[126:127], v[24:25], off offset:32
	global_load_dwordx2 v[104:105], v[18:19], off
	global_load_dwordx2 v[96:97], v[18:19], off offset:32
	global_load_dwordx2 v[108:109], v[20:21], off
	global_load_dwordx2 v[100:101], v[20:21], off offset:32
	v_mul_f32_e32 v53, 0xbfb8aa3b, v29
	v_exp_f32_e32 v18, v53
	v_add_f32_e32 v20, 1.0, v52
	v_rcp_f32_e32 v19, v32
	v_rcp_f32_e32 v20, v20
	v_add_f32_e32 v18, 1.0, v18
	v_rcp_f32_e32 v18, v18
	v_mul_f32_e32 v23, v26, v30
	v_lshl_add_u32 v22, v152, 1, 0
	v_mul_f32_e32 v26, v27, v19
	v_mul_f32_e32 v27, v28, v20
	v_cvt_pk_bf16_f32 v20, v154, v155
	v_mad_u64_u32 v[24:25], s[18:19], v46, s33, v[22:23]
	v_mul_f32_e32 v28, v29, v18
	v_cvt_pk_bf16_f32 v18, v47, v67
	v_cvt_pk_bf16_f32 v19, v103, v153
	v_cvt_pk_bf16_f32 v21, v102, v156
	ds_write_b128 v24, v[18:21]
	v_cvt_pk_bf16_f32 v20, v160, v66
	v_cvt_pk_bf16_f32 v18, v49, v157
	v_cvt_pk_bf16_f32 v19, v158, v159
	v_cvt_pk_bf16_f32 v21, v161, v48
	ds_write_b128 v24, v[18:21] offset:272
	v_cvt_pk_bf16_f32 v20, v70, v51
	v_cvt_pk_bf16_f32 v18, v68, v69
	v_cvt_pk_bf16_f32 v19, v60, v61
	v_cvt_pk_bf16_f32 v21, v62, v63
	ds_write_b128 v24, v[18:21] offset:544
	v_cvt_pk_bf16_f32 v20, v23, v26
	v_or_b32_e32 v23, 3, v151
	v_cvt_pk_bf16_f32 v18, v33, v71
	v_mad_u64_u32 v[22:23], s[18:19], v23, s33, v[22:23]
	v_cvt_pk_bf16_f32 v19, v50, v31
	v_cvt_pk_bf16_f32 v21, v27, v28
	ds_write_b128 v22, v[18:21]
	v_mul_lo_u32 v18, v150, s33
	v_lshl_add_u32 v46, v148, 4, 0
	v_or_b32_e32 v47, v111, v147
	v_add3_u32 v128, 0, v18, v2
	v_mad_u64_u32 v[22:23], s[18:19], v78, s33, v[46:47]
	v_mad_u64_u32 v[30:31], s[18:19], v80, s33, v[46:47]
	v_mad_u32_u24 v129, v47, s33, v46
	ds_write_b128 v128, v[14:17] offset:34816
	ds_write_b128 v128, v[6:9] offset:34832
	s_waitcnt lgkmcnt(0)
	s_barrier
	ds_read_b128 v[2:5], v22 offset:192
	ds_read_b128 v[10:13], v22 offset:128
	ds_read_b128 v[6:9], v30 offset:192
	ds_read_b128 v[14:17], v30 offset:128
	ds_read_b128 v[18:21], v22 offset:64
	ds_read_b128 v[26:29], v22
	ds_read_b128 v[22:25], v30 offset:64
	ds_read_b128 v[30:33], v30
	ds_read_b128 v[46:49], v129 offset:34816
	ds_read_b128 v[50:53], v129 offset:34880
	ds_read_b128 v[58:61], v129 offset:39168
	ds_read_b128 v[62:65], v129 offset:39232
	ds_read_b128 v[66:69], v129 offset:34944
	ds_read_b128 v[70:73], v129 offset:35008
	ds_read_b128 v[114:117], v129 offset:39296
	ds_read_b128 v[118:121], v129 offset:39360
	s_waitcnt vmcnt(5)
	v_lshlrev_b32_e32 v85, 16, v106
	s_waitcnt lgkmcnt(7)
	v_mfma_f32_16x16x32_bf16 v[122:125], v[46:49], v[30:33], 0
	v_mul_f32_e32 v102, 0xbfb8aa3b, v85
	v_exp_f32_e32 v102, v102
	v_and_b32_e32 v106, 0xffff0000, v106
	s_waitcnt lgkmcnt(6)
	v_mfma_f32_16x16x32_bf16 v[122:125], v[50:53], v[22:25], v[122:125]
	v_mul_f32_e32 v130, 0xbfb8aa3b, v106
	v_add_f32_e32 v102, 1.0, v102
	v_rcp_f32_e32 v102, v102
	v_exp_f32_e32 v134, v130
	s_waitcnt lgkmcnt(3)
	v_mfma_f32_16x16x32_bf16 v[122:125], v[66:69], v[14:17], v[122:125]
	v_mul_f32_e32 v83, 0x3fb8aa3b, v83
	v_mul_f32_e32 v85, v102, v85
	v_add_f32_e32 v102, 1.0, v134
	v_exp_f32_e32 v83, v83
	s_waitcnt lgkmcnt(2)
	v_mfma_f32_16x16x32_bf16 v[122:125], v[70:73], v[6:9], v[122:125]
	v_rcp_f32_e32 v102, v102
	v_lshlrev_b32_e32 v103, 16, v94
	v_and_b32_e32 v94, 0xffff0000, v94
	v_mfma_f32_16x16x32_bf16 v[46:49], v[46:49], v[26:29], 0
	v_mul_f32_e32 v102, v102, v106
	s_nop 2
	v_fmac_f32_e32 v94, v83, v123
	v_fmac_f32_e32 v103, v83, v122
	v_mul_f32_e32 v94, v102, v94
	v_lshlrev_b32_e32 v102, 16, v107
	v_mul_f32_e32 v85, v85, v103
	v_mul_f32_e32 v103, 0xbfb8aa3b, v102
	v_mfma_f32_16x16x32_bf16 v[46:49], v[50:53], v[18:21], v[46:49]
	v_exp_f32_e32 v103, v103
	v_lshlrev_b32_e32 v106, 16, v95
	v_fmac_f32_e32 v106, v83, v124
	v_mfma_f32_16x16x32_bf16 v[130:133], v[58:61], v[30:33], 0
	v_add_f32_e32 v103, 1.0, v103
	v_rcp_f32_e32 v103, v103
	v_and_b32_e32 v107, 0xffff0000, v107
	v_mfma_f32_16x16x32_bf16 v[58:61], v[58:61], v[26:29], 0
	v_mul_f32_e32 v122, 0xbfb8aa3b, v107
	s_or_b32 s20, s40, 1
	s_or_b32 s16, s39, s20
	v_mfma_f32_16x16x32_bf16 v[46:49], v[66:69], v[10:13], v[46:49]
	s_lshl_b64 s[18:19], s[16:17], 15
	s_add_u32 s18, s74, s18
	s_addc_u32 s19, s75, s19
	v_mfma_f32_16x16x32_bf16 v[130:133], v[62:65], v[22:25], v[130:133]
	v_cvt_pk_bf16_f32 v38, v38, v39
	v_cvt_pk_bf16_f32 v39, v40, v41
	v_cvt_pk_bf16_f32 v40, v54, v55
	v_mfma_f32_16x16x32_bf16 v[50:53], v[62:65], v[18:21], v[58:61]
	v_exp_f32_e32 v62, v122
	v_and_b32_e32 v64, 0xffff0000, v95
	v_fmac_f32_e32 v64, v83, v125
	v_mfma_f32_16x16x32_bf16 v[70:73], v[70:73], v[2:5], v[46:49]
	v_mul_f32_e32 v58, v103, v102
	v_mul_f32_e32 v63, v58, v106
	v_add_f32_e32 v62, 1.0, v62
	s_waitcnt vmcnt(4)
	v_lshlrev_b32_e32 v46, 16, v126
	v_mul_f32_e32 v47, 0xbfb8aa3b, v46
	v_exp_f32_e32 v47, v47
	s_waitcnt lgkmcnt(1)
	v_mfma_f32_16x16x32_bf16 v[58:61], v[114:117], v[14:17], v[130:133]
	v_and_b32_e32 v49, 0xffff0000, v126
	v_lshlrev_b32_e32 v48, 16, v98
	v_add_f32_e32 v47, 1.0, v47
	v_mfma_f32_16x16x32_bf16 v[50:53], v[114:117], v[10:13], v[50:53]
	v_rcp_f32_e32 v47, v47
	v_rcp_f32_e32 v62, v62
	v_cvt_pk_bf16_f32 v116, v85, v94
	s_waitcnt lgkmcnt(0)
	v_mfma_f32_16x16x32_bf16 v[58:61], v[118:121], v[6:9], v[58:61]
	v_mul_f32_e32 v46, v47, v46
	v_and_b32_e32 v47, 0xffff0000, v98
	v_mul_f32_e32 v62, v62, v107
	v_mfma_f32_16x16x32_bf16 v[66:69], v[118:121], v[2:5], v[50:53]
	v_mul_f32_e32 v62, v62, v64
	s_nop 2
	v_fmac_f32_e32 v48, v83, v58
	v_mul_f32_e32 v46, v46, v48
	v_mul_f32_e32 v50, 0xbfb8aa3b, v49
	v_exp_f32_e32 v50, v50
	v_fmac_f32_e32 v47, v83, v59
	v_lshlrev_b32_e32 v52, 16, v99
	v_fmac_f32_e32 v52, v83, v60
	v_add_f32_e32 v48, 1.0, v50
	v_lshlrev_b32_e32 v50, 16, v127
	v_rcp_f32_e32 v48, v48
	v_mul_f32_e32 v51, 0xbfb8aa3b, v50
	v_exp_f32_e32 v51, v51
	v_mul_f32_e32 v64, v94, v94
	v_mul_f32_e32 v48, v48, v49
	v_and_b32_e32 v49, 0xffff0000, v127
	v_mul_f32_e32 v47, v48, v47
	v_add_f32_e32 v48, 1.0, v51
	v_mul_f32_e32 v51, 0xbfb8aa3b, v49
	v_rcp_f32_e32 v48, v48
	v_exp_f32_e32 v51, v51
	v_cvt_pk_bf16_f32 v117, v46, v47
	v_fmac_f32_e32 v64, v85, v85
	v_mul_f32_e32 v48, v48, v50
	v_add_f32_e32 v50, 1.0, v51
	v_rcp_f32_e32 v50, v50
	v_and_b32_e32 v51, 0xffff0000, v99
	v_mul_f32_e32 v48, v48, v52
	v_fmac_f32_e32 v51, v83, v61
	v_mul_f32_e32 v49, v50, v49
	v_mul_f32_e32 v50, v47, v47
	v_fmac_f32_e32 v50, v46, v46
	v_mul_f32_e32 v46, 0x3fb8aa3b, v113
	v_exp_f32_e32 v113, v46
	s_waitcnt vmcnt(1)
	v_lshlrev_b32_e32 v46, 16, v108
	v_mul_f32_e32 v47, 0xbfb8aa3b, v46
	v_exp_f32_e32 v47, v47
	v_mul_f32_e32 v49, v49, v51
	v_fmac_f32_e32 v50, v48, v48
	v_cvt_pk_bf16_f32 v118, v48, v49
	v_lshlrev_b32_e32 v48, 16, v104
	v_fmac_f32_e32 v48, v113, v70
	v_add_f32_e32 v47, 1.0, v47
	v_and_b32_e32 v70, 0xffff0000, v108
	v_fmac_f32_e32 v50, v49, v49
	v_rcp_f32_e32 v47, v47
	v_mul_f32_e32 v49, 0xbfb8aa3b, v70
	v_exp_f32_e32 v49, v49
	v_and_b32_e32 v83, 0xffff0000, v104
	v_mul_f32_e32 v46, v47, v46
	v_mul_f32_e32 v119, v46, v48
	v_add_f32_e32 v46, 1.0, v49
	v_lshlrev_b32_e32 v104, 16, v109
	v_rcp_f32_e32 v85, v46
	v_mul_f32_e32 v46, 0xbfb8aa3b, v104
	v_exp_f32_e32 v108, v46
	v_lshl_add_u64 v[46:47], s[18:19], 0, v[92:93]
	s_lshl_b64 s[18:19], s[16:17], 9
	s_add_u32 s18, s26, s18
	s_addc_u32 s19, s27, s19
	s_lshl_b32 s16, s20, 7
	s_add_u32 s20, s24, s16
	s_addc_u32 s21, s25, 0
	v_fmac_f32_e32 v64, v63, v63
	v_lshl_add_u64 v[46:47], v[46:47], 0, v[74:75]
	s_add_u32 s22, s60, s16
	v_fmac_f32_e32 v64, v62, v62
	v_cvt_pk_bf16_f32 v115, v63, v62
	v_lshl_add_u64 v[62:63], v[46:47], 0, s[14:15]
	v_add_co_u32_e32 v46, vcc, s35, v46
	s_addc_u32 s23, s61, 0
	v_lshl_add_u64 v[98:99], s[20:21], 0, v[88:89]
	v_addc_co_u32_e32 v47, vcc, 0, v47, vcc
	v_lshl_add_u64 v[94:95], s[18:19], 0, v[86:87]
	v_mov_b64_e32 v[102:103], s[22:23]
	v_lshl_add_u64 v[98:99], v[98:99], 0, v[76:77]
	v_add_f32_e32 v137, v64, v50
	global_load_dwordx4 v[50:53], v[46:47], off
	s_nop 0
	global_load_dwordx4 v[46:49], v[62:63], off offset:48
	global_load_dwordx4 v[58:61], v[62:63], off offset:32
	s_nop 0
	global_load_dwordx4 v[62:65], v[62:63], off offset:16
	v_mad_u64_u32 v[106:107], s[18:19], v82, s28, v[102:103]
	global_load_dword v124, v[94:95], off
	global_load_dwordx2 v[142:143], v[98:99], off
	global_load_dwordx2 v[154:155], v[98:99], off offset:32
	global_load_dword v149, v[94:95], off offset:64
	v_mad_u64_u32 v[98:99], s[18:19], v84, s28, v[102:103]
	v_add_u32_e32 v107, v81, v107
	v_lshl_add_u64 v[94:95], s[20:21], 0, v[90:91]
	v_add_u32_e32 v99, v79, v99
	v_lshl_add_u64 v[106:107], v[106:107], 0, v[76:77]
	v_lshl_add_u64 v[94:95], v[94:95], 0, v[76:77]
	v_lshl_add_u64 v[98:99], v[98:99], 0, v[76:77]
	global_load_dwordx2 v[156:157], v[106:107], off
	global_load_dwordx2 v[158:159], v[106:107], off offset:32
	global_load_dwordx2 v[102:103], v[94:95], off
	s_nop 0
	global_load_dwordx2 v[94:95], v[94:95], off offset:32
	s_nop 0
	global_load_dwordx2 v[106:107], v[98:99], off
	s_nop 0
	global_load_dwordx2 v[98:99], v[98:99], off offset:32
	v_fmac_f32_e32 v83, v113, v71
	v_mul_f32_e32 v70, v85, v70
	v_and_b32_e32 v71, 0xffff0000, v109
	v_mul_f32_e32 v130, v70, v83
	v_mul_f32_e32 v83, 0xbfb8aa3b, v71
	v_exp_f32_e32 v83, v83
	v_add_f32_e32 v70, 1.0, v108
	v_rcp_f32_e32 v70, v70
	v_lshlrev_b32_e32 v85, 16, v105
	v_fmac_f32_e32 v85, v113, v72
	v_add_f32_e32 v72, 1.0, v83
	v_rcp_f32_e32 v72, v72
	v_mul_f32_e32 v70, v70, v104
	v_mul_f32_e32 v131, v70, v85
	v_and_b32_e32 v70, 0xffff0000, v105
	v_fmac_f32_e32 v70, v113, v73
	v_mul_f32_e32 v71, v72, v71
	v_mul_f32_e32 v132, v71, v70
	s_waitcnt vmcnt(14)
	v_lshlrev_b32_e32 v70, 16, v100
	v_mul_f32_e32 v71, 0xbfb8aa3b, v70
	v_exp_f32_e32 v71, v71
	v_and_b32_e32 v73, 0xffff0000, v100
	v_mul_f32_e32 v100, 0xbfb8aa3b, v73
	v_exp_f32_e32 v100, v100
	v_add_f32_e32 v71, 1.0, v71
	v_rcp_f32_e32 v71, v71
	v_lshlrev_b32_e32 v72, 16, v96
	v_fmac_f32_e32 v72, v113, v66
	v_cvt_pk_bf16_f32 v41, v56, v57
	v_mul_f32_e32 v66, v71, v70
	v_mul_f32_e32 v133, v66, v72
	v_add_f32_e32 v66, 1.0, v100
	v_lshlrev_b32_e32 v70, 16, v101
	v_rcp_f32_e32 v66, v66
	v_mul_f32_e32 v71, 0xbfb8aa3b, v70
	v_exp_f32_e32 v71, v71
	v_and_b32_e32 v72, 0xffff0000, v96
	v_fmac_f32_e32 v72, v113, v67
	v_mul_f32_e32 v66, v66, v73
	v_add_f32_e32 v67, 1.0, v71
	v_mul_f32_e32 v134, v66, v72
	v_lshlrev_b32_e32 v66, 16, v97
	v_and_b32_e32 v96, 0xffff0000, v101
	v_rcp_f32_e32 v67, v67
	v_fmac_f32_e32 v66, v113, v68
	v_mul_f32_e32 v68, 0xbfb8aa3b, v96
	v_exp_f32_e32 v68, v68
	v_mul_f32_e32 v67, v67, v70
	v_mul_f32_e32 v135, v67, v66
	v_and_b32_e32 v97, 0xffff0000, v97
	v_add_f32_e32 v66, 1.0, v68
	v_cvt_pk_bf16_f32 v42, v42, v43
	v_cvt_pk_bf16_f32 v43, v44, v45
	v_cvt_pk_bf16_f32 v44, v34, v35
	v_cvt_pk_bf16_f32 v45, v36, v37
	v_fmac_f32_e32 v97, v113, v69
	v_rcp_f32_e32 v100, v66
	ds_write_b128 v128, v[38:41] offset:52224
	ds_write_b128 v128, v[42:45] offset:52240
	s_waitcnt lgkmcnt(0)
	s_barrier
	ds_read_b128 v[34:37], v129 offset:52224
	ds_read_b128 v[38:41], v129 offset:52288
	ds_read_b128 v[42:45], v129 offset:56576
	ds_read_b128 v[54:57], v129 offset:56640
	ds_read_b128 v[66:69], v129 offset:52352
	ds_read_b128 v[70:73], v129 offset:52416
	ds_read_b128 v[120:123], v129 offset:56704
	ds_read_b128 v[138:141], v129 offset:56768
	v_mul_f32_e32 v96, v100, v96
	v_mul_f32_e32 v136, v96, v97
	v_cvt_pk_bf16_f32 v85, v119, v130
	v_cvt_pk_bf16_f32 v83, v131, v132
	v_cvt_pk_bf16_f32 v114, v133, v134
	v_cvt_pk_bf16_f32 v113, v135, v136
	s_waitcnt vmcnt(9)
	v_mul_f32_e32 v96, 0x3fb8aa3b, v124
	s_waitcnt lgkmcnt(7)
	v_mfma_f32_16x16x32_bf16 v[124:127], v[34:37], v[30:33], 0
	s_waitcnt vmcnt(5)
	v_lshlrev_b32_e32 v97, 16, v156
	v_mul_f32_e32 v100, 0xbfb8aa3b, v97
	v_exp_f32_e32 v100, v100
	s_waitcnt lgkmcnt(6)
	v_mfma_f32_16x16x32_bf16 v[124:127], v[38:41], v[22:25], v[124:127]
	v_and_b32_e32 v104, 0xffff0000, v156
	v_mul_f32_e32 v105, 0xbfb8aa3b, v104
	v_add_f32_e32 v100, 1.0, v100
	s_waitcnt lgkmcnt(3)
	v_mfma_f32_16x16x32_bf16 v[124:127], v[66:69], v[14:17], v[124:127]
	v_rcp_f32_e32 v100, v100
	v_exp_f32_e32 v105, v105
	v_exp_f32_e32 v96, v96
	s_waitcnt lgkmcnt(2)
	v_mfma_f32_16x16x32_bf16 v[124:127], v[70:73], v[6:9], v[124:127]
	v_mul_f32_e32 v97, v100, v97
	v_add_f32_e32 v100, 1.0, v105
	v_rcp_f32_e32 v100, v100
	v_lshlrev_b32_e32 v101, 16, v142
	v_mfma_f32_16x16x32_bf16 v[34:37], v[34:37], v[26:29], 0
	s_nop 2
	v_fmac_f32_e32 v101, v96, v124
	v_mul_f32_e32 v97, v97, v101
	v_and_b32_e32 v101, 0xffff0000, v142
	v_fmac_f32_e32 v101, v96, v125
	v_mul_f32_e32 v100, v100, v104
	v_mul_f32_e32 v100, v100, v101
	v_lshlrev_b32_e32 v101, 16, v157
	v_mul_f32_e32 v104, 0xbfb8aa3b, v101
	v_exp_f32_e32 v104, v104
	v_mfma_f32_16x16x32_bf16 v[150:153], v[42:45], v[30:33], 0
	v_lshlrev_b32_e32 v105, 16, v143
	v_fmac_f32_e32 v105, v96, v126
	v_add_f32_e32 v104, 1.0, v104
	v_mfma_f32_16x16x32_bf16 v[34:37], v[38:41], v[18:21], v[34:37]
	v_rcp_f32_e32 v104, v104
	v_and_b32_e32 v108, 0xffff0000, v157
	v_mul_f32_e32 v109, 0xbfb8aa3b, v108
	v_mfma_f32_16x16x32_bf16 v[42:45], v[42:45], v[26:29], 0
	s_or_b32 s20, s40, 2
	s_or_b32 s16, s39, s20
	s_lshl_b64 s[18:19], s[16:17], 15
	v_mfma_f32_16x16x32_bf16 v[150:153], v[54:57], v[22:25], v[150:153]
	s_add_u32 s18, s74, s18
	s_addc_u32 s19, s75, s19
	v_mfma_f32_16x16x32_bf16 v[34:37], v[66:69], v[10:13], v[34:37]
	v_mfma_f32_16x16x32_bf16 v[38:41], v[54:57], v[18:21], v[42:45]
	v_exp_f32_e32 v54, v109
	v_and_b32_e32 v56, 0xffff0000, v143
	v_fmac_f32_e32 v56, v96, v127
	v_mul_f32_e32 v42, v104, v101
	v_mul_f32_e32 v55, v42, v105
	s_waitcnt lgkmcnt(1)
	v_mfma_f32_16x16x32_bf16 v[42:45], v[120:123], v[14:17], v[150:153]
	v_add_f32_e32 v54, 1.0, v54
	v_rcp_f32_e32 v54, v54
	v_cvt_pk_bf16_f32 v127, v97, v100
	v_mfma_f32_16x16x32_bf16 v[70:73], v[70:73], v[2:5], v[34:37]
	v_mul_f32_e32 v54, v54, v108
	v_mul_f32_e32 v54, v54, v56
	s_waitcnt vmcnt(4)
	v_lshlrev_b32_e32 v34, 16, v158
	v_mul_f32_e32 v35, 0xbfb8aa3b, v34
	v_exp_f32_e32 v35, v35
	s_waitcnt lgkmcnt(0)
	v_mfma_f32_16x16x32_bf16 v[42:45], v[138:141], v[6:9], v[42:45]
	v_lshlrev_b32_e32 v36, 16, v154
	v_and_b32_e32 v37, 0xffff0000, v158
	v_add_f32_e32 v35, 1.0, v35
	v_rcp_f32_e32 v35, v35
	v_mul_f32_e32 v56, v100, v100
	s_nop 2
	v_fmac_f32_e32 v36, v96, v42
	v_mul_f32_e32 v42, 0xbfb8aa3b, v37
	v_exp_f32_e32 v42, v42
	v_fmac_f32_e32 v56, v97, v97
	v_mul_f32_e32 v34, v35, v34
	v_fmac_f32_e32 v56, v55, v55
	v_mul_f32_e32 v34, v34, v36
	v_add_f32_e32 v36, 1.0, v42
	v_lshlrev_b32_e32 v42, 16, v159
	v_mfma_f32_16x16x32_bf16 v[38:41], v[120:123], v[10:13], v[38:41]
	v_fmac_f32_e32 v56, v54, v54
	v_cvt_pk_bf16_f32 v122, v55, v54
	v_rcp_f32_e32 v36, v36
	v_mul_f32_e32 v54, 0xbfb8aa3b, v42
	v_exp_f32_e32 v54, v54
	v_and_b32_e32 v35, 0xffff0000, v154
	v_fmac_f32_e32 v35, v96, v43
	v_mul_f32_e32 v36, v36, v37
	v_and_b32_e32 v37, 0xffff0000, v159
	v_mul_f32_e32 v35, v36, v35
	v_add_f32_e32 v36, 1.0, v54
	v_mul_f32_e32 v43, 0xbfb8aa3b, v37
	v_rcp_f32_e32 v36, v36
	v_exp_f32_e32 v43, v43
	v_cvt_pk_bf16_f32 v125, v34, v35
	v_lshlrev_b32_e32 v54, 16, v155
	v_mul_f32_e32 v36, v36, v42
	v_add_f32_e32 v42, 1.0, v43
	v_rcp_f32_e32 v42, v42
	v_fmac_f32_e32 v54, v96, v44
	v_and_b32_e32 v43, 0xffff0000, v155
	v_mul_f32_e32 v36, v36, v54
	v_mul_f32_e32 v37, v42, v37
	v_mul_f32_e32 v42, v35, v35
	v_fmac_f32_e32 v42, v34, v34
	v_mul_f32_e32 v34, 0x3fb8aa3b, v149
	v_exp_f32_e32 v123, v34
	s_waitcnt vmcnt(1)
	v_lshlrev_b32_e32 v34, 16, v106
	v_mul_f32_e32 v35, 0xbfb8aa3b, v34
	v_exp_f32_e32 v35, v35
	v_fmac_f32_e32 v43, v96, v45
	v_mul_f32_e32 v37, v37, v43
	v_fmac_f32_e32 v42, v36, v36
	v_cvt_pk_bf16_f32 v126, v36, v37
	v_lshlrev_b32_e32 v36, 16, v102
	v_fmac_f32_e32 v36, v123, v70
	v_add_f32_e32 v35, 1.0, v35
	v_and_b32_e32 v70, 0xffff0000, v106
	v_fmac_f32_e32 v42, v37, v37
	v_rcp_f32_e32 v35, v35
	v_mul_f32_e32 v37, 0xbfb8aa3b, v70
	v_exp_f32_e32 v37, v37
	v_add_f32_e32 v56, v137, v56
	v_mul_f32_e32 v34, v35, v34
	v_mul_f32_e32 v137, v34, v36
	v_add_f32_e32 v34, 1.0, v37
	v_lshlrev_b32_e32 v120, 16, v107
	v_rcp_f32_e32 v106, v34
	v_mul_f32_e32 v34, 0xbfb8aa3b, v120
	v_exp_f32_e32 v121, v34
	v_lshl_add_u64 v[34:35], s[18:19], 0, v[92:93]
	s_lshl_b64 s[18:19], s[16:17], 9
	s_add_u32 s18, s26, s18
	s_addc_u32 s19, s27, s19
	s_lshl_b32 s16, s20, 7
	s_add_u32 s20, s24, s16
	s_addc_u32 s21, s25, 0
	v_lshl_add_u64 v[34:35], v[34:35], 0, v[74:75]
	s_add_u32 s22, s60, s16
	v_lshl_add_u64 v[66:67], v[34:35], 0, s[14:15]
	v_add_co_u32_e32 v34, vcc, s35, v34
	s_addc_u32 s23, s61, 0
	v_lshl_add_u64 v[100:101], s[20:21], 0, v[88:89]
	v_addc_co_u32_e32 v35, vcc, 0, v35, vcc
	v_lshl_add_u64 v[96:97], s[18:19], 0, v[86:87]
	v_mov_b64_e32 v[104:105], s[22:23]
	v_lshl_add_u64 v[100:101], v[100:101], 0, v[76:77]
	v_add_f32_e32 v150, v56, v42
	global_load_dwordx4 v[42:45], v[34:35], off
	s_nop 0
	global_load_dwordx4 v[34:37], v[66:67], off offset:48
	global_load_dwordx4 v[54:57], v[66:67], off offset:32
	s_nop 0
	global_load_dwordx4 v[66:69], v[66:67], off offset:16
	v_mad_u64_u32 v[108:109], s[18:19], v82, s28, v[104:105]
	global_load_dword v149, v[96:97], off
	global_load_dwordx2 v[142:143], v[100:101], off
	global_load_dwordx2 v[170:171], v[100:101], off offset:32
	global_load_dword v176, v[96:97], off offset:64
	v_mad_u64_u32 v[100:101], s[18:19], v84, s28, v[104:105]
	v_add_u32_e32 v109, v81, v109
	v_lshl_add_u64 v[96:97], s[20:21], 0, v[90:91]
	v_add_u32_e32 v101, v79, v101
	v_lshl_add_u64 v[108:109], v[108:109], 0, v[76:77]
	v_lshl_add_u64 v[96:97], v[96:97], 0, v[76:77]
	v_lshl_add_u64 v[100:101], v[100:101], 0, v[76:77]
	global_load_dwordx2 v[172:173], v[108:109], off
	global_load_dwordx2 v[174:175], v[108:109], off offset:32
	global_load_dwordx2 v[104:105], v[96:97], off
	s_nop 0
	global_load_dwordx2 v[96:97], v[96:97], off offset:32
	s_nop 0
	global_load_dwordx2 v[108:109], v[100:101], off
	s_nop 0
	global_load_dwordx2 v[100:101], v[100:101], off offset:32
	v_and_b32_e32 v102, 0xffff0000, v102
	v_fmac_f32_e32 v102, v123, v71
	v_mul_f32_e32 v70, v106, v70
	v_and_b32_e32 v71, 0xffff0000, v107
	v_mul_f32_e32 v151, v70, v102
	v_mul_f32_e32 v102, 0xbfb8aa3b, v71
	v_exp_f32_e32 v102, v102
	v_add_f32_e32 v70, 1.0, v121
	v_rcp_f32_e32 v70, v70
	v_lshlrev_b32_e32 v106, 16, v103
	v_fmac_f32_e32 v106, v123, v72
	v_add_f32_e32 v72, 1.0, v102
	v_rcp_f32_e32 v72, v72
	v_mul_f32_e32 v70, v70, v120
	v_mul_f32_e32 v152, v70, v106
	v_and_b32_e32 v70, 0xffff0000, v103
	v_fmac_f32_e32 v70, v123, v73
	v_mul_f32_e32 v71, v72, v71
	v_mul_f32_e32 v153, v71, v70
	s_waitcnt vmcnt(14)
	v_lshlrev_b32_e32 v70, 16, v98
	v_mul_f32_e32 v71, 0xbfb8aa3b, v70
	v_exp_f32_e32 v71, v71
	v_and_b32_e32 v73, 0xffff0000, v98
	v_mfma_f32_16x16x32_bf16 v[38:41], v[138:141], v[2:5], v[38:41]
	v_mul_f32_e32 v98, 0xbfb8aa3b, v73
	v_add_f32_e32 v71, 1.0, v71
	v_rcp_f32_e32 v71, v71
	v_exp_f32_e32 v98, v98
	v_lshlrev_b32_e32 v72, 16, v94
	s_nop 2
	v_fmac_f32_e32 v72, v123, v38
	v_mul_f32_e32 v38, v71, v70
	v_mul_f32_e32 v154, v38, v72
	v_add_f32_e32 v38, 1.0, v98
	v_lshlrev_b32_e32 v70, 16, v99
	v_rcp_f32_e32 v38, v38
	v_mul_f32_e32 v71, 0xbfb8aa3b, v70
	v_exp_f32_e32 v71, v71
	v_and_b32_e32 v72, 0xffff0000, v94
	v_fmac_f32_e32 v72, v123, v39
	v_mul_f32_e32 v38, v38, v73
	v_add_f32_e32 v39, 1.0, v71
	v_mul_f32_e32 v155, v38, v72
	v_lshlrev_b32_e32 v38, 16, v95
	v_and_b32_e32 v94, 0xffff0000, v99
	v_rcp_f32_e32 v39, v39
	v_fmac_f32_e32 v38, v123, v40
	v_mul_f32_e32 v40, 0xbfb8aa3b, v94
	v_exp_f32_e32 v40, v40
	v_mul_f32_e32 v39, v39, v70
	v_mul_f32_e32 v156, v39, v38
	v_and_b32_e32 v95, 0xffff0000, v95
	v_add_f32_e32 v38, 1.0, v40
	v_fmac_f32_e32 v95, v123, v41
	v_rcp_f32_e32 v98, v38
	v_cvt_pk_bf16_f32 v38, v50, v51
	v_cvt_pk_bf16_f32 v39, v52, v53
	v_cvt_pk_bf16_f32 v40, v62, v63
	v_cvt_pk_bf16_f32 v41, v64, v65
	v_cvt_pk_bf16_f32 v50, v58, v59
	v_cvt_pk_bf16_f32 v51, v60, v61
	v_cvt_pk_bf16_f32 v52, v46, v47
	v_cvt_pk_bf16_f32 v53, v48, v49
	ds_write_b128 v128, v[38:41] offset:34816
	ds_write_b128 v128, v[50:53] offset:34832
	s_waitcnt lgkmcnt(0)
	s_barrier
	ds_read_b128 v[38:41], v129 offset:34816
	ds_read_b128 v[46:49], v129 offset:34880
	ds_read_b128 v[50:53], v129 offset:39168
	ds_read_b128 v[58:61], v129 offset:39232
	ds_read_b128 v[62:65], v129 offset:34944
	ds_read_b128 v[70:73], v129 offset:35008
	ds_read_b128 v[138:141], v129 offset:39296
	ds_read_b128 v[158:161], v129 offset:39360
	v_mul_f32_e32 v94, v98, v94
	v_mul_f32_e32 v157, v94, v95
	v_cvt_pk_bf16_f32 v121, v137, v151
	v_cvt_pk_bf16_f32 v120, v152, v153
	v_cvt_pk_bf16_f32 v124, v154, v155
	v_cvt_pk_bf16_f32 v123, v156, v157
	s_waitcnt lgkmcnt(7)
	v_mfma_f32_16x16x32_bf16 v[162:165], v[38:41], v[30:33], 0
	s_waitcnt vmcnt(5)
	v_lshlrev_b32_e32 v95, 16, v172
	v_mul_f32_e32 v98, 0xbfb8aa3b, v95
	v_exp_f32_e32 v98, v98
	s_waitcnt lgkmcnt(6)
	v_mfma_f32_16x16x32_bf16 v[162:165], v[46:49], v[22:25], v[162:165]
	v_and_b32_e32 v102, 0xffff0000, v172
	v_mul_f32_e32 v103, 0xbfb8aa3b, v102
	v_add_f32_e32 v98, 1.0, v98
	s_waitcnt lgkmcnt(3)
	v_mfma_f32_16x16x32_bf16 v[162:165], v[62:65], v[14:17], v[162:165]
	v_rcp_f32_e32 v98, v98
	v_exp_f32_e32 v103, v103
	v_mul_f32_e32 v94, 0x3fb8aa3b, v149
	v_exp_f32_e32 v94, v94
	s_waitcnt lgkmcnt(2)
	v_mfma_f32_16x16x32_bf16 v[162:165], v[70:73], v[6:9], v[162:165]
	v_mul_f32_e32 v95, v98, v95
	v_add_f32_e32 v98, 1.0, v103
	v_rcp_f32_e32 v98, v98
	v_lshlrev_b32_e32 v99, 16, v142
	v_mfma_f32_16x16x32_bf16 v[38:41], v[38:41], v[26:29], 0
	s_nop 2
	v_fmac_f32_e32 v99, v94, v162
	v_mul_f32_e32 v95, v95, v99
	v_and_b32_e32 v99, 0xffff0000, v142
	v_fmac_f32_e32 v99, v94, v163
	v_mul_f32_e32 v98, v98, v102
	v_mul_f32_e32 v98, v98, v99
	v_lshlrev_b32_e32 v99, 16, v173
	v_mul_f32_e32 v102, 0xbfb8aa3b, v99
	v_mfma_f32_16x16x32_bf16 v[38:41], v[46:49], v[18:21], v[38:41]
	v_exp_f32_e32 v102, v102
	v_lshlrev_b32_e32 v103, 16, v143
	v_fmac_f32_e32 v103, v94, v164
	v_mfma_f32_16x16x32_bf16 v[166:169], v[50:53], v[30:33], 0
	v_add_f32_e32 v102, 1.0, v102
	v_rcp_f32_e32 v102, v102
	v_and_b32_e32 v106, 0xffff0000, v173
	v_mfma_f32_16x16x32_bf16 v[50:53], v[50:53], v[26:29], 0
	v_mul_f32_e32 v107, 0xbfb8aa3b, v106
	s_or_b32 s20, s40, 3
	s_or_b32 s16, s39, s20
	v_mfma_f32_16x16x32_bf16 v[38:41], v[62:65], v[10:13], v[38:41]
	s_lshl_b64 s[18:19], s[16:17], 15
	s_add_u32 s18, s74, s18
	s_addc_u32 s19, s75, s19
	v_mfma_f32_16x16x32_bf16 v[166:169], v[58:61], v[22:25], v[166:169]
	v_cvt_pk_bf16_f32 v42, v42, v43
	v_cvt_pk_bf16_f32 v43, v44, v45
	v_cvt_pk_bf16_f32 v44, v66, v67
	v_mfma_f32_16x16x32_bf16 v[46:49], v[58:61], v[18:21], v[50:53]
	v_exp_f32_e32 v58, v107
	v_and_b32_e32 v60, 0xffff0000, v143
	v_fmac_f32_e32 v60, v94, v165
	v_mfma_f32_16x16x32_bf16 v[70:73], v[70:73], v[2:5], v[38:41]
	v_mul_f32_e32 v50, v102, v99
	v_mul_f32_e32 v59, v50, v103
	v_add_f32_e32 v58, 1.0, v58
	s_waitcnt vmcnt(4)
	v_lshlrev_b32_e32 v38, 16, v174
	v_mul_f32_e32 v39, 0xbfb8aa3b, v38
	v_exp_f32_e32 v39, v39
	s_waitcnt lgkmcnt(1)
	v_mfma_f32_16x16x32_bf16 v[50:53], v[138:141], v[14:17], v[166:169]
	v_and_b32_e32 v41, 0xffff0000, v174
	v_lshlrev_b32_e32 v40, 16, v170
	v_add_f32_e32 v39, 1.0, v39
	v_mfma_f32_16x16x32_bf16 v[46:49], v[138:141], v[10:13], v[46:49]
	v_rcp_f32_e32 v39, v39
	v_rcp_f32_e32 v58, v58
	s_waitcnt vmcnt(1)
	v_lshlrev_b32_e32 v138, 16, v109
	s_waitcnt lgkmcnt(0)
	v_mfma_f32_16x16x32_bf16 v[50:53], v[158:161], v[6:9], v[50:53]
	v_mul_f32_e32 v38, v39, v38
	v_and_b32_e32 v39, 0xffff0000, v170
	v_mul_f32_e32 v58, v58, v106
	v_mfma_f32_16x16x32_bf16 v[62:65], v[158:161], v[2:5], v[46:49]
	v_mul_f32_e32 v58, v58, v60
	s_nop 2
	v_fmac_f32_e32 v40, v94, v50
	v_mul_f32_e32 v38, v38, v40
	v_mul_f32_e32 v46, 0xbfb8aa3b, v41
	v_exp_f32_e32 v46, v46
	v_fmac_f32_e32 v39, v94, v51
	v_mul_f32_e32 v60, v98, v98
	v_fmac_f32_e32 v60, v95, v95
	v_add_f32_e32 v40, 1.0, v46
	v_lshlrev_b32_e32 v46, 16, v175
	v_rcp_f32_e32 v40, v40
	v_mul_f32_e32 v47, 0xbfb8aa3b, v46
	v_exp_f32_e32 v47, v47
	v_lshlrev_b32_e32 v48, 16, v171
	v_mul_f32_e32 v40, v40, v41
	v_and_b32_e32 v41, 0xffff0000, v175
	v_mul_f32_e32 v39, v40, v39
	v_add_f32_e32 v40, 1.0, v47
	v_mul_f32_e32 v47, 0xbfb8aa3b, v41
	v_rcp_f32_e32 v40, v40
	v_exp_f32_e32 v47, v47
	v_cvt_pk_bf16_f32 v149, v38, v39
	v_fmac_f32_e32 v60, v59, v59
	v_mul_f32_e32 v40, v40, v46
	v_add_f32_e32 v46, 1.0, v47
	v_rcp_f32_e32 v46, v46
	v_fmac_f32_e32 v48, v94, v52
	v_and_b32_e32 v47, 0xffff0000, v171
	v_fmac_f32_e32 v60, v58, v58
	v_mul_f32_e32 v41, v46, v41
	v_mul_f32_e32 v46, v39, v39
	v_fmac_f32_e32 v46, v38, v38
	v_mul_f32_e32 v38, 0x3fb8aa3b, v176
	v_exp_f32_e32 v142, v38
	v_lshlrev_b32_e32 v38, 16, v108
	v_mul_f32_e32 v39, 0xbfb8aa3b, v38
	v_exp_f32_e32 v39, v39
	v_mul_f32_e32 v40, v40, v48
	v_fmac_f32_e32 v47, v94, v53
	v_add_f32_e32 v60, v150, v60
	v_mul_f32_e32 v41, v41, v47
	v_fmac_f32_e32 v46, v40, v40
	v_cvt_pk_bf16_f32 v150, v40, v41
	v_lshlrev_b32_e32 v40, 16, v104
	v_fmac_f32_e32 v40, v142, v70
	v_add_f32_e32 v39, 1.0, v39
	v_and_b32_e32 v70, 0xffff0000, v108
	v_fmac_f32_e32 v46, v41, v41
	v_rcp_f32_e32 v39, v39
	v_mul_f32_e32 v41, 0xbfb8aa3b, v70
	v_exp_f32_e32 v41, v41
	v_cvt_pk_bf16_f32 v140, v95, v98
	v_mul_f32_e32 v38, v39, v38
	v_mul_f32_e32 v160, v38, v40
	v_add_f32_e32 v38, 1.0, v41
	v_rcp_f32_e32 v108, v38
	v_mul_f32_e32 v38, 0xbfb8aa3b, v138
	v_exp_f32_e32 v139, v38
	v_lshl_add_u64 v[38:39], s[18:19], 0, v[92:93]
	s_lshl_b64 s[18:19], s[16:17], 9
	s_add_u32 s18, s26, s18
	s_addc_u32 s19, s27, s19
	s_lshl_b32 s16, s20, 7
	s_add_u32 s20, s24, s16
	s_addc_u32 s21, s25, 0
	v_lshl_add_u64 v[38:39], v[38:39], 0, v[74:75]
	s_add_u32 s22, s60, s16
	v_cvt_pk_bf16_f32 v141, v59, v58
	v_lshl_add_u64 v[58:59], v[38:39], 0, s[14:15]
	v_add_co_u32_e32 v38, vcc, s35, v38
	s_addc_u32 s23, s61, 0
	v_lshl_add_u64 v[98:99], s[20:21], 0, v[88:89]
	v_addc_co_u32_e32 v39, vcc, 0, v39, vcc
	v_lshl_add_u64 v[94:95], s[18:19], 0, v[86:87]
	v_mov_b64_e32 v[102:103], s[22:23]
	v_lshl_add_u64 v[98:99], v[98:99], 0, v[76:77]
	v_add_f32_e32 v161, v60, v46
	global_load_dwordx4 v[46:49], v[38:39], off
	s_nop 0
	global_load_dwordx4 v[38:41], v[58:59], off offset:48
	global_load_dwordx4 v[50:53], v[58:59], off offset:32
	s_nop 0
	global_load_dwordx4 v[58:61], v[58:59], off offset:16
	v_mad_u64_u32 v[106:107], s[18:19], v82, s28, v[102:103]
	global_load_dword v166, v[94:95], off
	global_load_dwordx2 v[158:159], v[98:99], off
	global_load_dwordx2 v[182:183], v[98:99], off offset:32
	global_load_dword v185, v[94:95], off offset:64
	v_mad_u64_u32 v[98:99], s[18:19], v84, s28, v[102:103]
	v_add_u32_e32 v107, v81, v107
	v_lshl_add_u64 v[94:95], s[20:21], 0, v[90:91]
	v_add_u32_e32 v99, v79, v99
	v_lshl_add_u64 v[106:107], v[106:107], 0, v[76:77]
	v_lshl_add_u64 v[94:95], v[94:95], 0, v[76:77]
	v_lshl_add_u64 v[98:99], v[98:99], 0, v[76:77]
	global_load_dwordx2 v[190:191], v[106:107], off
	global_load_dwordx2 v[192:193], v[106:107], off offset:32
	global_load_dwordx2 v[102:103], v[94:95], off
	s_nop 0
	global_load_dwordx2 v[94:95], v[94:95], off offset:32
	s_nop 0
	global_load_dwordx2 v[106:107], v[98:99], off
	s_nop 0
	global_load_dwordx2 v[98:99], v[98:99], off offset:32
	v_and_b32_e32 v104, 0xffff0000, v104
	v_fmac_f32_e32 v104, v142, v71
	v_mul_f32_e32 v70, v108, v70
	v_and_b32_e32 v71, 0xffff0000, v109
	v_mul_f32_e32 v167, v70, v104
	v_mul_f32_e32 v104, 0xbfb8aa3b, v71
	v_exp_f32_e32 v104, v104
	v_add_f32_e32 v70, 1.0, v139
	v_rcp_f32_e32 v70, v70
	v_lshlrev_b32_e32 v108, 16, v105
	v_fmac_f32_e32 v108, v142, v72
	v_add_f32_e32 v72, 1.0, v104
	v_rcp_f32_e32 v72, v72
	v_mul_f32_e32 v70, v70, v138
	v_mul_f32_e32 v168, v70, v108
	v_and_b32_e32 v70, 0xffff0000, v105
	v_fmac_f32_e32 v70, v142, v73
	v_mul_f32_e32 v71, v72, v71
	v_mul_f32_e32 v169, v71, v70
	s_waitcnt vmcnt(14)
	v_lshlrev_b32_e32 v70, 16, v100
	v_mul_f32_e32 v71, 0xbfb8aa3b, v70
	v_exp_f32_e32 v71, v71
	v_and_b32_e32 v73, 0xffff0000, v100
	v_mul_f32_e32 v100, 0xbfb8aa3b, v73
	v_exp_f32_e32 v100, v100
	v_add_f32_e32 v71, 1.0, v71
	v_rcp_f32_e32 v71, v71
	v_lshlrev_b32_e32 v72, 16, v96
	v_fmac_f32_e32 v72, v142, v62
	v_cvt_pk_bf16_f32 v45, v68, v69
	v_mul_f32_e32 v62, v71, v70
	v_mul_f32_e32 v170, v62, v72
	v_add_f32_e32 v62, 1.0, v100
	v_lshlrev_b32_e32 v70, 16, v101
	v_rcp_f32_e32 v62, v62
	v_mul_f32_e32 v71, 0xbfb8aa3b, v70
	v_exp_f32_e32 v71, v71
	v_and_b32_e32 v72, 0xffff0000, v96
	v_fmac_f32_e32 v72, v142, v63
	v_mul_f32_e32 v62, v62, v73
	v_add_f32_e32 v63, 1.0, v71
	v_mul_f32_e32 v171, v62, v72
	v_lshlrev_b32_e32 v62, 16, v97
	v_and_b32_e32 v96, 0xffff0000, v101
	v_rcp_f32_e32 v63, v63
	v_fmac_f32_e32 v62, v142, v64
	v_mul_f32_e32 v64, 0xbfb8aa3b, v96
	v_exp_f32_e32 v64, v64
	v_mul_f32_e32 v63, v63, v70
	v_mul_f32_e32 v172, v63, v62
	v_and_b32_e32 v97, 0xffff0000, v97
	v_add_f32_e32 v62, 1.0, v64
	v_cvt_pk_bf16_f32 v54, v54, v55
	v_cvt_pk_bf16_f32 v55, v56, v57
	v_cvt_pk_bf16_f32 v56, v34, v35
	v_cvt_pk_bf16_f32 v57, v36, v37
	v_fmac_f32_e32 v97, v142, v65
	v_rcp_f32_e32 v100, v62
	ds_write_b128 v128, v[42:45] offset:52224
	ds_write_b128 v128, v[54:57] offset:52240
	s_waitcnt lgkmcnt(0)
	s_barrier
	ds_read_b128 v[34:37], v129 offset:52224
	ds_read_b128 v[42:45], v129 offset:52288
	ds_read_b128 v[54:57], v129 offset:56576
	ds_read_b128 v[62:65], v129 offset:56640
	ds_read_b128 v[66:69], v129 offset:52352
	ds_read_b128 v[70:73], v129 offset:52416
	ds_read_b128 v[162:165], v129 offset:56704
	ds_read_b128 v[174:177], v129 offset:56768
	v_mul_f32_e32 v96, v100, v96
	v_mul_f32_e32 v173, v96, v97
	v_cvt_pk_bf16_f32 v139, v160, v167
	v_cvt_pk_bf16_f32 v138, v168, v169
	v_cvt_pk_bf16_f32 v143, v170, v171
	v_cvt_pk_bf16_f32 v142, v172, v173
	s_waitcnt lgkmcnt(7)
	v_mfma_f32_16x16x32_bf16 v[178:181], v[34:37], v[30:33], 0
	s_waitcnt vmcnt(5)
	v_lshlrev_b32_e32 v97, 16, v190
	v_mul_f32_e32 v100, 0xbfb8aa3b, v97
	v_exp_f32_e32 v100, v100
	s_waitcnt lgkmcnt(6)
	v_mfma_f32_16x16x32_bf16 v[178:181], v[42:45], v[22:25], v[178:181]
	v_and_b32_e32 v104, 0xffff0000, v190
	v_mul_f32_e32 v105, 0xbfb8aa3b, v104
	v_add_f32_e32 v100, 1.0, v100
	s_waitcnt lgkmcnt(3)
	v_mfma_f32_16x16x32_bf16 v[178:181], v[66:69], v[14:17], v[178:181]
	v_rcp_f32_e32 v100, v100
	v_exp_f32_e32 v105, v105
	v_mul_f32_e32 v96, 0x3fb8aa3b, v166
	v_exp_f32_e32 v96, v96
	s_waitcnt lgkmcnt(2)
	v_mfma_f32_16x16x32_bf16 v[178:181], v[70:73], v[6:9], v[178:181]
	v_mul_f32_e32 v97, v100, v97
	v_add_f32_e32 v100, 1.0, v105
	v_rcp_f32_e32 v100, v100
	v_lshlrev_b32_e32 v101, 16, v158
	v_mfma_f32_16x16x32_bf16 v[34:37], v[34:37], v[26:29], 0
	s_nop 2
	v_fmac_f32_e32 v101, v96, v178
	v_mul_f32_e32 v97, v97, v101
	v_and_b32_e32 v101, 0xffff0000, v158
	v_fmac_f32_e32 v101, v96, v179
	v_mul_f32_e32 v100, v100, v104
	v_mul_f32_e32 v100, v100, v101
	v_lshlrev_b32_e32 v101, 16, v191
	v_mul_f32_e32 v104, 0xbfb8aa3b, v101
	v_mfma_f32_16x16x32_bf16 v[34:37], v[42:45], v[18:21], v[34:37]
	v_exp_f32_e32 v104, v104
	v_lshlrev_b32_e32 v105, 16, v159
	v_fmac_f32_e32 v105, v96, v180
	v_mfma_f32_16x16x32_bf16 v[186:189], v[54:57], v[30:33], 0
	v_add_f32_e32 v104, 1.0, v104
	v_rcp_f32_e32 v104, v104
	v_and_b32_e32 v108, 0xffff0000, v191
	v_mfma_f32_16x16x32_bf16 v[54:57], v[54:57], v[26:29], 0
	v_mul_f32_e32 v109, 0xbfb8aa3b, v108
	s_or_b32 s20, s40, 4
	s_or_b32 s16, s39, s20
	v_mfma_f32_16x16x32_bf16 v[34:37], v[66:69], v[10:13], v[34:37]
	s_lshl_b64 s[18:19], s[16:17], 15
	s_waitcnt vmcnt(1)
	v_lshlrev_b32_e32 v158, 16, v107
	s_add_u32 s18, s74, s18
	v_mfma_f32_16x16x32_bf16 v[186:189], v[62:65], v[22:25], v[186:189]
	s_addc_u32 s19, s75, s19
	v_cvt_pk_bf16_f32 v46, v46, v47
	v_cvt_pk_bf16_f32 v47, v48, v49
	v_mfma_f32_16x16x32_bf16 v[42:45], v[62:65], v[18:21], v[54:57]
	v_exp_f32_e32 v62, v109
	v_and_b32_e32 v64, 0xffff0000, v159
	v_fmac_f32_e32 v64, v96, v181
	v_mfma_f32_16x16x32_bf16 v[70:73], v[70:73], v[2:5], v[34:37]
	v_mul_f32_e32 v54, v104, v101
	v_mul_f32_e32 v63, v54, v105
	v_add_f32_e32 v62, 1.0, v62
	v_lshlrev_b32_e32 v34, 16, v192
	v_mul_f32_e32 v35, 0xbfb8aa3b, v34
	v_exp_f32_e32 v35, v35
	s_waitcnt lgkmcnt(1)
	v_mfma_f32_16x16x32_bf16 v[54:57], v[162:165], v[14:17], v[186:189]
	v_and_b32_e32 v37, 0xffff0000, v192
	v_lshlrev_b32_e32 v36, 16, v182
	v_add_f32_e32 v35, 1.0, v35
	v_mfma_f32_16x16x32_bf16 v[42:45], v[162:165], v[10:13], v[42:45]
	v_rcp_f32_e32 v35, v35
	v_rcp_f32_e32 v62, v62
	v_cvt_pk_bf16_f32 v48, v58, v59
	s_waitcnt lgkmcnt(0)
	v_mfma_f32_16x16x32_bf16 v[54:57], v[174:177], v[6:9], v[54:57]
	v_mul_f32_e32 v34, v35, v34
	v_and_b32_e32 v35, 0xffff0000, v182
	v_mul_f32_e32 v62, v62, v108
	v_mfma_f32_16x16x32_bf16 v[66:69], v[174:177], v[2:5], v[42:45]
	v_mul_f32_e32 v62, v62, v64
	s_nop 2
	v_fmac_f32_e32 v36, v96, v54
	v_mul_f32_e32 v34, v34, v36
	v_mul_f32_e32 v42, 0xbfb8aa3b, v37
	v_exp_f32_e32 v42, v42
	v_fmac_f32_e32 v35, v96, v55
	v_lshlrev_b32_e32 v44, 16, v183
	v_fmac_f32_e32 v44, v96, v56
	v_add_f32_e32 v36, 1.0, v42
	v_lshlrev_b32_e32 v42, 16, v193
	v_rcp_f32_e32 v36, v36
	v_mul_f32_e32 v43, 0xbfb8aa3b, v42
	v_exp_f32_e32 v43, v43
	v_mul_f32_e32 v64, v100, v100
	v_mul_f32_e32 v36, v36, v37
	v_and_b32_e32 v37, 0xffff0000, v193
	v_mul_f32_e32 v35, v36, v35
	v_add_f32_e32 v36, 1.0, v43
	v_mul_f32_e32 v43, 0xbfb8aa3b, v37
	v_rcp_f32_e32 v36, v36
	v_exp_f32_e32 v43, v43
	v_cvt_pk_bf16_f32 v165, v34, v35
	v_fmac_f32_e32 v64, v97, v97
	v_mul_f32_e32 v36, v36, v42
	v_add_f32_e32 v42, 1.0, v43
	v_rcp_f32_e32 v42, v42
	v_and_b32_e32 v43, 0xffff0000, v183
	v_mul_f32_e32 v36, v36, v44
	v_fmac_f32_e32 v43, v96, v57
	v_mul_f32_e32 v37, v42, v37
	v_mul_f32_e32 v42, v35, v35
	v_fmac_f32_e32 v42, v34, v34
	v_mul_f32_e32 v34, 0x3fb8aa3b, v185
	v_exp_f32_e32 v163, v34
	v_lshlrev_b32_e32 v34, 16, v106
	v_mul_f32_e32 v35, 0xbfb8aa3b, v34
	v_exp_f32_e32 v35, v35
	v_mul_f32_e32 v37, v37, v43
	v_fmac_f32_e32 v42, v36, v36
	v_cvt_pk_bf16_f32 v166, v36, v37
	v_lshlrev_b32_e32 v36, 16, v102
	v_fmac_f32_e32 v36, v163, v70
	v_add_f32_e32 v35, 1.0, v35
	v_and_b32_e32 v70, 0xffff0000, v106
	v_fmac_f32_e32 v42, v37, v37
	v_rcp_f32_e32 v35, v35
	v_mul_f32_e32 v37, 0xbfb8aa3b, v70
	v_exp_f32_e32 v37, v37
	v_fmac_f32_e32 v64, v63, v63
	v_mul_f32_e32 v34, v35, v34
	v_mul_f32_e32 v176, v34, v36
	v_add_f32_e32 v34, 1.0, v37
	v_rcp_f32_e32 v106, v34
	v_mul_f32_e32 v34, 0xbfb8aa3b, v158
	v_exp_f32_e32 v159, v34
	v_lshl_add_u64 v[34:35], s[18:19], 0, v[92:93]
	s_lshl_b64 s[18:19], s[16:17], 9
	s_add_u32 s18, s26, s18
	s_addc_u32 s19, s27, s19
	s_lshl_b32 s16, s20, 7
	s_add_u32 s20, s24, s16
	s_addc_u32 s21, s25, 0
	v_fmac_f32_e32 v64, v62, v62
	v_lshl_add_u64 v[34:35], v[34:35], 0, v[74:75]
	s_add_u32 s22, s60, s16
	v_add_f32_e32 v64, v161, v64
	v_cvt_pk_bf16_f32 v161, v97, v100
	v_cvt_pk_bf16_f32 v162, v63, v62
	v_lshl_add_u64 v[62:63], v[34:35], 0, s[14:15]
	v_add_co_u32_e32 v34, vcc, s35, v34
	s_addc_u32 s23, s61, 0
	v_lshl_add_u64 v[100:101], s[20:21], 0, v[88:89]
	v_addc_co_u32_e32 v35, vcc, 0, v35, vcc
	v_lshl_add_u64 v[96:97], s[18:19], 0, v[86:87]
	v_mov_b64_e32 v[104:105], s[22:23]
	v_lshl_add_u64 v[100:101], v[100:101], 0, v[76:77]
	v_add_f32_e32 v177, v64, v42
	global_load_dwordx4 v[42:45], v[34:35], off
	s_nop 0
	global_load_dwordx4 v[34:37], v[62:63], off offset:48
	global_load_dwordx4 v[54:57], v[62:63], off offset:32
	s_nop 0
	global_load_dwordx4 v[62:65], v[62:63], off offset:16
	v_mad_u64_u32 v[108:109], s[18:19], v82, s28, v[104:105]
	global_load_dword v180, v[96:97], off
	global_load_dwordx2 v[174:175], v[100:101], off
	global_load_dwordx2 v[178:179], v[100:101], off offset:32
	global_load_dword v189, v[96:97], off offset:64
	v_mad_u64_u32 v[100:101], s[18:19], v84, s28, v[104:105]
	v_add_u32_e32 v109, v81, v109
	v_lshl_add_u64 v[96:97], s[20:21], 0, v[90:91]
	v_add_u32_e32 v101, v79, v101
	v_lshl_add_u64 v[108:109], v[108:109], 0, v[76:77]
	v_lshl_add_u64 v[96:97], v[96:97], 0, v[76:77]
	v_lshl_add_u64 v[100:101], v[100:101], 0, v[76:77]
	global_load_dwordx2 v[206:207], v[108:109], off
	global_load_dwordx2 v[208:209], v[108:109], off offset:32
	global_load_dwordx2 v[104:105], v[96:97], off
	s_nop 0
	global_load_dwordx2 v[96:97], v[96:97], off offset:32
	s_nop 0
	global_load_dwordx2 v[108:109], v[100:101], off
	s_nop 0
	global_load_dwordx2 v[100:101], v[100:101], off offset:32
	v_and_b32_e32 v102, 0xffff0000, v102
	v_fmac_f32_e32 v102, v163, v71
	v_mul_f32_e32 v70, v106, v70
	v_and_b32_e32 v71, 0xffff0000, v107
	v_mul_f32_e32 v181, v70, v102
	v_mul_f32_e32 v102, 0xbfb8aa3b, v71
	v_exp_f32_e32 v102, v102
	v_add_f32_e32 v70, 1.0, v159
	v_rcp_f32_e32 v70, v70
	v_lshlrev_b32_e32 v106, 16, v103
	v_fmac_f32_e32 v106, v163, v72
	v_add_f32_e32 v72, 1.0, v102
	v_rcp_f32_e32 v72, v72
	v_mul_f32_e32 v70, v70, v158
	v_mul_f32_e32 v182, v70, v106
	v_and_b32_e32 v70, 0xffff0000, v103
	v_fmac_f32_e32 v70, v163, v73
	v_mul_f32_e32 v71, v72, v71
	v_mul_f32_e32 v183, v71, v70
	s_waitcnt vmcnt(14)
	v_lshlrev_b32_e32 v70, 16, v98
	v_mul_f32_e32 v71, 0xbfb8aa3b, v70
	v_exp_f32_e32 v71, v71
	v_and_b32_e32 v73, 0xffff0000, v98
	v_mul_f32_e32 v98, 0xbfb8aa3b, v73
	v_exp_f32_e32 v98, v98
	v_add_f32_e32 v71, 1.0, v71
	v_rcp_f32_e32 v71, v71
	v_lshlrev_b32_e32 v72, 16, v94
	v_fmac_f32_e32 v72, v163, v66
	v_cvt_pk_bf16_f32 v49, v60, v61
	v_mul_f32_e32 v66, v71, v70
	v_mul_f32_e32 v185, v66, v72
	v_add_f32_e32 v66, 1.0, v98
	v_lshlrev_b32_e32 v70, 16, v99
	v_rcp_f32_e32 v66, v66
	v_mul_f32_e32 v71, 0xbfb8aa3b, v70
	v_exp_f32_e32 v71, v71
	v_and_b32_e32 v72, 0xffff0000, v94
	v_fmac_f32_e32 v72, v163, v67
	v_mul_f32_e32 v66, v66, v73
	v_add_f32_e32 v67, 1.0, v71
	v_mul_f32_e32 v186, v66, v72
	v_lshlrev_b32_e32 v66, 16, v95
	v_and_b32_e32 v94, 0xffff0000, v99
	v_rcp_f32_e32 v67, v67
	v_fmac_f32_e32 v66, v163, v68
	v_mul_f32_e32 v68, 0xbfb8aa3b, v94
	v_exp_f32_e32 v68, v68
	v_mul_f32_e32 v67, v67, v70
	v_mul_f32_e32 v187, v67, v66
	v_and_b32_e32 v95, 0xffff0000, v95
	v_add_f32_e32 v66, 1.0, v68
	v_cvt_pk_bf16_f32 v50, v50, v51
	v_cvt_pk_bf16_f32 v51, v52, v53
	v_cvt_pk_bf16_f32 v52, v38, v39
	v_cvt_pk_bf16_f32 v53, v40, v41
	v_fmac_f32_e32 v95, v163, v69
	v_rcp_f32_e32 v98, v66
	ds_write_b128 v128, v[46:49] offset:34816
	ds_write_b128 v128, v[50:53] offset:34832
	s_waitcnt lgkmcnt(0)
	s_barrier
	ds_read_b128 v[38:41], v129 offset:34816
	ds_read_b128 v[46:49], v129 offset:34880
	ds_read_b128 v[50:53], v129 offset:39168
	ds_read_b128 v[58:61], v129 offset:39232
	ds_read_b128 v[66:69], v129 offset:34944
	ds_read_b128 v[70:73], v129 offset:35008
	ds_read_b128 v[190:193], v129 offset:39296
	ds_read_b128 v[194:197], v129 offset:39360
	v_mul_f32_e32 v94, v98, v94
	v_mul_f32_e32 v188, v94, v95
	v_cvt_pk_bf16_f32 v159, v176, v181
	v_cvt_pk_bf16_f32 v158, v182, v183
	v_cvt_pk_bf16_f32 v164, v185, v186
	v_cvt_pk_bf16_f32 v163, v187, v188
	s_waitcnt lgkmcnt(7)
	v_mfma_f32_16x16x32_bf16 v[198:201], v[38:41], v[30:33], 0
	s_waitcnt vmcnt(5)
	v_lshlrev_b32_e32 v95, 16, v206
	v_mul_f32_e32 v98, 0xbfb8aa3b, v95
	v_exp_f32_e32 v98, v98
	s_waitcnt lgkmcnt(6)
	v_mfma_f32_16x16x32_bf16 v[198:201], v[46:49], v[22:25], v[198:201]
	v_and_b32_e32 v102, 0xffff0000, v206
	v_mul_f32_e32 v103, 0xbfb8aa3b, v102
	v_add_f32_e32 v98, 1.0, v98
	s_waitcnt lgkmcnt(3)
	v_mfma_f32_16x16x32_bf16 v[198:201], v[66:69], v[14:17], v[198:201]
	v_rcp_f32_e32 v98, v98
	v_exp_f32_e32 v103, v103
	v_mul_f32_e32 v94, 0x3fb8aa3b, v180
	v_exp_f32_e32 v94, v94
	s_waitcnt lgkmcnt(2)
	v_mfma_f32_16x16x32_bf16 v[198:201], v[70:73], v[6:9], v[198:201]
	v_mul_f32_e32 v95, v98, v95
	v_add_f32_e32 v98, 1.0, v103
	v_rcp_f32_e32 v98, v98
	v_lshlrev_b32_e32 v99, 16, v174
	v_mfma_f32_16x16x32_bf16 v[38:41], v[38:41], v[26:29], 0
	s_nop 2
	v_fmac_f32_e32 v99, v94, v198
	v_mul_f32_e32 v95, v95, v99
	v_and_b32_e32 v99, 0xffff0000, v174
	v_fmac_f32_e32 v99, v94, v199
	v_mul_f32_e32 v98, v98, v102
	v_mul_f32_e32 v98, v98, v99
	v_lshlrev_b32_e32 v99, 16, v207
	v_mul_f32_e32 v102, 0xbfb8aa3b, v99
	v_mfma_f32_16x16x32_bf16 v[38:41], v[46:49], v[18:21], v[38:41]
	v_exp_f32_e32 v102, v102
	v_lshlrev_b32_e32 v103, 16, v175
	v_fmac_f32_e32 v103, v94, v200
	v_mfma_f32_16x16x32_bf16 v[202:205], v[50:53], v[30:33], 0
	v_add_f32_e32 v102, 1.0, v102
	v_rcp_f32_e32 v102, v102
	v_and_b32_e32 v106, 0xffff0000, v207
	v_mfma_f32_16x16x32_bf16 v[50:53], v[50:53], v[26:29], 0
	v_mul_f32_e32 v107, 0xbfb8aa3b, v106
	s_or_b32 s20, s40, 5
	s_or_b32 s16, s39, s20
	v_mfma_f32_16x16x32_bf16 v[38:41], v[66:69], v[10:13], v[38:41]
	s_lshl_b64 s[18:19], s[16:17], 15
	s_add_u32 s18, s74, s18
	s_addc_u32 s19, s75, s19
	v_mfma_f32_16x16x32_bf16 v[202:205], v[58:61], v[22:25], v[202:205]
	v_cvt_pk_bf16_f32 v174, v95, v98
	v_cvt_pk_bf16_f32 v42, v42, v43
	v_cvt_pk_bf16_f32 v43, v44, v45
	v_mfma_f32_16x16x32_bf16 v[46:49], v[58:61], v[18:21], v[50:53]
	v_exp_f32_e32 v58, v107
	v_and_b32_e32 v60, 0xffff0000, v175
	v_fmac_f32_e32 v60, v94, v201
	v_mfma_f32_16x16x32_bf16 v[70:73], v[70:73], v[2:5], v[38:41]
	v_mul_f32_e32 v50, v102, v99
	v_mul_f32_e32 v59, v50, v103
	v_add_f32_e32 v58, 1.0, v58
	s_waitcnt vmcnt(4)
	v_lshlrev_b32_e32 v38, 16, v208
	v_mul_f32_e32 v39, 0xbfb8aa3b, v38
	v_exp_f32_e32 v39, v39
	s_waitcnt lgkmcnt(1)
	v_mfma_f32_16x16x32_bf16 v[50:53], v[190:193], v[14:17], v[202:205]
	v_and_b32_e32 v41, 0xffff0000, v208
	v_lshlrev_b32_e32 v40, 16, v178
	v_add_f32_e32 v39, 1.0, v39
	v_mfma_f32_16x16x32_bf16 v[46:49], v[190:193], v[10:13], v[46:49]
	v_rcp_f32_e32 v39, v39
	v_rcp_f32_e32 v58, v58
	v_cvt_pk_bf16_f32 v44, v62, v63
	s_waitcnt lgkmcnt(0)
	v_mfma_f32_16x16x32_bf16 v[50:53], v[194:197], v[6:9], v[50:53]
	v_mul_f32_e32 v38, v39, v38
	v_and_b32_e32 v39, 0xffff0000, v178
	v_mul_f32_e32 v58, v58, v106
	v_mfma_f32_16x16x32_bf16 v[66:69], v[194:197], v[2:5], v[46:49]
	v_mul_f32_e32 v58, v58, v60
	s_nop 2
	v_fmac_f32_e32 v40, v94, v50
	v_mul_f32_e32 v38, v38, v40
	v_mul_f32_e32 v46, 0xbfb8aa3b, v41
	v_exp_f32_e32 v46, v46
	v_fmac_f32_e32 v39, v94, v51
	v_mul_f32_e32 v60, v98, v98
	v_fmac_f32_e32 v60, v95, v95
	v_add_f32_e32 v40, 1.0, v46
	v_lshlrev_b32_e32 v46, 16, v209
	v_rcp_f32_e32 v40, v40
	v_mul_f32_e32 v47, 0xbfb8aa3b, v46
	v_exp_f32_e32 v47, v47
	v_fmac_f32_e32 v60, v59, v59
	v_mul_f32_e32 v40, v40, v41
	v_and_b32_e32 v41, 0xffff0000, v209
	v_mul_f32_e32 v39, v40, v39
	v_add_f32_e32 v40, 1.0, v47
	v_mul_f32_e32 v47, 0xbfb8aa3b, v41
	v_rcp_f32_e32 v40, v40
	v_exp_f32_e32 v47, v47
	v_fmac_f32_e32 v60, v58, v58
	v_lshlrev_b32_e32 v48, 16, v179
	v_mul_f32_e32 v40, v40, v46
	v_add_f32_e32 v46, 1.0, v47
	v_rcp_f32_e32 v46, v46
	v_and_b32_e32 v47, 0xffff0000, v179
	v_cvt_pk_bf16_f32 v179, v38, v39
	v_add_f32_e32 v60, v177, v60
	v_mul_f32_e32 v41, v46, v41
	v_mul_f32_e32 v46, v39, v39
	v_fmac_f32_e32 v46, v38, v38
	v_mul_f32_e32 v38, 0x3fb8aa3b, v189
	v_exp_f32_e32 v177, v38
	s_waitcnt vmcnt(1)
	v_lshlrev_b32_e32 v38, 16, v108
	v_mul_f32_e32 v39, 0xbfb8aa3b, v38
	v_exp_f32_e32 v39, v39
	v_fmac_f32_e32 v48, v94, v52
	v_mul_f32_e32 v40, v40, v48
	v_fmac_f32_e32 v47, v94, v53
	v_mul_f32_e32 v41, v41, v47
	v_fmac_f32_e32 v46, v40, v40
	v_cvt_pk_bf16_f32 v180, v40, v41
	v_lshlrev_b32_e32 v40, 16, v104
	v_fmac_f32_e32 v40, v177, v70
	v_add_f32_e32 v39, 1.0, v39
	v_and_b32_e32 v70, 0xffff0000, v108
	v_fmac_f32_e32 v46, v41, v41
	v_rcp_f32_e32 v39, v39
	v_mul_f32_e32 v41, 0xbfb8aa3b, v70
	v_exp_f32_e32 v41, v41
	v_lshlrev_b32_e32 v178, 16, v109
	v_mul_f32_e32 v38, v39, v38
	v_mul_f32_e32 v191, v38, v40
	v_add_f32_e32 v38, 1.0, v41
	v_rcp_f32_e32 v108, v38
	v_mul_f32_e32 v38, 0xbfb8aa3b, v178
	v_exp_f32_e32 v189, v38
	v_lshl_add_u64 v[38:39], s[18:19], 0, v[92:93]
	s_lshl_b64 s[18:19], s[16:17], 9
	s_add_u32 s18, s26, s18
	s_addc_u32 s19, s27, s19
	s_lshl_b32 s16, s20, 7
	s_add_u32 s20, s24, s16
	s_addc_u32 s21, s25, 0
	v_lshl_add_u64 v[38:39], v[38:39], 0, v[74:75]
	s_add_u32 s22, s60, s16
	v_cvt_pk_bf16_f32 v175, v59, v58
	v_lshl_add_u64 v[58:59], v[38:39], 0, s[14:15]
	v_add_co_u32_e32 v38, vcc, s35, v38
	s_addc_u32 s23, s61, 0
	v_lshl_add_u64 v[98:99], s[20:21], 0, v[88:89]
	v_addc_co_u32_e32 v39, vcc, 0, v39, vcc
	v_lshl_add_u64 v[94:95], s[18:19], 0, v[86:87]
	v_mov_b64_e32 v[102:103], s[22:23]
	v_lshl_add_u64 v[98:99], v[98:99], 0, v[76:77]
	v_add_f32_e32 v190, v60, v46
	global_load_dwordx4 v[46:49], v[38:39], off
	s_nop 0
	global_load_dwordx4 v[38:41], v[58:59], off offset:48
	global_load_dwordx4 v[50:53], v[58:59], off offset:32
	s_nop 0
	global_load_dwordx4 v[58:61], v[58:59], off offset:16
	v_mad_u64_u32 v[106:107], s[18:19], v82, s28, v[102:103]
	global_load_dword v201, v[94:95], off
	global_load_dwordx2 v[192:193], v[98:99], off
	global_load_dwordx2 v[218:219], v[98:99], off offset:32
	global_load_dword v224, v[94:95], off offset:64
	v_mad_u64_u32 v[98:99], s[18:19], v84, s28, v[102:103]
	v_add_u32_e32 v107, v81, v107
	v_lshl_add_u64 v[94:95], s[20:21], 0, v[90:91]
	v_add_u32_e32 v99, v79, v99
	v_lshl_add_u64 v[106:107], v[106:107], 0, v[76:77]
	v_lshl_add_u64 v[94:95], v[94:95], 0, v[76:77]
	v_lshl_add_u64 v[98:99], v[98:99], 0, v[76:77]
	global_load_dwordx2 v[220:221], v[106:107], off
	global_load_dwordx2 v[222:223], v[106:107], off offset:32
	global_load_dwordx2 v[102:103], v[94:95], off
	s_nop 0
	global_load_dwordx2 v[94:95], v[94:95], off offset:32
	s_nop 0
	global_load_dwordx2 v[106:107], v[98:99], off
	s_nop 0
	global_load_dwordx2 v[98:99], v[98:99], off offset:32
	v_and_b32_e32 v104, 0xffff0000, v104
	v_fmac_f32_e32 v104, v177, v71
	v_mul_f32_e32 v70, v108, v70
	v_and_b32_e32 v71, 0xffff0000, v109
	v_mul_f32_e32 v194, v70, v104
	v_mul_f32_e32 v104, 0xbfb8aa3b, v71
	v_exp_f32_e32 v104, v104
	v_add_f32_e32 v70, 1.0, v189
	v_rcp_f32_e32 v70, v70
	v_lshlrev_b32_e32 v108, 16, v105
	v_fmac_f32_e32 v108, v177, v72
	v_add_f32_e32 v72, 1.0, v104
	v_rcp_f32_e32 v72, v72
	v_mul_f32_e32 v70, v70, v178
	v_mul_f32_e32 v195, v70, v108
	v_and_b32_e32 v70, 0xffff0000, v105
	v_fmac_f32_e32 v70, v177, v73
	v_mul_f32_e32 v71, v72, v71
	v_mul_f32_e32 v196, v71, v70
	s_waitcnt vmcnt(14)
	v_lshlrev_b32_e32 v70, 16, v100
	v_mul_f32_e32 v71, 0xbfb8aa3b, v70
	v_exp_f32_e32 v71, v71
	v_and_b32_e32 v73, 0xffff0000, v100
	v_mul_f32_e32 v100, 0xbfb8aa3b, v73
	v_exp_f32_e32 v100, v100
	v_add_f32_e32 v71, 1.0, v71
	v_rcp_f32_e32 v71, v71
	v_lshlrev_b32_e32 v72, 16, v96
	v_fmac_f32_e32 v72, v177, v66
	v_cvt_pk_bf16_f32 v45, v64, v65
	v_mul_f32_e32 v66, v71, v70
	v_mul_f32_e32 v197, v66, v72
	v_add_f32_e32 v66, 1.0, v100
	v_lshlrev_b32_e32 v70, 16, v101
	v_rcp_f32_e32 v66, v66
	v_mul_f32_e32 v71, 0xbfb8aa3b, v70
	v_exp_f32_e32 v71, v71
	v_and_b32_e32 v72, 0xffff0000, v96
	v_fmac_f32_e32 v72, v177, v67
	v_mul_f32_e32 v66, v66, v73
	v_add_f32_e32 v67, 1.0, v71
	v_mul_f32_e32 v198, v66, v72
	v_lshlrev_b32_e32 v66, 16, v97
	v_and_b32_e32 v96, 0xffff0000, v101
	v_rcp_f32_e32 v67, v67
	v_fmac_f32_e32 v66, v177, v68
	v_mul_f32_e32 v68, 0xbfb8aa3b, v96
	v_exp_f32_e32 v68, v68
	v_mul_f32_e32 v67, v67, v70
	v_mul_f32_e32 v199, v67, v66
	v_and_b32_e32 v97, 0xffff0000, v97
	v_add_f32_e32 v66, 1.0, v68
	v_cvt_pk_bf16_f32 v54, v54, v55
	v_cvt_pk_bf16_f32 v55, v56, v57
	v_cvt_pk_bf16_f32 v56, v34, v35
	v_cvt_pk_bf16_f32 v57, v36, v37
	v_fmac_f32_e32 v97, v177, v69
	v_rcp_f32_e32 v100, v66
	ds_write_b128 v128, v[42:45] offset:52224
	ds_write_b128 v128, v[54:57] offset:52240
	s_waitcnt lgkmcnt(0)
	s_barrier
	ds_read_b128 v[34:37], v129 offset:52224
	ds_read_b128 v[42:45], v129 offset:52288
	ds_read_b128 v[54:57], v129 offset:56576
	ds_read_b128 v[62:65], v129 offset:56640
	ds_read_b128 v[66:69], v129 offset:52352
	ds_read_b128 v[70:73], v129 offset:52416
	ds_read_b128 v[202:205], v129 offset:56704
	ds_read_b128 v[206:209], v129 offset:56768
	v_mul_f32_e32 v96, v100, v96
	v_mul_f32_e32 v200, v96, v97
	v_cvt_pk_bf16_f32 v109, v191, v194
	v_cvt_pk_bf16_f32 v108, v195, v196
	v_cvt_pk_bf16_f32 v178, v197, v198
	v_cvt_pk_bf16_f32 v177, v199, v200
	s_waitcnt lgkmcnt(7)
	v_mfma_f32_16x16x32_bf16 v[210:213], v[34:37], v[30:33], 0
	s_waitcnt vmcnt(5)
	v_lshlrev_b32_e32 v97, 16, v220
	v_mul_f32_e32 v100, 0xbfb8aa3b, v97
	v_exp_f32_e32 v100, v100
	s_waitcnt lgkmcnt(6)
	v_mfma_f32_16x16x32_bf16 v[210:213], v[42:45], v[22:25], v[210:213]
	v_and_b32_e32 v104, 0xffff0000, v220
	v_mul_f32_e32 v105, 0xbfb8aa3b, v104
	v_add_f32_e32 v100, 1.0, v100
	s_waitcnt lgkmcnt(3)
	v_mfma_f32_16x16x32_bf16 v[210:213], v[66:69], v[14:17], v[210:213]
	v_rcp_f32_e32 v100, v100
	v_exp_f32_e32 v105, v105
	v_mul_f32_e32 v96, 0x3fb8aa3b, v201
	v_exp_f32_e32 v96, v96
	s_waitcnt lgkmcnt(2)
	v_mfma_f32_16x16x32_bf16 v[210:213], v[70:73], v[6:9], v[210:213]
	v_mul_f32_e32 v97, v100, v97
	v_add_f32_e32 v100, 1.0, v105
	v_rcp_f32_e32 v100, v100
	v_lshlrev_b32_e32 v101, 16, v192
	v_mfma_f32_16x16x32_bf16 v[34:37], v[34:37], v[26:29], 0
	s_nop 2
	v_fmac_f32_e32 v101, v96, v210
	v_mul_f32_e32 v97, v97, v101
	v_and_b32_e32 v101, 0xffff0000, v192
	v_fmac_f32_e32 v101, v96, v211
	v_mul_f32_e32 v100, v100, v104
	v_mul_f32_e32 v100, v100, v101
	v_lshlrev_b32_e32 v101, 16, v221
	v_mul_f32_e32 v104, 0xbfb8aa3b, v101
	v_mfma_f32_16x16x32_bf16 v[34:37], v[42:45], v[18:21], v[34:37]
	v_exp_f32_e32 v104, v104
	v_lshlrev_b32_e32 v105, 16, v193
	v_fmac_f32_e32 v105, v96, v212
	v_mfma_f32_16x16x32_bf16 v[214:217], v[54:57], v[30:33], 0
	v_add_f32_e32 v104, 1.0, v104
	v_rcp_f32_e32 v104, v104
	v_and_b32_e32 v189, 0xffff0000, v221
	v_mfma_f32_16x16x32_bf16 v[54:57], v[54:57], v[26:29], 0
	v_mul_f32_e32 v192, 0xbfb8aa3b, v189
	s_or_b32 s20, s40, 6
	s_or_b32 s16, s39, s20
	v_mfma_f32_16x16x32_bf16 v[34:37], v[66:69], v[10:13], v[34:37]
	s_lshl_b64 s[18:19], s[16:17], 15
	s_add_u32 s18, s74, s18
	s_addc_u32 s19, s75, s19
	v_mfma_f32_16x16x32_bf16 v[214:217], v[62:65], v[22:25], v[214:217]
	v_cvt_pk_bf16_f32 v46, v46, v47
	v_cvt_pk_bf16_f32 v47, v48, v49
	v_cvt_pk_bf16_f32 v48, v58, v59
	v_mfma_f32_16x16x32_bf16 v[42:45], v[62:65], v[18:21], v[54:57]
	v_exp_f32_e32 v62, v192
	v_and_b32_e32 v64, 0xffff0000, v193
	v_fmac_f32_e32 v64, v96, v213
	v_mfma_f32_16x16x32_bf16 v[70:73], v[70:73], v[2:5], v[34:37]
	v_mul_f32_e32 v54, v104, v101
	v_mul_f32_e32 v63, v54, v105
	v_add_f32_e32 v62, 1.0, v62
	s_waitcnt vmcnt(4)
	v_lshlrev_b32_e32 v34, 16, v222
	v_mul_f32_e32 v35, 0xbfb8aa3b, v34
	v_exp_f32_e32 v35, v35
	s_waitcnt lgkmcnt(1)
	v_mfma_f32_16x16x32_bf16 v[54:57], v[202:205], v[14:17], v[214:217]
	v_and_b32_e32 v37, 0xffff0000, v222
	v_lshlrev_b32_e32 v36, 16, v218
	v_add_f32_e32 v35, 1.0, v35
	v_mfma_f32_16x16x32_bf16 v[42:45], v[202:205], v[10:13], v[42:45]
	v_rcp_f32_e32 v35, v35
	v_rcp_f32_e32 v62, v62
	s_waitcnt vmcnt(1)
	v_lshlrev_b32_e32 v204, 16, v107
	s_waitcnt lgkmcnt(0)
	v_mfma_f32_16x16x32_bf16 v[54:57], v[206:209], v[6:9], v[54:57]
	v_mul_f32_e32 v34, v35, v34
	v_and_b32_e32 v35, 0xffff0000, v218
	v_mul_f32_e32 v62, v62, v189
	v_mfma_f32_16x16x32_bf16 v[66:69], v[206:209], v[2:5], v[42:45]
	v_mul_f32_e32 v62, v62, v64
	s_nop 2
	v_fmac_f32_e32 v36, v96, v54
	v_mul_f32_e32 v34, v34, v36
	v_mul_f32_e32 v42, 0xbfb8aa3b, v37
	v_exp_f32_e32 v42, v42
	v_fmac_f32_e32 v35, v96, v55
	v_lshlrev_b32_e32 v44, 16, v219
	v_fmac_f32_e32 v44, v96, v56
	v_add_f32_e32 v36, 1.0, v42
	v_lshlrev_b32_e32 v42, 16, v223
	v_rcp_f32_e32 v36, v36
	v_mul_f32_e32 v43, 0xbfb8aa3b, v42
	v_exp_f32_e32 v43, v43
	v_mul_f32_e32 v64, v100, v100
	v_mul_f32_e32 v36, v36, v37
	v_and_b32_e32 v37, 0xffff0000, v223
	v_mul_f32_e32 v35, v36, v35
	v_add_f32_e32 v36, 1.0, v43
	v_mul_f32_e32 v43, 0xbfb8aa3b, v37
	v_rcp_f32_e32 v36, v36
	v_exp_f32_e32 v43, v43
	v_cvt_pk_bf16_f32 v192, v34, v35
	v_fmac_f32_e32 v64, v97, v97
	v_mul_f32_e32 v36, v36, v42
	v_add_f32_e32 v42, 1.0, v43
	v_rcp_f32_e32 v42, v42
	v_and_b32_e32 v43, 0xffff0000, v219
	v_mul_f32_e32 v36, v36, v44
	v_fmac_f32_e32 v43, v96, v57
	v_mul_f32_e32 v37, v42, v37
	v_mul_f32_e32 v42, v35, v35
	v_fmac_f32_e32 v42, v34, v34
	v_mul_f32_e32 v34, 0x3fb8aa3b, v224
	v_exp_f32_e32 v202, v34
	v_lshlrev_b32_e32 v34, 16, v106
	v_mul_f32_e32 v35, 0xbfb8aa3b, v34
	v_exp_f32_e32 v35, v35
	v_mul_f32_e32 v37, v37, v43
	v_fmac_f32_e32 v42, v36, v36
	v_cvt_pk_bf16_f32 v193, v36, v37
	v_lshlrev_b32_e32 v36, 16, v102
	v_fmac_f32_e32 v36, v202, v70
	v_add_f32_e32 v35, 1.0, v35
	v_and_b32_e32 v70, 0xffff0000, v106
	v_fmac_f32_e32 v42, v37, v37
	v_rcp_f32_e32 v35, v35
	v_mul_f32_e32 v37, 0xbfb8aa3b, v70
	v_exp_f32_e32 v37, v37
	v_fmac_f32_e32 v64, v63, v63
	v_mul_f32_e32 v34, v35, v34
	v_mul_f32_e32 v106, v34, v36
	v_add_f32_e32 v34, 1.0, v37
	v_rcp_f32_e32 v203, v34
	v_mul_f32_e32 v34, 0xbfb8aa3b, v204
	v_exp_f32_e32 v205, v34
	v_lshl_add_u64 v[34:35], s[18:19], 0, v[92:93]
	s_lshl_b64 s[18:19], s[16:17], 9
	s_add_u32 s18, s26, s18
	s_addc_u32 s19, s27, s19
	s_lshl_b32 s16, s20, 7
	s_add_u32 s20, s24, s16
	s_addc_u32 s21, s25, 0
	v_fmac_f32_e32 v64, v62, v62
	v_lshl_add_u64 v[34:35], v[34:35], 0, v[74:75]
	s_add_u32 s22, s60, s16
	v_add_f32_e32 v64, v190, v64
	v_cvt_pk_bf16_f32 v189, v97, v100
	v_cvt_pk_bf16_f32 v190, v63, v62
	v_lshl_add_u64 v[62:63], v[34:35], 0, s[14:15]
	v_add_co_u32_e32 v34, vcc, s35, v34
	s_addc_u32 s23, s61, 0
	v_lshl_add_u64 v[96:97], s[20:21], 0, v[88:89]
	v_addc_co_u32_e32 v35, vcc, 0, v35, vcc
	v_lshl_add_u64 v[92:93], s[18:19], 0, v[86:87]
	v_mov_b64_e32 v[100:101], s[22:23]
	v_lshl_add_u64 v[96:97], v[96:97], 0, v[76:77]
	v_add_f32_e32 v201, v64, v42
	global_load_dwordx4 v[42:45], v[34:35], off
	s_nop 0
	global_load_dwordx4 v[34:37], v[62:63], off offset:48
	global_load_dwordx4 v[54:57], v[62:63], off offset:32
	s_nop 0
	global_load_dwordx4 v[62:65], v[62:63], off offset:16
	v_mad_u64_u32 v[104:105], s[18:19], v82, s28, v[100:101]
	global_load_dword v222, v[92:93], off
	global_load_dwordx2 v[230:231], v[96:97], off
	global_load_dwordx2 v[232:233], v[96:97], off offset:32
	global_load_dword v238, v[92:93], off offset:64
	v_mad_u64_u32 v[96:97], s[18:19], v84, s28, v[100:101]
	v_add_u32_e32 v105, v81, v105
	v_lshl_add_u64 v[92:93], s[20:21], 0, v[90:91]
	v_add_u32_e32 v97, v79, v97
	v_lshl_add_u64 v[104:105], v[104:105], 0, v[76:77]
	v_lshl_add_u64 v[92:93], v[92:93], 0, v[76:77]
	v_lshl_add_u64 v[96:97], v[96:97], 0, v[76:77]
	global_load_dwordx2 v[234:235], v[104:105], off
	global_load_dwordx2 v[236:237], v[104:105], off offset:32
	global_load_dwordx2 v[100:101], v[92:93], off
	s_nop 0
	global_load_dwordx2 v[92:93], v[92:93], off offset:32
	s_nop 0
	global_load_dwordx2 v[104:105], v[96:97], off
	s_nop 0
	global_load_dwordx2 v[96:97], v[96:97], off offset:32
	v_and_b32_e32 v102, 0xffff0000, v102
	v_fmac_f32_e32 v102, v202, v71
	v_mul_f32_e32 v70, v203, v70
	v_and_b32_e32 v71, 0xffff0000, v107
	v_mul_f32_e32 v74, v70, v102
	v_mul_f32_e32 v102, 0xbfb8aa3b, v71
	v_exp_f32_e32 v102, v102
	v_add_f32_e32 v70, 1.0, v205
	v_rcp_f32_e32 v70, v70
	v_lshlrev_b32_e32 v107, 16, v103
	v_fmac_f32_e32 v107, v202, v72
	v_add_f32_e32 v72, 1.0, v102
	v_rcp_f32_e32 v72, v72
	v_mul_f32_e32 v70, v70, v204
	v_mul_f32_e32 v102, v70, v107
	v_and_b32_e32 v70, 0xffff0000, v103
	v_fmac_f32_e32 v70, v202, v73
	v_mul_f32_e32 v71, v72, v71
	s_waitcnt vmcnt(14)
	v_lshlrev_b32_e32 v72, 16, v98
	v_mul_f32_e32 v103, v71, v70
	v_mul_f32_e32 v70, 0xbfb8aa3b, v72
	v_exp_f32_e32 v73, v70
	v_and_b32_e32 v98, 0xffff0000, v98
	v_mul_f32_e32 v203, 0xbfb8aa3b, v98
	v_exp_f32_e32 v203, v203
	v_add_f32_e32 v73, 1.0, v73
	v_rcp_f32_e32 v73, v73
	v_lshlrev_b32_e32 v107, 16, v94
	v_fmac_f32_e32 v107, v202, v66
	v_and_b32_e32 v94, 0xffff0000, v94
	v_mul_f32_e32 v66, v73, v72
	v_lshlrev_b32_e32 v73, 16, v99
	v_mul_f32_e32 v66, v66, v107
	v_add_f32_e32 v72, 1.0, v203
	v_mul_f32_e32 v107, 0xbfb8aa3b, v73
	v_rcp_f32_e32 v72, v72
	v_exp_f32_e32 v107, v107
	v_fmac_f32_e32 v94, v202, v67
	v_cvt_pk_bf16_f32 v49, v60, v61
	v_mul_f32_e32 v67, v72, v98
	v_add_f32_e32 v72, 1.0, v107
	v_rcp_f32_e32 v72, v72
	v_mul_f32_e32 v67, v67, v94
	v_lshlrev_b32_e32 v94, 16, v95
	v_fmac_f32_e32 v94, v202, v68
	v_mul_f32_e32 v68, v72, v73
	v_and_b32_e32 v72, 0xffff0000, v99
	v_mul_f32_e32 v73, 0xbfb8aa3b, v72
	v_mul_f32_e32 v68, v68, v94
	v_and_b32_e32 v94, 0xffff0000, v95
	v_cvt_pk_bf16_f32 v50, v50, v51
	v_cvt_pk_bf16_f32 v51, v52, v53
	v_cvt_pk_bf16_f32 v52, v38, v39
	v_cvt_pk_bf16_f32 v53, v40, v41
	v_exp_f32_e32 v73, v73
	v_fmac_f32_e32 v94, v202, v69
	ds_write_b128 v128, v[46:49] offset:34816
	ds_write_b128 v128, v[50:53] offset:34832
	s_waitcnt lgkmcnt(0)
	s_barrier
	ds_read_b128 v[38:41], v129 offset:34816
	ds_read_b128 v[46:49], v129 offset:34880
	ds_read_b128 v[50:53], v129 offset:39168
	ds_read_b128 v[202:205], v129 offset:39232
	ds_read_b128 v[206:209], v129 offset:34944
	ds_read_b128 v[210:213], v129 offset:35008
	ds_read_b128 v[214:217], v129 offset:39296
	ds_read_b128 v[218:221], v129 offset:39360
	v_add_f32_e32 v69, 1.0, v73
	v_rcp_f32_e32 v69, v69
	v_cvt_pk_bf16_f32 v71, v106, v74
	v_cvt_pk_bf16_f32 v70, v102, v103
	v_cvt_pk_bf16_f32 v73, v66, v67
	s_nop 0
	v_mul_f32_e32 v58, v69, v72
	v_mul_f32_e32 v58, v58, v94
	v_cvt_pk_bf16_f32 v72, v68, v58
	s_waitcnt vmcnt(9)
	v_mul_f32_e32 v59, 0x3fb8aa3b, v222
	s_waitcnt lgkmcnt(7)
	v_mfma_f32_16x16x32_bf16 v[222:225], v[38:41], v[30:33], 0
	s_waitcnt vmcnt(5)
	v_lshlrev_b32_e32 v60, 16, v234
	v_mul_f32_e32 v61, 0xbfb8aa3b, v60
	v_exp_f32_e32 v61, v61
	s_waitcnt lgkmcnt(6)
	v_mfma_f32_16x16x32_bf16 v[222:225], v[46:49], v[22:25], v[222:225]
	v_and_b32_e32 v94, 0xffff0000, v234
	v_mul_f32_e32 v95, 0xbfb8aa3b, v94
	v_add_f32_e32 v61, 1.0, v61
	s_waitcnt lgkmcnt(3)
	v_mfma_f32_16x16x32_bf16 v[222:225], v[206:209], v[14:17], v[222:225]
	v_rcp_f32_e32 v61, v61
	v_exp_f32_e32 v95, v95
	v_exp_f32_e32 v59, v59
	s_waitcnt lgkmcnt(2)
	v_mfma_f32_16x16x32_bf16 v[222:225], v[210:213], v[6:9], v[222:225]
	v_mul_f32_e32 v60, v61, v60
	v_add_f32_e32 v61, 1.0, v95
	v_rcp_f32_e32 v61, v61
	v_lshlrev_b32_e32 v69, 16, v230
	v_and_b32_e32 v98, 0xffff0000, v235
	s_nop 2
	v_fmac_f32_e32 v69, v59, v222
	v_mul_f32_e32 v60, v60, v69
	v_and_b32_e32 v69, 0xffff0000, v230
	v_fmac_f32_e32 v69, v59, v223
	v_mul_f32_e32 v61, v61, v94
	v_mul_f32_e32 v61, v61, v69
	v_lshlrev_b32_e32 v69, 16, v235
	v_mul_f32_e32 v94, 0xbfb8aa3b, v69
	v_exp_f32_e32 v94, v94
	v_mul_f32_e32 v99, 0xbfb8aa3b, v98
	v_mfma_f32_16x16x32_bf16 v[226:229], v[50:53], v[30:33], 0
	v_exp_f32_e32 v99, v99
	v_add_f32_e32 v94, 1.0, v94
	v_rcp_f32_e32 v94, v94
	v_mfma_f32_16x16x32_bf16 v[38:41], v[38:41], v[26:29], 0
	v_lshlrev_b32_e32 v95, 16, v231
	v_fmac_f32_e32 v95, v59, v224
	s_or_b32 s18, s40, 7
	v_mfma_f32_16x16x32_bf16 v[50:53], v[50:53], v[26:29], 0
	s_or_b32 s16, s39, s18
	s_lshl_b64 s[16:17], s[16:17], 9
	s_add_u32 s16, s26, s16
	v_mfma_f32_16x16x32_bf16 v[38:41], v[46:49], v[18:21], v[38:41]
	s_addc_u32 s17, s27, s17
	s_lshl_b32 s20, s18, 7
	s_add_u32 s18, s24, s20
	v_mfma_f32_16x16x32_bf16 v[46:49], v[202:205], v[18:21], v[50:53]
	s_addc_u32 s19, s25, 0
	s_add_u32 s20, s60, s20
	s_addc_u32 s21, s61, 0
	v_mul_f32_e32 v50, v94, v69
	v_add_f32_e32 v94, 1.0, v99
	v_rcp_f32_e32 v94, v94
	v_mul_f32_e32 v69, v50, v95
	v_and_b32_e32 v95, 0xffff0000, v231
	v_fmac_f32_e32 v95, v59, v225
	v_mul_f32_e32 v94, v94, v98
	v_mul_f32_e32 v95, v94, v95
	v_mul_f32_e32 v94, v61, v61
	v_mfma_f32_16x16x32_bf16 v[38:41], v[206:209], v[10:13], v[38:41]
	v_fmac_f32_e32 v94, v60, v60
	v_fmac_f32_e32 v94, v69, v69
	v_fmac_f32_e32 v94, v95, v95
	v_mfma_f32_16x16x32_bf16 v[226:229], v[202:205], v[22:25], v[226:229]
	v_add_f32_e32 v98, v201, v94
	v_cvt_pk_bf16_f32 v94, v60, v61
	s_waitcnt vmcnt(4)
	v_lshlrev_b32_e32 v60, 16, v236
	s_waitcnt lgkmcnt(1)
	v_mfma_f32_16x16x32_bf16 v[46:49], v[214:217], v[10:13], v[46:49]
	v_cvt_pk_bf16_f32 v95, v69, v95
	v_cvt_pk_bf16_f32 v42, v42, v43
	v_cvt_pk_bf16_f32 v43, v44, v45
	v_mfma_f32_16x16x32_bf16 v[202:205], v[210:213], v[2:5], v[38:41]
	v_cvt_pk_bf16_f32 v44, v62, v63
	v_cvt_pk_bf16_f32 v45, v64, v65
	v_cvt_pk_bf16_f32 v54, v54, v55
	v_mfma_f32_16x16x32_bf16 v[50:53], v[214:217], v[14:17], v[226:229]
	v_cvt_pk_bf16_f32 v55, v56, v57
	s_nop 1
	v_mul_f32_e32 v38, 0xbfb8aa3b, v60
	v_exp_f32_e32 v61, v38
	s_waitcnt lgkmcnt(0)
	v_mfma_f32_16x16x32_bf16 v[38:41], v[218:221], v[2:5], v[46:49]
	v_cvt_pk_bf16_f32 v56, v34, v35
	v_cvt_pk_bf16_f32 v57, v36, v37
	v_mfma_f32_16x16x32_bf16 v[50:53], v[218:221], v[6:9], v[50:53]
	s_nop 1
	v_and_b32_e32 v48, 0xffff0000, v236
	v_mul_f32_e32 v49, 0xbfb8aa3b, v48
	v_add_f32_e32 v47, 1.0, v61
	v_exp_f32_e32 v49, v49
	v_rcp_f32_e32 v47, v47
	v_lshlrev_b32_e32 v46, 16, v232
	v_fmac_f32_e32 v46, v59, v50
	v_add_f32_e32 v49, 1.0, v49
	v_lshlrev_b32_e32 v50, 16, v237
	v_mul_f32_e32 v47, v47, v60
	v_rcp_f32_e32 v49, v49
	v_mul_f32_e32 v60, 0xbfb8aa3b, v50
	v_exp_f32_e32 v60, v60
	v_mul_f32_e32 v46, v47, v46
	v_and_b32_e32 v47, 0xffff0000, v232
	v_fmac_f32_e32 v47, v59, v51
	v_mul_f32_e32 v48, v49, v48
	v_and_b32_e32 v49, 0xffff0000, v237
	v_mul_f32_e32 v47, v48, v47
	v_add_f32_e32 v48, 1.0, v60
	v_mul_f32_e32 v51, 0xbfb8aa3b, v49
	v_rcp_f32_e32 v48, v48
	v_exp_f32_e32 v51, v51
	v_lshlrev_b32_e32 v60, 16, v233
	v_fmac_f32_e32 v60, v59, v52
	v_mul_f32_e32 v48, v48, v50
	v_add_f32_e32 v50, 1.0, v51
	v_rcp_f32_e32 v50, v50
	v_and_b32_e32 v51, 0xffff0000, v233
	v_mul_f32_e32 v48, v48, v60
	v_fmac_f32_e32 v51, v59, v53
	v_mul_f32_e32 v49, v50, v49
	v_mul_f32_e32 v50, v47, v47
	v_fmac_f32_e32 v50, v46, v46
	v_mul_f32_e32 v49, v49, v51
	v_fmac_f32_e32 v50, v48, v48
	v_fmac_f32_e32 v50, v49, v49
	v_add_f32_e32 v107, v98, v50
	v_cvt_pk_bf16_f32 v98, v46, v47
	v_mul_f32_e32 v46, 0x3fb8aa3b, v238
	v_exp_f32_e32 v201, v46
	s_waitcnt vmcnt(1)
	v_lshlrev_b32_e32 v46, 16, v104
	v_mul_f32_e32 v47, 0xbfb8aa3b, v46
	v_exp_f32_e32 v47, v47
	v_and_b32_e32 v60, 0xffff0000, v104
	v_cvt_pk_bf16_f32 v99, v48, v49
	v_mul_f32_e32 v49, 0xbfb8aa3b, v60
	v_add_f32_e32 v47, 1.0, v47
	v_rcp_f32_e32 v47, v47
	v_exp_f32_e32 v49, v49
	v_lshlrev_b32_e32 v48, 16, v100
	v_fmac_f32_e32 v48, v201, v202
	v_mul_f32_e32 v46, v47, v46
	v_mul_f32_e32 v59, v46, v48
	v_and_b32_e32 v61, 0xffff0000, v100
	v_add_f32_e32 v46, 1.0, v49
	v_lshlrev_b32_e32 v100, 16, v105
	v_rcp_f32_e32 v69, v46
	v_mul_f32_e32 v46, 0xbfb8aa3b, v100
	v_lshl_add_u64 v[48:49], s[18:19], 0, v[88:89]
	v_exp_f32_e32 v104, v46
	v_lshl_add_u64 v[46:47], s[16:17], 0, v[86:87]
	v_mov_b64_e32 v[50:51], s[20:21]
	v_lshl_add_u64 v[48:49], v[48:49], 0, v[76:77]
	v_mad_u64_u32 v[52:53], s[16:17], v82, s28, v[50:51]
	global_load_dword v218, v[46:47], off
	global_load_dwordx2 v[222:223], v[48:49], off
	global_load_dwordx2 v[224:225], v[48:49], off offset:32
	global_load_dword v230, v[46:47], off offset:64
	v_mad_u64_u32 v[48:49], s[16:17], v84, s28, v[50:51]
	v_add_u32_e32 v53, v81, v53
	v_lshl_add_u64 v[46:47], s[18:19], 0, v[90:91]
	v_add_u32_e32 v49, v79, v49
	v_lshl_add_u64 v[52:53], v[52:53], 0, v[76:77]
	v_lshl_add_u64 v[46:47], v[46:47], 0, v[76:77]
	v_lshl_add_u64 v[48:49], v[48:49], 0, v[76:77]
	global_load_dwordx2 v[226:227], v[52:53], off
	global_load_dwordx2 v[228:229], v[52:53], off offset:32
	global_load_dwordx2 v[50:51], v[46:47], off
	s_nop 0
	global_load_dwordx2 v[46:47], v[46:47], off offset:32
	s_nop 0
	global_load_dwordx2 v[52:53], v[48:49], off
	s_nop 0
	global_load_dwordx2 v[48:49], v[48:49], off offset:32
	v_mul_f32_e32 v60, v69, v60
	v_and_b32_e32 v69, 0xffff0000, v105
	v_mul_f32_e32 v77, 0xbfb8aa3b, v69
	v_exp_f32_e32 v77, v77
	v_fmac_f32_e32 v61, v201, v203
	v_mul_f32_e32 v60, v60, v61
	v_add_f32_e32 v61, 1.0, v104
	v_rcp_f32_e32 v61, v61
	v_add_f32_e32 v77, 1.0, v77
	v_rcp_f32_e32 v77, v77
	v_lshlrev_b32_e32 v86, 16, v101
	v_fmac_f32_e32 v86, v201, v204
	v_mul_f32_e32 v61, v61, v100
	v_mul_f32_e32 v61, v61, v86
	v_and_b32_e32 v86, 0xffff0000, v101
	v_fmac_f32_e32 v86, v201, v205
	v_mul_f32_e32 v69, v77, v69
	s_waitcnt vmcnt(10)
	v_lshlrev_b32_e32 v77, 16, v96
	v_mul_f32_e32 v69, v69, v86
	v_mul_f32_e32 v86, 0xbfb8aa3b, v77
	v_exp_f32_e32 v88, v86
	v_and_b32_e32 v90, 0xffff0000, v96
	v_mul_f32_e32 v91, 0xbfb8aa3b, v90
	v_exp_f32_e32 v91, v91
	v_add_f32_e32 v88, 1.0, v88
	v_rcp_f32_e32 v88, v88
	v_lshlrev_b32_e32 v89, 16, v92
	v_fmac_f32_e32 v89, v201, v38
	ds_write_b128 v128, v[42:45] offset:52224
	ds_write_b128 v128, v[54:57] offset:52240
	v_mul_f32_e32 v38, v88, v77
	v_lshlrev_b32_e32 v88, 16, v97
	v_mul_f32_e32 v38, v38, v89
	v_add_f32_e32 v77, 1.0, v91
	v_mul_f32_e32 v89, 0xbfb8aa3b, v88
	v_rcp_f32_e32 v77, v77
	v_exp_f32_e32 v89, v89
	v_and_b32_e32 v91, 0xffff0000, v92
	v_fmac_f32_e32 v91, v201, v39
	v_mul_f32_e32 v39, v77, v90
	v_add_f32_e32 v77, 1.0, v89
	v_rcp_f32_e32 v77, v77
	v_lshlrev_b32_e32 v89, 16, v93
	v_fmac_f32_e32 v89, v201, v40
	v_mul_f32_e32 v39, v39, v91
	v_mul_f32_e32 v40, v77, v88
	v_and_b32_e32 v77, 0xffff0000, v97
	v_mul_f32_e32 v88, 0xbfb8aa3b, v77
	v_exp_f32_e32 v88, v88
	v_mul_f32_e32 v40, v40, v89
	v_and_b32_e32 v89, 0xffff0000, v93
	s_waitcnt lgkmcnt(0)
	s_barrier
	ds_read_b128 v[42:45], v129 offset:52224
	ds_read_b128 v[54:57], v129 offset:52288
	ds_read_b128 v[62:65], v129 offset:56576
	ds_read_b128 v[90:93], v129 offset:56640
	ds_read_b128 v[202:205], v129 offset:52352
	ds_read_b128 v[206:209], v129 offset:52416
	ds_read_b128 v[210:213], v129 offset:56704
	ds_read_b128 v[214:217], v129 offset:56768
	v_fmac_f32_e32 v89, v201, v41
	v_add_f32_e32 v41, 1.0, v88
	v_rcp_f32_e32 v41, v41
	v_cvt_pk_bf16_f32 v87, v59, v60
	v_cvt_pk_bf16_f32 v86, v61, v69
	s_nop 0
	v_mul_f32_e32 v34, v41, v77
	v_mul_f32_e32 v34, v34, v89
	v_cvt_pk_bf16_f32 v89, v38, v39
	v_cvt_pk_bf16_f32 v88, v40, v34
	s_waitcnt vmcnt(9)
	v_mul_f32_e32 v35, 0x3fb8aa3b, v218
	s_waitcnt lgkmcnt(7)
	v_mfma_f32_16x16x32_bf16 v[218:221], v[42:45], v[30:33], 0
	s_waitcnt vmcnt(5)
	v_lshlrev_b32_e32 v36, 16, v226
	v_mul_f32_e32 v37, 0xbfb8aa3b, v36
	v_exp_f32_e32 v37, v37
	s_waitcnt lgkmcnt(5)
	v_mfma_f32_16x16x32_bf16 v[30:33], v[62:65], v[30:33], 0
	v_exp_f32_e32 v35, v35
	v_and_b32_e32 v77, 0xffff0000, v226
	v_add_f32_e32 v37, 1.0, v37
	v_mfma_f32_16x16x32_bf16 v[42:45], v[42:45], v[26:29], 0
	v_mul_f32_e32 v96, 0xbfb8aa3b, v77
	v_rcp_f32_e32 v37, v37
	v_exp_f32_e32 v96, v96
	v_mfma_f32_16x16x32_bf16 v[26:29], v[62:65], v[26:29], 0
	v_lshlrev_b32_e32 v41, 16, v222
	v_mul_f32_e32 v36, v37, v36
	v_add_f32_e32 v37, 1.0, v96
	v_mfma_f32_16x16x32_bf16 v[218:221], v[54:57], v[22:25], v[218:221]
	v_rcp_f32_e32 v37, v37
	v_lshlrev_b32_e32 v63, 16, v223
	v_mul_f32_e32 v37, v37, v77
	s_waitcnt lgkmcnt(4)
	v_mfma_f32_16x16x32_bf16 v[22:25], v[90:93], v[22:25], v[30:33]
	v_mfma_f32_16x16x32_bf16 v[30:33], v[54:57], v[18:21], v[42:45]
	s_nop 2
	v_and_b32_e32 v43, 0xffff0000, v227
	v_mul_f32_e32 v44, 0xbfb8aa3b, v43
	v_mfma_f32_16x16x32_bf16 v[18:21], v[90:93], v[18:21], v[26:29]
	s_nop 2
	v_exp_f32_e32 v26, v44
	s_waitcnt lgkmcnt(3)
	v_mfma_f32_16x16x32_bf16 v[218:221], v[202:205], v[14:17], v[218:221]
	v_and_b32_e32 v28, 0xffff0000, v223
	s_waitcnt lgkmcnt(1)
	v_mfma_f32_16x16x32_bf16 v[14:17], v[210:213], v[14:17], v[22:25]
	s_nop 2
	v_add_f32_e32 v22, 1.0, v26
	v_rcp_f32_e32 v26, v22
	v_mfma_f32_16x16x32_bf16 v[22:25], v[202:205], v[10:13], v[30:33]
	v_mul_f32_e32 v26, v26, v43
	v_mfma_f32_16x16x32_bf16 v[10:13], v[210:213], v[10:13], v[18:21]
	s_waitcnt vmcnt(4)
	s_nop 1
	v_lshlrev_b32_e32 v19, 16, v228
	v_mul_f32_e32 v20, 0xbfb8aa3b, v19
	v_exp_f32_e32 v20, v20
	v_mfma_f32_16x16x32_bf16 v[218:221], v[206:209], v[6:9], v[218:221]
	s_waitcnt lgkmcnt(0)
	v_mfma_f32_16x16x32_bf16 v[6:9], v[214:217], v[6:9], v[14:17]
	v_mfma_f32_16x16x32_bf16 v[14:17], v[206:209], v[2:5], v[22:25]
	s_nop 4
	v_fmac_f32_e32 v41, v35, v218
	v_mul_f32_e32 v36, v36, v41
	v_and_b32_e32 v41, 0xffff0000, v222
	v_mfma_f32_16x16x32_bf16 v[10:13], v[214:217], v[2:5], v[10:13]
	v_and_b32_e32 v4, 0xffff0000, v228
	v_mul_f32_e32 v5, 0xbfb8aa3b, v4
	v_add_f32_e32 v3, 1.0, v20
	v_exp_f32_e32 v5, v5
	v_rcp_f32_e32 v3, v3
	v_lshlrev_b32_e32 v2, 16, v224
	v_fmac_f32_e32 v2, v35, v6
	v_add_f32_e32 v5, 1.0, v5
	v_lshlrev_b32_e32 v6, 16, v229
	v_mul_f32_e32 v3, v3, v19
	v_rcp_f32_e32 v5, v5
	v_mul_f32_e32 v19, 0xbfb8aa3b, v6
	v_exp_f32_e32 v19, v19
	v_mul_f32_e32 v2, v3, v2
	v_and_b32_e32 v3, 0xffff0000, v224
	v_fmac_f32_e32 v3, v35, v7
	v_mul_f32_e32 v4, v5, v4
	v_and_b32_e32 v5, 0xffff0000, v229
	v_mul_f32_e32 v3, v4, v3
	v_add_f32_e32 v4, 1.0, v19
	v_mul_f32_e32 v7, 0xbfb8aa3b, v5
	v_rcp_f32_e32 v4, v4
	v_exp_f32_e32 v7, v7
	v_fmac_f32_e32 v41, v35, v219
	v_mul_f32_e32 v37, v37, v41
	v_lshlrev_b32_e32 v41, 16, v227
	v_mul_f32_e32 v62, 0xbfb8aa3b, v41
	v_exp_f32_e32 v62, v62
	v_mul_f32_e32 v4, v4, v6
	v_add_f32_e32 v6, 1.0, v7
	v_rcp_f32_e32 v6, v6
	v_add_f32_e32 v62, 1.0, v62
	v_rcp_f32_e32 v42, v62
	v_and_b32_e32 v7, 0xffff0000, v225
	v_mul_f32_e32 v5, v6, v5
	v_mul_f32_e32 v6, v3, v3
	v_fmac_f32_e32 v6, v2, v2
	v_cvt_pk_bf16_f32 v101, v2, v3
	v_mul_f32_e32 v2, 0x3fb8aa3b, v230
	v_fmac_f32_e32 v7, v35, v9
	v_exp_f32_e32 v9, v2
	s_waitcnt vmcnt(1)
	v_lshlrev_b32_e32 v2, 16, v52
	v_mul_f32_e32 v3, 0xbfb8aa3b, v2
	v_fmac_f32_e32 v63, v35, v220
	v_mul_f32_e32 v27, v42, v41
	v_mul_f32_e32 v18, v37, v37
	v_lshlrev_b32_e32 v19, 16, v225
	v_exp_f32_e32 v3, v3
	v_mul_f32_e32 v27, v27, v63
	v_fmac_f32_e32 v28, v35, v221
	v_fmac_f32_e32 v18, v36, v36
	v_fmac_f32_e32 v19, v35, v8
	v_mul_f32_e32 v26, v26, v28
	v_fmac_f32_e32 v18, v27, v27
	v_mul_f32_e32 v4, v4, v19
	v_fmac_f32_e32 v18, v26, v26
	v_mul_f32_e32 v5, v5, v7
	v_fmac_f32_e32 v6, v4, v4
	v_add_f32_e32 v18, v107, v18
	v_fmac_f32_e32 v6, v5, v5
	v_cvt_pk_bf16_f32 v100, v4, v5
	v_add_f32_e32 v3, 1.0, v3
	v_and_b32_e32 v5, 0xffff0000, v52
	v_add_f32_e32 v18, v18, v6
	v_rcp_f32_e32 v3, v3
	v_mul_f32_e32 v6, 0xbfb8aa3b, v5
	v_exp_f32_e32 v6, v6
	v_lshlrev_b32_e32 v4, 16, v50
	v_fmac_f32_e32 v4, v9, v14
	v_mul_f32_e32 v2, v3, v2
	v_mul_f32_e32 v2, v2, v4
	v_add_f32_e32 v4, 1.0, v6
	v_lshlrev_b32_e32 v6, 16, v53
	v_rcp_f32_e32 v4, v4
	v_mul_f32_e32 v7, 0xbfb8aa3b, v6
	v_exp_f32_e32 v7, v7
	v_and_b32_e32 v3, 0xffff0000, v50
	v_fmac_f32_e32 v3, v9, v15
	v_mul_f32_e32 v4, v4, v5
	v_and_b32_e32 v5, 0xffff0000, v53
	v_mul_f32_e32 v3, v4, v3
	v_add_f32_e32 v4, 1.0, v7
	v_mul_f32_e32 v7, 0xbfb8aa3b, v5
	v_rcp_f32_e32 v4, v4
	v_exp_f32_e32 v7, v7
	v_lshlrev_b32_e32 v8, 16, v51
	v_fmac_f32_e32 v8, v9, v16
	v_mul_f32_e32 v4, v4, v6
	v_add_f32_e32 v6, 1.0, v7
	v_rcp_f32_e32 v6, v6
	v_and_b32_e32 v7, 0xffff0000, v51
	v_fmac_f32_e32 v7, v9, v17
	v_mul_f32_e32 v4, v4, v8
	v_mul_f32_e32 v5, v6, v5
	s_waitcnt vmcnt(0)
	v_lshlrev_b32_e32 v6, 16, v48
	v_mul_f32_e32 v5, v5, v7
	v_mul_f32_e32 v7, 0xbfb8aa3b, v6
	v_exp_f32_e32 v7, v7
	v_lshlrev_b32_e32 v8, 16, v46
	v_fmac_f32_e32 v8, v9, v10
	v_and_b32_e32 v10, 0xffff0000, v48
	v_add_f32_e32 v7, 1.0, v7
	v_rcp_f32_e32 v7, v7
	v_mul_f32_e32 v14, 0xbfb8aa3b, v10
	v_exp_f32_e32 v14, v14
	v_lshlrev_b32_e32 v16, 2, v147
	v_mul_f32_e32 v6, v7, v6
	v_mul_f32_e32 v6, v6, v8
	v_add_f32_e32 v8, 1.0, v14
	v_rcp_f32_e32 v8, v8
	v_and_b32_e32 v7, 0xffff0000, v46
	v_fmac_f32_e32 v7, v9, v11
	v_lshlrev_b32_e32 v14, 16, v49
	v_mul_f32_e32 v8, v8, v10
	v_and_b32_e32 v10, 0xffff0000, v49
	v_mul_f32_e32 v11, 0xbfb8aa3b, v10
	v_exp_f32_e32 v11, v11
	v_mul_f32_e32 v15, 0xbfb8aa3b, v14
	v_exp_f32_e32 v15, v15
	v_mul_f32_e32 v7, v8, v7
	v_add_f32_e32 v11, 1.0, v11
	v_rcp_f32_e32 v11, v11
	v_add_f32_e32 v8, 1.0, v15
	v_lshlrev_b32_e32 v15, 16, v47
	v_fmac_f32_e32 v15, v9, v12
	v_and_b32_e32 v12, 0xffff0000, v47
	v_fmac_f32_e32 v12, v9, v13
	v_mul_f32_e32 v9, v11, v10
	v_and_b32_e32 v11, 64, v144
	v_xor_b32_e32 v10, 16, v144
	v_add_u32_e32 v11, 64, v11
	v_cmp_lt_i32_e32 vcc, v10, v11
	v_rcp_f32_e32 v8, v8
	v_mul_f32_e32 v9, v9, v12
	v_cndmask_b32_e32 v10, v144, v10, vcc
	v_lshlrev_b32_e32 v10, 2, v10
	ds_bpermute_b32 v13, v10, v18
	v_xor_b32_e32 v12, 32, v144
	v_cmp_lt_i32_e32 vcc, v12, v11
	v_mul_f32_e32 v8, v8, v14
	v_mul_f32_e32 v8, v8, v15
	v_cndmask_b32_e32 v11, v144, v12, vcc
	v_lshlrev_b32_e32 v12, 2, v11
	s_waitcnt lgkmcnt(0)
	v_add_f32_e32 v13, v18, v13
	ds_bpermute_b32 v14, v12, v13
	v_lshl_add_u32 v11, v112, 9, s36
	v_and_b32_e32 v15, 0xffffff80, v146
	v_cmp_eq_u32_e32 vcc, 0, v148
	v_add3_u32 v11, v11, v15, v16
	v_cvt_pk_bf16_f32 v96, v36, v37
	v_cvt_pk_bf16_f32 v97, v27, v26
	v_cvt_pk_bf16_f32 v90, v2, v3
	v_cvt_pk_bf16_f32 v91, v4, v5
	v_cvt_pk_bf16_f32 v93, v6, v7
	v_cvt_pk_bf16_f32 v92, v8, v9
	s_and_saveexec_b64 s[16:17], vcc
	s_cbranch_execz .LBB0_546
	s_waitcnt lgkmcnt(0)
	v_add_f32_e32 v13, v13, v14
	ds_write_b32 v11, v13
